# trans-use hazard fixed in RG-LRU constants (s_nop after v_exp); hand-written row phases 1,7,10,14,17
# speedup vs baseline: 1.2374x; 1.0021x over previous
; __device__ __forceinline__ float bf2f(u16 h) { return __uint_as_float(((unsigned)h) << 16); }
; __device__ __forceinline__ void lru_tile(const Params& P, int chunk, int head, int pass, char* smem_raw) {
;     ...
;     const float w0 = P.conv_w[gch], w1 = P.conv_w[512 + gch], w2 = P.conv_w[1024 + gch], w3 = P.conv_w[1536 + gch];
;     const float cb = P.conv_b[gch];
;     const u16* zu = P.zq + gch;
;     const int r = row0 + q * 32;
;     float uv[35];
; #pragma unroll
;     for (int i = 0; i < 35; ++i) {
;       const int rr = r - 2 + i;
;       uv[i] = (rr >= seq_lo && rr < seq_hi) ? bf2f(zu[(long)rr * 1536]) : 0.f;
;     ...
;       *reinterpret_cast<uint4*>(&sm_w[rowi * LDSS + kg * 8]) = ldg16(P.wg + ((long)(d * 8 + head) * 128 + rowi) * 64 + kg * 8);
;     }
;     float ba[4], bi[4], c8[4];
; #pragma unroll
;     for (int tc = 0; tc < 4; ++tc) {
;       const int cidx = d * 512 + head * 64 + 16 * tc + (lane & 15);
;       ba[tc] = P.b_a[cidx] * -1.4426950408889634f; bi[tc] = P.b_i[cidx] * -1.4426950408889634f;
;       const float nl = -P.lam[cidx];
;       const float e_ = __expf(nl);
;       const float sp = (nl > 20.f) ? nl
;                      : (e_ < 0.03f ? e_ * (1.f - e_ * (0.5f - e_ * (0.33333334f - 0.25f * e_))) : __logf(1.f + e_));
;       c8[tc] = 8.f * 1.4426950408889634f * sp;
.Lmy_lrua_fl:
	s_cmp_eq_u32 s57, 0
	s_cselect_b64 s[0:1], s[84:85], 0
	s_cmp_eq_u32 s57, s60
	s_cselect_b64 s[4:5], s[86:87], 0
	v_cndmask_b32_e64 v202, 1.0, 0, s[0:1]
	v_cndmask_b32_e64 v203, 1.0, 0, s[4:5]
	v_mov_b32_e32 v255, 0x1800
	v_cndmask_b32_e64 v150, 0, v255, s[0:1]
	v_lshlrev_b32_e32 v136, 1, v150
	v_add_u32_e32 v136, v134, v136
	v_add_u32_e32 v150, v134, v150
	v_cndmask_b32_e64 v151, 0, v255, s[4:5]
	v_sub_u32_e32 v151, v134, v151
	s_lshl_b32 s61, s71, 7
	s_mul_i32 s0, s61, 0xc00
	s_lshl_b32 s1, s56, 1
	s_add_u32 s0, s0, s1
	s_add_u32 s4, s10, s0
	s_addc_u32 s5, s11, 0
	s_sub_u32 s4, s4, 0x1800
	s_subb_u32 s5, s5, 0
	global_load_ushort v90, v136, s[4:5]
	s_add_u32 s4, s4, 0xc00
	s_addc_u32 s5, s5, 0
	global_load_ushort v91, v150, s[4:5]
	s_add_u32 s4, s4, 0xc00
	s_addc_u32 s5, s5, 0
	global_load_ushort v92, v134, s[4:5]
	s_add_u32 s4, s4, 0xc00
	s_addc_u32 s5, s5, 0
	global_load_ushort v93, v134, s[4:5]
	s_add_u32 s4, s4, 0xc00
	s_addc_u32 s5, s5, 0
	global_load_ushort v94, v134, s[4:5]
	s_add_u32 s4, s4, 0xc00
	s_addc_u32 s5, s5, 0
	global_load_ushort v95, v134, s[4:5]
	s_add_u32 s4, s4, 0xc00
	s_addc_u32 s5, s5, 0
	global_load_ushort v96, v134, s[4:5]
	s_add_u32 s4, s4, 0xc00
	s_addc_u32 s5, s5, 0
	global_load_ushort v97, v134, s[4:5]
	s_add_u32 s4, s4, 0xc00
	s_addc_u32 s5, s5, 0
	global_load_ushort v98, v134, s[4:5]
	s_add_u32 s4, s4, 0xc00
	s_addc_u32 s5, s5, 0
	global_load_ushort v99, v134, s[4:5]
	s_add_u32 s4, s4, 0xc00
	s_addc_u32 s5, s5, 0
	global_load_ushort v100, v134, s[4:5]
	s_add_u32 s4, s4, 0xc00
	s_addc_u32 s5, s5, 0
	global_load_ushort v101, v134, s[4:5]
	s_add_u32 s4, s4, 0xc00
	s_addc_u32 s5, s5, 0
	global_load_ushort v102, v134, s[4:5]
	s_add_u32 s4, s4, 0xc00
	s_addc_u32 s5, s5, 0
	global_load_ushort v103, v134, s[4:5]
	s_add_u32 s4, s4, 0xc00
	s_addc_u32 s5, s5, 0
	global_load_ushort v104, v134, s[4:5]
	s_add_u32 s4, s4, 0xc00
	s_addc_u32 s5, s5, 0
	global_load_ushort v105, v134, s[4:5]
	s_add_u32 s4, s4, 0xc00
	s_addc_u32 s5, s5, 0
	global_load_ushort v106, v134, s[4:5]
	s_add_u32 s4, s4, 0xc00
	s_addc_u32 s5, s5, 0
	global_load_ushort v107, v134, s[4:5]
	s_add_u32 s4, s4, 0xc00
	s_addc_u32 s5, s5, 0
	global_load_ushort v108, v134, s[4:5]
	s_add_u32 s4, s4, 0xc00
	s_addc_u32 s5, s5, 0
	global_load_ushort v109, v134, s[4:5]
	s_add_u32 s4, s4, 0xc00
	s_addc_u32 s5, s5, 0
	global_load_ushort v110, v134, s[4:5]
	s_add_u32 s4, s4, 0xc00
	s_addc_u32 s5, s5, 0
	global_load_ushort v111, v134, s[4:5]
	s_add_u32 s4, s4, 0xc00
	s_addc_u32 s5, s5, 0
	global_load_ushort v112, v134, s[4:5]
	s_add_u32 s4, s4, 0xc00
	s_addc_u32 s5, s5, 0
	global_load_ushort v113, v134, s[4:5]
	s_add_u32 s4, s4, 0xc00
	s_addc_u32 s5, s5, 0
	global_load_ushort v114, v134, s[4:5]
	s_add_u32 s4, s4, 0xc00
	s_addc_u32 s5, s5, 0
	global_load_ushort v115, v134, s[4:5]
	s_add_u32 s4, s4, 0xc00
	s_addc_u32 s5, s5, 0
	global_load_ushort v116, v134, s[4:5]
	s_add_u32 s4, s4, 0xc00
	s_addc_u32 s5, s5, 0
	global_load_ushort v117, v134, s[4:5]
	s_add_u32 s4, s4, 0xc00
	s_addc_u32 s5, s5, 0
	global_load_ushort v118, v134, s[4:5]
	s_add_u32 s4, s4, 0xc00
	s_addc_u32 s5, s5, 0
	global_load_ushort v119, v134, s[4:5]
	s_add_u32 s4, s4, 0xc00
	s_addc_u32 s5, s5, 0
	global_load_ushort v120, v134, s[4:5]
	s_add_u32 s4, s4, 0xc00
	s_addc_u32 s5, s5, 0
	global_load_ushort v121, v134, s[4:5]
	s_add_u32 s4, s4, 0xc00
	s_addc_u32 s5, s5, 0
	global_load_ushort v122, v134, s[4:5]
	s_add_u32 s4, s4, 0xc00
	s_addc_u32 s5, s5, 0
	global_load_ushort v123, v134, s[4:5]
	s_add_u32 s4, s4, 0xc00
	s_addc_u32 s5, s5, 0
	global_load_ushort v124, v151, s[4:5]
	v_bfe_u32 v255, v152, 6, 2
	v_and_b32_e32 v253, 15, v152
	v_lshl_add_u32 v255, v255, 4, v253
	v_add_u32_e32 v255, s56, v255
	v_lshlrev_b32_e32 v255, 2, v255
	global_load_dword v65, v255, s[24:25]
	global_load_dword v67, v255, s[24:25] offset:2048
	s_add_u32 s0, s24, 0x1000
	s_addc_u32 s1, s25, 0
	global_load_dword v68, v255, s[0:1]
	global_load_dword v70, v255, s[0:1] offset:2048
	global_load_dword v73, v255, s[26:27]
	s_lshl_b32 s0, s56, 8
	s_add_u32 s0, s0, 0x0
	s_add_u32 s4, s20, s0
	s_addc_u32 s5, s21, 0
	global_load_dwordx4 v[238:241], v251, s[4:5]
	global_load_dwordx4 v[242:245], v251, s[4:5] offset:64
	s_add_u32 s4, s4, 0x2000
	s_addc_u32 s5, s5, 0
	global_load_dwordx4 v[246:249], v251, s[4:5]
	global_load_dwordx4 v[194:197], v251, s[4:5] offset:64
	v_bfe_u32 v255, v152, 6, 2
	v_and_b32_e32 v253, 15, v152
	v_lshl_add_u32 v255, v255, 4, v253
	v_add_u32_e32 v255, s56, v255
	v_lshlrev_b32_e32 v255, 2, v255
	s_add_u32 s0, s28, 0x0
	s_addc_u32 s1, s29, 0
	global_load_dword v75, v255, s[0:1]
	s_add_u32 s0, s30, 0x0
	s_addc_u32 s1, s31, 0
	global_load_dword v84, v255, s[0:1]
	s_add_u32 s0, s36, 0x0
	s_addc_u32 s1, s37, 0
	global_load_dword v85, v255, s[0:1]
	s_barrier
; __device__ __forceinline__ float bf2f(u16 h) { return __uint_as_float(((unsigned)h) << 16); }
; __device__ __forceinline__ void lru_tile(const Params& P, int chunk, int head, int pass, char* smem_raw) {
;     ...
; #pragma unroll
;     for (int i = 0; i < 35; ++i) {
;       const int rr = r - 2 + i;
;       uv[i] = (rr >= seq_lo && rr < seq_hi) ? bf2f(zu[(long)rr * 1536]) : 0.f;
;     }
;     __syncthreads();
; #pragma unroll
;     for (int i = 0; i < 32; ++i) {
;       const float v = cb + uv[i] * w0 + uv[i + 1] * w1 + uv[i + 2] * w2 + uv[i + 3] * w3;
;       sm_uc[(q * 32 + i) * LDSS + ch] = f2bf(v);
	s_waitcnt vmcnt(0)
	v_lshlrev_b32_e32 v90, 16, v90
	v_lshlrev_b32_e32 v91, 16, v91
	v_lshlrev_b32_e32 v92, 16, v92
	v_lshlrev_b32_e32 v93, 16, v93
	v_lshlrev_b32_e32 v94, 16, v94
	v_lshlrev_b32_e32 v95, 16, v95
	v_lshlrev_b32_e32 v96, 16, v96
	v_lshlrev_b32_e32 v97, 16, v97
	v_lshlrev_b32_e32 v98, 16, v98
	v_lshlrev_b32_e32 v99, 16, v99
	v_lshlrev_b32_e32 v100, 16, v100
	v_lshlrev_b32_e32 v101, 16, v101
	v_lshlrev_b32_e32 v102, 16, v102
	v_lshlrev_b32_e32 v103, 16, v103
	v_lshlrev_b32_e32 v104, 16, v104
	v_lshlrev_b32_e32 v105, 16, v105
	v_lshlrev_b32_e32 v106, 16, v106
	v_lshlrev_b32_e32 v107, 16, v107
	v_lshlrev_b32_e32 v108, 16, v108
	v_lshlrev_b32_e32 v109, 16, v109
	v_lshlrev_b32_e32 v110, 16, v110
	v_lshlrev_b32_e32 v111, 16, v111
	v_lshlrev_b32_e32 v112, 16, v112
	v_lshlrev_b32_e32 v113, 16, v113
	v_lshlrev_b32_e32 v114, 16, v114
	v_lshlrev_b32_e32 v115, 16, v115
	v_lshlrev_b32_e32 v116, 16, v116
	v_lshlrev_b32_e32 v117, 16, v117
	v_lshlrev_b32_e32 v118, 16, v118
	v_lshlrev_b32_e32 v119, 16, v119
	v_lshlrev_b32_e32 v120, 16, v120
	v_lshlrev_b32_e32 v121, 16, v121
	v_lshlrev_b32_e32 v122, 16, v122
	v_lshlrev_b32_e32 v123, 16, v123
	v_lshlrev_b32_e32 v124, 16, v124
	v_mul_f32_e32 v90, v90, v202
	v_mul_f32_e32 v91, v91, v202
	v_mul_f32_e32 v124, v124, v203
	v_fma_f32 v162, v90, v65, v73
	v_fma_f32 v162, v91, v67, v162
	v_fma_f32 v162, v92, v68, v162
	v_fma_f32 v162, v93, v70, v162
	v_fma_f32 v163, v91, v65, v73
	v_fma_f32 v163, v92, v67, v163
	v_fma_f32 v163, v93, v68, v163
	v_fma_f32 v163, v94, v70, v163
	v_fma_f32 v164, v92, v65, v73
	v_fma_f32 v164, v93, v67, v164
	v_fma_f32 v164, v94, v68, v164
	v_fma_f32 v164, v95, v70, v164
	v_fma_f32 v165, v93, v65, v73
	v_fma_f32 v165, v94, v67, v165
	v_fma_f32 v165, v95, v68, v165
	v_fma_f32 v165, v96, v70, v165
	v_fma_f32 v166, v94, v65, v73
	v_fma_f32 v166, v95, v67, v166
	v_fma_f32 v166, v96, v68, v166
	v_fma_f32 v166, v97, v70, v166
	v_fma_f32 v167, v95, v65, v73
	v_fma_f32 v167, v96, v67, v167
	v_fma_f32 v167, v97, v68, v167
	v_fma_f32 v167, v98, v70, v167
	v_fma_f32 v168, v96, v65, v73
	v_fma_f32 v168, v97, v67, v168
	v_fma_f32 v168, v98, v68, v168
	v_fma_f32 v168, v99, v70, v168
	v_fma_f32 v169, v97, v65, v73
	v_fma_f32 v169, v98, v67, v169
	v_fma_f32 v169, v99, v68, v169
	v_fma_f32 v169, v100, v70, v169
	v_fma_f32 v170, v98, v65, v73
	v_fma_f32 v170, v99, v67, v170
	v_fma_f32 v170, v100, v68, v170
	v_fma_f32 v170, v101, v70, v170
	v_fma_f32 v171, v99, v65, v73
	v_fma_f32 v171, v100, v67, v171
	v_fma_f32 v171, v101, v68, v171
	v_fma_f32 v171, v102, v70, v171
	v_fma_f32 v172, v100, v65, v73
	v_fma_f32 v172, v101, v67, v172
	v_fma_f32 v172, v102, v68, v172
	v_fma_f32 v172, v103, v70, v172
	v_fma_f32 v173, v101, v65, v73
	v_fma_f32 v173, v102, v67, v173
	v_fma_f32 v173, v103, v68, v173
	v_fma_f32 v173, v104, v70, v173
	v_fma_f32 v174, v102, v65, v73
	v_fma_f32 v174, v103, v67, v174
	v_fma_f32 v174, v104, v68, v174
	v_fma_f32 v174, v105, v70, v174
	v_fma_f32 v175, v103, v65, v73
	v_fma_f32 v175, v104, v67, v175
	v_fma_f32 v175, v105, v68, v175
	v_fma_f32 v175, v106, v70, v175
	v_fma_f32 v176, v104, v65, v73
	v_fma_f32 v176, v105, v67, v176
	v_fma_f32 v176, v106, v68, v176
	v_fma_f32 v176, v107, v70, v176
	v_fma_f32 v177, v105, v65, v73
	v_fma_f32 v177, v106, v67, v177
	v_fma_f32 v177, v107, v68, v177
	v_fma_f32 v177, v108, v70, v177
	v_fma_f32 v178, v106, v65, v73
	v_fma_f32 v178, v107, v67, v178
	v_fma_f32 v178, v108, v68, v178
	v_fma_f32 v178, v109, v70, v178
	v_fma_f32 v179, v107, v65, v73
	v_fma_f32 v179, v108, v67, v179
	v_fma_f32 v179, v109, v68, v179
	v_fma_f32 v179, v110, v70, v179
	v_fma_f32 v180, v108, v65, v73
	v_fma_f32 v180, v109, v67, v180
	v_fma_f32 v180, v110, v68, v180
	v_fma_f32 v180, v111, v70, v180
	v_fma_f32 v181, v109, v65, v73
	v_fma_f32 v181, v110, v67, v181
	v_fma_f32 v181, v111, v68, v181
	v_fma_f32 v181, v112, v70, v181
	v_fma_f32 v182, v110, v65, v73
	v_fma_f32 v182, v111, v67, v182
	v_fma_f32 v182, v112, v68, v182
	v_fma_f32 v182, v113, v70, v182
	v_fma_f32 v183, v111, v65, v73
	v_fma_f32 v183, v112, v67, v183
	v_fma_f32 v183, v113, v68, v183
	v_fma_f32 v183, v114, v70, v183
	v_fma_f32 v184, v112, v65, v73
	v_fma_f32 v184, v113, v67, v184
	v_fma_f32 v184, v114, v68, v184
	v_fma_f32 v184, v115, v70, v184
	v_fma_f32 v185, v113, v65, v73
	v_fma_f32 v185, v114, v67, v185
	v_fma_f32 v185, v115, v68, v185
	v_fma_f32 v185, v116, v70, v185
	v_fma_f32 v186, v114, v65, v73
	v_fma_f32 v186, v115, v67, v186
	v_fma_f32 v186, v116, v68, v186
	v_fma_f32 v186, v117, v70, v186
	v_fma_f32 v187, v115, v65, v73
	v_fma_f32 v187, v116, v67, v187
	v_fma_f32 v187, v117, v68, v187
	v_fma_f32 v187, v118, v70, v187
	v_fma_f32 v188, v116, v65, v73
	v_fma_f32 v188, v117, v67, v188
	v_fma_f32 v188, v118, v68, v188
	v_fma_f32 v188, v119, v70, v188
	v_fma_f32 v189, v117, v65, v73
	v_fma_f32 v189, v118, v67, v189
	v_fma_f32 v189, v119, v68, v189
	v_fma_f32 v189, v120, v70, v189
	v_fma_f32 v190, v118, v65, v73
	v_fma_f32 v190, v119, v67, v190
	v_fma_f32 v190, v120, v68, v190
	v_fma_f32 v190, v121, v70, v190
	v_fma_f32 v191, v119, v65, v73
	v_fma_f32 v191, v120, v67, v191
	v_fma_f32 v191, v121, v68, v191
	v_fma_f32 v191, v122, v70, v191
	v_fma_f32 v192, v120, v65, v73
	v_fma_f32 v192, v121, v67, v192
	v_fma_f32 v192, v122, v68, v192
	v_fma_f32 v192, v123, v70, v192
	v_fma_f32 v193, v121, v65, v73
	v_fma_f32 v193, v122, v67, v193
	v_fma_f32 v193, v123, v68, v193
	v_fma_f32 v193, v124, v70, v193
	v_cvt_pk_bf16_f32 v162, v162, v162
	v_cvt_pk_bf16_f32 v163, v163, v163
	v_cvt_pk_bf16_f32 v164, v164, v164
	v_cvt_pk_bf16_f32 v165, v165, v165
	v_cvt_pk_bf16_f32 v166, v166, v166
	v_cvt_pk_bf16_f32 v167, v167, v167
; __device__ __forceinline__ void lru_tile(const Params& P, int chunk, int head, int pass, char* smem_raw) {
;     ...
; #pragma unroll
;     for (int i = 0; i < 32; ++i) {
;       const float v = cb + uv[i] * w0 + uv[i + 1] * w1 + uv[i + 2] * w2 + uv[i + 3] * w3;
;       sm_uc[(q * 32 + i) * LDSS + ch] = f2bf(v);
;     ...
;       f32x4 acc[8];
; #pragma unroll
;       for (int t = 0; t < 8; ++t) acc[t] = f32x4{0.f, 0.f, 0.f, 0.f};
; #pragma unroll
;       for (int s = 0; s < 2; ++s) {
;         const bf16x8 af = *reinterpret_cast<const bf16x8*>(&sm_uc[(sb * 64 + wid * 16 + (lane & 15)) * LDSS + s * 32 + (lane >> 4) * 8]);
; #pragma unroll
;         for (int t = 0; t < 8; ++t) {
;           const bf16x8 bfr = *reinterpret_cast<const bf16x8*>(&sm_w[(t * 16 + (lane & 15)) * LDSS + s * 32 + (lane >> 4) * 8]);
;           acc[t] = __builtin_amdgcn_mfma_f32_16x16x32_bf16(af, bfr, acc[t], 0, 0, 0);
;         }
;       }
	v_cvt_pk_bf16_f32 v168, v168, v168
	v_cvt_pk_bf16_f32 v169, v169, v169
	v_cvt_pk_bf16_f32 v170, v170, v170
	v_cvt_pk_bf16_f32 v171, v171, v171
	v_cvt_pk_bf16_f32 v172, v172, v172
	v_cvt_pk_bf16_f32 v173, v173, v173
	v_cvt_pk_bf16_f32 v174, v174, v174
	v_cvt_pk_bf16_f32 v175, v175, v175
	v_cvt_pk_bf16_f32 v176, v176, v176
	v_cvt_pk_bf16_f32 v177, v177, v177
	v_cvt_pk_bf16_f32 v178, v178, v178
	v_cvt_pk_bf16_f32 v179, v179, v179
	v_cvt_pk_bf16_f32 v180, v180, v180
	v_cvt_pk_bf16_f32 v181, v181, v181
	v_cvt_pk_bf16_f32 v182, v182, v182
	v_cvt_pk_bf16_f32 v183, v183, v183
	v_cvt_pk_bf16_f32 v184, v184, v184
	v_cvt_pk_bf16_f32 v185, v185, v185
	v_cvt_pk_bf16_f32 v186, v186, v186
	v_cvt_pk_bf16_f32 v187, v187, v187
	v_cvt_pk_bf16_f32 v188, v188, v188
	v_cvt_pk_bf16_f32 v189, v189, v189
	v_cvt_pk_bf16_f32 v190, v190, v190
	v_cvt_pk_bf16_f32 v191, v191, v191
	v_cvt_pk_bf16_f32 v192, v192, v192
	v_cvt_pk_bf16_f32 v193, v193, v193
	ds_write_b16 v89, v162 offset:0
	ds_write_b16 v89, v163 offset:128
	ds_write_b16 v130, v164 offset:256
	ds_write_b16 v130, v165 offset:384
	ds_write_b16 v89, v166 offset:512
	ds_write_b16 v89, v167 offset:640
	ds_write_b16 v130, v168 offset:768
	ds_write_b16 v130, v169 offset:896
	ds_write_b16 v89, v170 offset:1024
	ds_write_b16 v89, v171 offset:1152
	ds_write_b16 v130, v172 offset:1280
	ds_write_b16 v130, v173 offset:1408
	ds_write_b16 v89, v174 offset:1536
	ds_write_b16 v89, v175 offset:1664
	ds_write_b16 v130, v176 offset:1792
	ds_write_b16 v130, v177 offset:1920
	ds_write_b16 v89, v178 offset:2048
	ds_write_b16 v89, v179 offset:2176
	ds_write_b16 v130, v180 offset:2304
	ds_write_b16 v130, v181 offset:2432
	ds_write_b16 v89, v182 offset:2560
	ds_write_b16 v89, v183 offset:2688
	ds_write_b16 v130, v184 offset:2816
	ds_write_b16 v130, v185 offset:2944
	ds_write_b16 v89, v186 offset:3072
	ds_write_b16 v89, v187 offset:3200
	ds_write_b16 v130, v188 offset:3328
	ds_write_b16 v130, v189 offset:3456
	ds_write_b16 v89, v190 offset:3584
	ds_write_b16 v89, v191 offset:3712
	ds_write_b16 v130, v192 offset:3840
	ds_write_b16 v130, v193 offset:3968
	v_lshlrev_b32_e32 v162, 16, v162
	v_lshlrev_b32_e32 v163, 16, v163
	v_lshlrev_b32_e32 v164, 16, v164
	v_lshlrev_b32_e32 v165, 16, v165
	v_lshlrev_b32_e32 v166, 16, v166
	v_lshlrev_b32_e32 v167, 16, v167
	v_lshlrev_b32_e32 v168, 16, v168
	v_lshlrev_b32_e32 v169, 16, v169
	v_lshlrev_b32_e32 v170, 16, v170
	v_lshlrev_b32_e32 v171, 16, v171
	v_lshlrev_b32_e32 v172, 16, v172
	v_lshlrev_b32_e32 v173, 16, v173
	v_lshlrev_b32_e32 v174, 16, v174
	v_lshlrev_b32_e32 v175, 16, v175
	v_lshlrev_b32_e32 v176, 16, v176
	v_lshlrev_b32_e32 v177, 16, v177
	v_lshlrev_b32_e32 v178, 16, v178
	v_lshlrev_b32_e32 v179, 16, v179
	v_lshlrev_b32_e32 v180, 16, v180
	v_lshlrev_b32_e32 v181, 16, v181
	v_lshlrev_b32_e32 v182, 16, v182
	v_lshlrev_b32_e32 v183, 16, v183
	v_lshlrev_b32_e32 v184, 16, v184
	v_lshlrev_b32_e32 v185, 16, v185
	v_lshlrev_b32_e32 v186, 16, v186
	v_lshlrev_b32_e32 v187, 16, v187
	v_lshlrev_b32_e32 v188, 16, v188
	v_lshlrev_b32_e32 v189, 16, v189
	v_lshlrev_b32_e32 v190, 16, v190
	v_lshlrev_b32_e32 v191, 16, v191
	v_lshlrev_b32_e32 v192, 16, v192
	v_lshlrev_b32_e32 v193, 16, v193
	s_waitcnt lgkmcnt(0)
	s_barrier
	ds_read_b128 v[76:79], v131 offset:0
	ds_read_b128 v[80:83], v133 offset:0
	ds_read_b128 v[122:125], v131 offset:512
	ds_read_b128 v[126:129], v133 offset:512
	s_waitcnt lgkmcnt(3)
	v_mfma_f32_16x16x32_bf16 v[0:3], v[76:79], v[238:241], 0
	v_mfma_f32_16x16x32_bf16 v[90:93], v[76:79], v[246:249], 0
	ds_read_b128 v[76:79], v131 offset:1024
	s_waitcnt lgkmcnt(3)
	v_mfma_f32_16x16x32_bf16 v[0:3], v[80:83], v[242:245], v[0:3]
	v_mfma_f32_16x16x32_bf16 v[90:93], v[80:83], v[194:197], v[90:93]
	ds_read_b128 v[80:83], v133 offset:1024
	s_waitcnt lgkmcnt(3)
	v_mfma_f32_16x16x32_bf16 v[4:7], v[122:125], v[238:241], 0
	v_mfma_f32_16x16x32_bf16 v[94:97], v[122:125], v[246:249], 0
	ds_read_b128 v[122:125], v131 offset:1536
	s_waitcnt lgkmcnt(3)
	v_mfma_f32_16x16x32_bf16 v[4:7], v[126:129], v[242:245], v[4:7]
	v_mfma_f32_16x16x32_bf16 v[94:97], v[126:129], v[194:197], v[94:97]
	ds_read_b128 v[126:129], v133 offset:1536
	s_waitcnt lgkmcnt(3)
	v_mfma_f32_16x16x32_bf16 v[8:11], v[76:79], v[238:241], 0
	v_mfma_f32_16x16x32_bf16 v[98:101], v[76:79], v[246:249], 0
	ds_read_b128 v[76:79], v131 offset:2048
	s_waitcnt lgkmcnt(3)
	v_mfma_f32_16x16x32_bf16 v[8:11], v[80:83], v[242:245], v[8:11]
	v_mfma_f32_16x16x32_bf16 v[98:101], v[80:83], v[194:197], v[98:101]
	ds_read_b128 v[80:83], v133 offset:2048
	s_waitcnt lgkmcnt(3)
	v_mfma_f32_16x16x32_bf16 v[12:15], v[122:125], v[238:241], 0
	v_mfma_f32_16x16x32_bf16 v[102:105], v[122:125], v[246:249], 0
	ds_read_b128 v[122:125], v131 offset:2560
	s_waitcnt lgkmcnt(3)
	v_mfma_f32_16x16x32_bf16 v[12:15], v[126:129], v[242:245], v[12:15]
	v_mfma_f32_16x16x32_bf16 v[102:105], v[126:129], v[194:197], v[102:105]
	ds_read_b128 v[126:129], v133 offset:2560
	s_waitcnt lgkmcnt(3)
	v_mfma_f32_16x16x32_bf16 v[16:19], v[76:79], v[238:241], 0
	v_mfma_f32_16x16x32_bf16 v[106:109], v[76:79], v[246:249], 0
	ds_read_b128 v[76:79], v131 offset:3072
	s_waitcnt lgkmcnt(3)
	v_mfma_f32_16x16x32_bf16 v[16:19], v[80:83], v[242:245], v[16:19]
	v_mfma_f32_16x16x32_bf16 v[106:109], v[80:83], v[194:197], v[106:109]
	ds_read_b128 v[80:83], v133 offset:3072
	s_waitcnt lgkmcnt(3)
	v_mfma_f32_16x16x32_bf16 v[20:23], v[122:125], v[238:241], 0
	v_mfma_f32_16x16x32_bf16 v[110:113], v[122:125], v[246:249], 0
	ds_read_b128 v[122:125], v131 offset:3584
	s_waitcnt lgkmcnt(3)
	v_mfma_f32_16x16x32_bf16 v[20:23], v[126:129], v[242:245], v[20:23]
	v_mfma_f32_16x16x32_bf16 v[110:113], v[126:129], v[194:197], v[110:113]
	ds_read_b128 v[126:129], v133 offset:3584
	s_waitcnt lgkmcnt(3)
; __device__ __forceinline__ float bf2f(u16 h) { return __uint_as_float(((unsigned)h) << 16); }
; __device__ __forceinline__ void lru_tile(const Params& P, int chunk, int head, int pass, char* smem_raw) {
;     ...
;     float ba[4], bi[4], c8[4];
; #pragma unroll
;     for (int tc = 0; tc < 4; ++tc) {
;       const int cidx = d * 512 + head * 64 + 16 * tc + (lane & 15);
;       ba[tc] = P.b_a[cidx] * -1.4426950408889634f; bi[tc] = P.b_i[cidx] * -1.4426950408889634f;
;       const float nl = -P.lam[cidx];
;       const float e_ = __expf(nl);
;       const float sp = (nl > 20.f) ? nl
;                      : (e_ < 0.03f ? e_ * (1.f - e_ * (0.5f - e_ * (0.33333334f - 0.25f * e_))) : __logf(1.f + e_));
;       c8[tc] = 8.f * 1.4426950408889634f * sp;
;     ...
; #pragma unroll
;       for (int tc = 0; tc < 4; ++tc)
; #pragma unroll
;         for (int reg = 0; reg < 4; ++reg) {
;           const int tl = wid * 16 + (lane >> 4) * 4 + reg;
;           const int c = 16 * tc + (lane & 15);
;           const float r = __builtin_amdgcn_rcpf(1.f + __builtin_amdgcn_exp2f(acc[tc][reg] + ba[tc]));
;           const float ii = __builtin_amdgcn_rcpf(1.f + __builtin_amdgcn_exp2f(acc[tc + 4][reg] + bi[tc]));
;           const float la = -c8[tc] * r;
;           const float a = __builtin_amdgcn_exp2f(la);
;           const float ucv = bf2f(sm_uc[(sb * 64 + tl) * LDSS + c]);
;           const float bt = __builtin_amdgcn_sqrtf(fmaxf(1.f - a * a, 0.f)) * (ii * ucv);
	v_mfma_f32_16x16x32_bf16 v[24:27], v[76:79], v[238:241], 0
	v_mfma_f32_16x16x32_bf16 v[114:117], v[76:79], v[246:249], 0
	s_waitcnt lgkmcnt(2)
	v_mfma_f32_16x16x32_bf16 v[24:27], v[80:83], v[242:245], v[24:27]
	v_mfma_f32_16x16x32_bf16 v[114:117], v[80:83], v[194:197], v[114:117]
	s_waitcnt lgkmcnt(1)
	v_mfma_f32_16x16x32_bf16 v[28:31], v[122:125], v[238:241], 0
	v_mfma_f32_16x16x32_bf16 v[118:121], v[122:125], v[246:249], 0
	s_waitcnt lgkmcnt(0)
	v_mfma_f32_16x16x32_bf16 v[28:31], v[126:129], v[242:245], v[28:31]
	v_mfma_f32_16x16x32_bf16 v[118:121], v[126:129], v[194:197], v[118:121]
	s_lshl_b32 s0, s56, 8
	s_add_u32 s0, s0, 0x20000
	s_add_u32 s4, s20, s0
	s_addc_u32 s5, s21, 0
	global_load_dwordx4 v[238:241], v251, s[4:5]
	global_load_dwordx4 v[242:245], v251, s[4:5] offset:64
	s_add_u32 s4, s4, 0x2000
	s_addc_u32 s5, s5, 0
	global_load_dwordx4 v[246:249], v251, s[4:5]
	global_load_dwordx4 v[194:197], v251, s[4:5] offset:64
	v_bfe_u32 v255, v152, 6, 2
	v_and_b32_e32 v253, 15, v152
	v_lshl_add_u32 v255, v255, 4, v253
	v_add_u32_e32 v255, s56, v255
	v_lshlrev_b32_e32 v255, 2, v255
	s_add_u32 s0, s28, 0x800
	s_addc_u32 s1, s29, 0
	global_load_dword v68, v255, s[0:1]
	s_add_u32 s0, s30, 0x800
	s_addc_u32 s1, s31, 0
	global_load_dword v70, v255, s[0:1]
	s_add_u32 s0, s36, 0x800
	s_addc_u32 s1, s37, 0
	global_load_dword v73, v255, s[0:1]
	v_mul_f32_e32 v75, 0xbfb8aa3b, v75
	v_mul_f32_e32 v84, 0xbfb8aa3b, v84
	v_sub_f32_e32 v138, 0, v85
	v_mul_f32_e32 v139, 0x3fb8aa3b, v138
	v_exp_f32_e32 v139, v139
	s_nop 0
	v_mul_f32_e32 v140, 0xbe800000, v139
	v_add_f32_e32 v140, 0x3eaaaaab, v140
	v_fma_f32 v140, -v139, v140, 0.5
	v_fma_f32 v140, -v139, v140, 1.0
	v_mul_f32_e32 v140, v139, v140
	v_add_f32_e32 v141, 1.0, v139
	v_log_f32_e32 v141, v141
	v_mov_b32_e32 v255, 0x3cf5c28f
	v_mul_f32_e32 v141, 0x3f317218, v141
	v_cmp_gt_f32_e32 vcc, v255, v139
	s_nop 1
	v_cndmask_b32_e32 v140, v141, v140, vcc
	v_mov_b32_e32 v255, 0x41a00000
	v_cmp_lt_f32_e32 vcc, v255, v138
	s_nop 1
	v_cndmask_b32_e32 v140, v140, v138, vcc
	v_mul_f32_e32 v85, 0xc138aa3b, v140
	s_nop 7
	v_add_f32_e32 v0, v0, v75
	v_add_f32_e32 v1, v1, v75
	v_add_f32_e32 v2, v2, v75
	v_add_f32_e32 v3, v3, v75
	v_add_f32_e32 v90, v90, v84
	v_add_f32_e32 v91, v91, v84
	v_add_f32_e32 v92, v92, v84
	v_add_f32_e32 v93, v93, v84
	v_exp_f32_e32 v0, v0
	v_exp_f32_e32 v1, v1
	v_exp_f32_e32 v2, v2
	v_exp_f32_e32 v3, v3
	v_exp_f32_e32 v90, v90
	v_exp_f32_e32 v91, v91
	v_exp_f32_e32 v92, v92
	v_exp_f32_e32 v93, v93
	v_add_f32_e32 v0, 1.0, v0
	v_add_f32_e32 v1, 1.0, v1
	v_add_f32_e32 v2, 1.0, v2
	v_add_f32_e32 v3, 1.0, v3
	v_add_f32_e32 v90, 1.0, v90
	v_add_f32_e32 v91, 1.0, v91
	v_add_f32_e32 v92, 1.0, v92
	v_add_f32_e32 v93, 1.0, v93
	v_rcp_f32_e32 v0, v0
	v_rcp_f32_e32 v1, v1
	v_rcp_f32_e32 v2, v2
	v_rcp_f32_e32 v3, v3
	v_rcp_f32_e32 v90, v90
	v_rcp_f32_e32 v91, v91
	v_rcp_f32_e32 v92, v92
	v_rcp_f32_e32 v93, v93
	v_mul_f32_e32 v0, v85, v0
	v_mul_f32_e32 v1, v85, v1
	v_mul_f32_e32 v2, v85, v2
	v_mul_f32_e32 v3, v85, v3
	v_mul_f32_e32 v90, v90, v162
	v_mul_f32_e32 v91, v91, v163
	v_mul_f32_e32 v92, v92, v164
	v_mul_f32_e32 v93, v93, v165
	v_exp_f32_e32 v0, v0
	v_exp_f32_e32 v1, v1
	v_exp_f32_e32 v2, v2
	v_exp_f32_e32 v3, v3
	s_nop 0
	v_fma_f32 v138, -v0, v0, 1.0
	v_fma_f32 v139, -v1, v1, 1.0
	v_fma_f32 v140, -v2, v2, 1.0
	v_fma_f32 v141, -v3, v3, 1.0
	v_max_f32_e32 v138, 0, v138
	v_max_f32_e32 v139, 0, v139
	v_max_f32_e32 v140, 0, v140
	v_max_f32_e32 v141, 0, v141
	v_sqrt_f32_e32 v138, v138
	v_sqrt_f32_e32 v139, v139
	v_sqrt_f32_e32 v140, v140
	v_sqrt_f32_e32 v141, v141
	s_nop 0
	v_mul_f32_e32 v90, v138, v90
	v_mul_f32_e32 v91, v139, v91
	v_mul_f32_e32 v92, v140, v92
	v_mul_f32_e32 v93, v141, v93
	v_add_f32_e32 v4, v4, v75
	v_add_f32_e32 v5, v5, v75
	v_add_f32_e32 v6, v6, v75
	v_add_f32_e32 v7, v7, v75
	v_add_f32_e32 v94, v94, v84
	v_add_f32_e32 v95, v95, v84
	v_add_f32_e32 v96, v96, v84
	v_add_f32_e32 v97, v97, v84
	v_exp_f32_e32 v4, v4
	v_exp_f32_e32 v5, v5
	v_exp_f32_e32 v6, v6
	v_exp_f32_e32 v7, v7
	v_exp_f32_e32 v94, v94
	v_exp_f32_e32 v95, v95
	v_exp_f32_e32 v96, v96
	v_exp_f32_e32 v97, v97
	v_add_f32_e32 v4, 1.0, v4
	v_add_f32_e32 v5, 1.0, v5
	v_add_f32_e32 v6, 1.0, v6
	v_add_f32_e32 v7, 1.0, v7
	v_add_f32_e32 v94, 1.0, v94
	v_add_f32_e32 v95, 1.0, v95
	v_add_f32_e32 v96, 1.0, v96
	v_add_f32_e32 v97, 1.0, v97
	v_rcp_f32_e32 v4, v4
	v_rcp_f32_e32 v5, v5
	v_rcp_f32_e32 v6, v6
	v_rcp_f32_e32 v7, v7
	v_rcp_f32_e32 v94, v94
	v_rcp_f32_e32 v95, v95
	v_rcp_f32_e32 v96, v96
	v_rcp_f32_e32 v97, v97
	v_mul_f32_e32 v4, v85, v4
	v_mul_f32_e32 v5, v85, v5
	v_mul_f32_e32 v6, v85, v6
	v_mul_f32_e32 v7, v85, v7
	v_mul_f32_e32 v94, v94, v166
	v_mul_f32_e32 v95, v95, v167
	v_mul_f32_e32 v96, v96, v168
	v_mul_f32_e32 v97, v97, v169
	v_exp_f32_e32 v4, v4
	v_exp_f32_e32 v5, v5
	v_exp_f32_e32 v6, v6
	v_exp_f32_e32 v7, v7
	s_nop 0
	v_fma_f32 v138, -v4, v4, 1.0
	v_fma_f32 v139, -v5, v5, 1.0
	v_fma_f32 v140, -v6, v6, 1.0
	v_fma_f32 v141, -v7, v7, 1.0
	v_max_f32_e32 v138, 0, v138
	v_max_f32_e32 v139, 0, v139
	v_max_f32_e32 v140, 0, v140
	v_max_f32_e32 v141, 0, v141
	v_sqrt_f32_e32 v138, v138
	v_sqrt_f32_e32 v139, v139
	v_sqrt_f32_e32 v140, v140
	v_sqrt_f32_e32 v141, v141
	s_nop 0
	v_mul_f32_e32 v94, v138, v94
	v_mul_f32_e32 v95, v139, v95
	v_mul_f32_e32 v96, v140, v96
	v_mul_f32_e32 v97, v141, v97
	v_add_f32_e32 v8, v8, v75
	v_add_f32_e32 v9, v9, v75
	v_add_f32_e32 v10, v10, v75
	v_add_f32_e32 v11, v11, v75
	v_add_f32_e32 v98, v98, v84
	v_add_f32_e32 v99, v99, v84
	v_add_f32_e32 v100, v100, v84
	v_add_f32_e32 v101, v101, v84
	v_exp_f32_e32 v8, v8
	v_exp_f32_e32 v9, v9
	v_exp_f32_e32 v10, v10
	v_exp_f32_e32 v11, v11
; __device__ __forceinline__ float bf2f(u16 h) { return __uint_as_float(((unsigned)h) << 16); }
; __device__ __forceinline__ void lru_tile(const Params& P, int chunk, int head, int pass, char* smem_raw) {
;     ...
; #pragma unroll
;       for (int tc = 0; tc < 4; ++tc)
; #pragma unroll
;         for (int reg = 0; reg < 4; ++reg) {
;           const int tl = wid * 16 + (lane >> 4) * 4 + reg;
;           const int c = 16 * tc + (lane & 15);
;           const float r = __builtin_amdgcn_rcpf(1.f + __builtin_amdgcn_exp2f(acc[tc][reg] + ba[tc]));
;           const float ii = __builtin_amdgcn_rcpf(1.f + __builtin_amdgcn_exp2f(acc[tc + 4][reg] + bi[tc]));
;           const float la = -c8[tc] * r;
;           const float a = __builtin_amdgcn_exp2f(la);
;           const float ucv = bf2f(sm_uc[(sb * 64 + tl) * LDSS + c]);
;           const float bt = __builtin_amdgcn_sqrtf(fmaxf(1.f - a * a, 0.f)) * (ii * ucv);
	v_exp_f32_e32 v98, v98
	v_exp_f32_e32 v99, v99
	v_exp_f32_e32 v100, v100
	v_exp_f32_e32 v101, v101
	v_add_f32_e32 v8, 1.0, v8
	v_add_f32_e32 v9, 1.0, v9
	v_add_f32_e32 v10, 1.0, v10
	v_add_f32_e32 v11, 1.0, v11
	v_add_f32_e32 v98, 1.0, v98
	v_add_f32_e32 v99, 1.0, v99
	v_add_f32_e32 v100, 1.0, v100
	v_add_f32_e32 v101, 1.0, v101
	v_rcp_f32_e32 v8, v8
	v_rcp_f32_e32 v9, v9
	v_rcp_f32_e32 v10, v10
	v_rcp_f32_e32 v11, v11
	v_rcp_f32_e32 v98, v98
	v_rcp_f32_e32 v99, v99
	v_rcp_f32_e32 v100, v100
	v_rcp_f32_e32 v101, v101
	v_mul_f32_e32 v8, v85, v8
	v_mul_f32_e32 v9, v85, v9
	v_mul_f32_e32 v10, v85, v10
	v_mul_f32_e32 v11, v85, v11
	v_mul_f32_e32 v98, v98, v170
	v_mul_f32_e32 v99, v99, v171
	v_mul_f32_e32 v100, v100, v172
	v_mul_f32_e32 v101, v101, v173
	v_exp_f32_e32 v8, v8
	v_exp_f32_e32 v9, v9
	v_exp_f32_e32 v10, v10
	v_exp_f32_e32 v11, v11
	s_nop 0
	v_fma_f32 v138, -v8, v8, 1.0
	v_fma_f32 v139, -v9, v9, 1.0
	v_fma_f32 v140, -v10, v10, 1.0
	v_fma_f32 v141, -v11, v11, 1.0
	v_max_f32_e32 v138, 0, v138
	v_max_f32_e32 v139, 0, v139
	v_max_f32_e32 v140, 0, v140
	v_max_f32_e32 v141, 0, v141
	v_sqrt_f32_e32 v138, v138
	v_sqrt_f32_e32 v139, v139
	v_sqrt_f32_e32 v140, v140
	v_sqrt_f32_e32 v141, v141
	s_nop 0
	v_mul_f32_e32 v98, v138, v98
	v_mul_f32_e32 v99, v139, v99
	v_mul_f32_e32 v100, v140, v100
	v_mul_f32_e32 v101, v141, v101
	v_add_f32_e32 v12, v12, v75
	v_add_f32_e32 v13, v13, v75
	v_add_f32_e32 v14, v14, v75
	v_add_f32_e32 v15, v15, v75
	v_add_f32_e32 v102, v102, v84
	v_add_f32_e32 v103, v103, v84
	v_add_f32_e32 v104, v104, v84
	v_add_f32_e32 v105, v105, v84
	v_exp_f32_e32 v12, v12
	v_exp_f32_e32 v13, v13
	v_exp_f32_e32 v14, v14
	v_exp_f32_e32 v15, v15
	v_exp_f32_e32 v102, v102
	v_exp_f32_e32 v103, v103
	v_exp_f32_e32 v104, v104
	v_exp_f32_e32 v105, v105
	v_add_f32_e32 v12, 1.0, v12
	v_add_f32_e32 v13, 1.0, v13
	v_add_f32_e32 v14, 1.0, v14
	v_add_f32_e32 v15, 1.0, v15
	v_add_f32_e32 v102, 1.0, v102
	v_add_f32_e32 v103, 1.0, v103
	v_add_f32_e32 v104, 1.0, v104
	v_add_f32_e32 v105, 1.0, v105
	v_rcp_f32_e32 v12, v12
	v_rcp_f32_e32 v13, v13
	v_rcp_f32_e32 v14, v14
	v_rcp_f32_e32 v15, v15
	v_rcp_f32_e32 v102, v102
	v_rcp_f32_e32 v103, v103
	v_rcp_f32_e32 v104, v104
	v_rcp_f32_e32 v105, v105
	v_mul_f32_e32 v12, v85, v12
	v_mul_f32_e32 v13, v85, v13
	v_mul_f32_e32 v14, v85, v14
	v_mul_f32_e32 v15, v85, v15
	v_mul_f32_e32 v102, v102, v174
	v_mul_f32_e32 v103, v103, v175
	v_mul_f32_e32 v104, v104, v176
	v_mul_f32_e32 v105, v105, v177
	v_exp_f32_e32 v12, v12
	v_exp_f32_e32 v13, v13
	v_exp_f32_e32 v14, v14
	v_exp_f32_e32 v15, v15
	s_nop 0
	v_fma_f32 v138, -v12, v12, 1.0
	v_fma_f32 v139, -v13, v13, 1.0
	v_fma_f32 v140, -v14, v14, 1.0
	v_fma_f32 v141, -v15, v15, 1.0
	v_max_f32_e32 v138, 0, v138
	v_max_f32_e32 v139, 0, v139
	v_max_f32_e32 v140, 0, v140
	v_max_f32_e32 v141, 0, v141
	v_sqrt_f32_e32 v138, v138
	v_sqrt_f32_e32 v139, v139
	v_sqrt_f32_e32 v140, v140
	v_sqrt_f32_e32 v141, v141
	s_nop 0
	v_mul_f32_e32 v102, v138, v102
	v_mul_f32_e32 v103, v139, v103
	v_mul_f32_e32 v104, v140, v104
	v_mul_f32_e32 v105, v141, v105
	v_add_f32_e32 v16, v16, v75
	v_add_f32_e32 v17, v17, v75
	v_add_f32_e32 v18, v18, v75
	v_add_f32_e32 v19, v19, v75
	v_add_f32_e32 v106, v106, v84
	v_add_f32_e32 v107, v107, v84
	v_add_f32_e32 v108, v108, v84
	v_add_f32_e32 v109, v109, v84
	v_exp_f32_e32 v16, v16
	v_exp_f32_e32 v17, v17
	v_exp_f32_e32 v18, v18
	v_exp_f32_e32 v19, v19
	v_exp_f32_e32 v106, v106
	v_exp_f32_e32 v107, v107
	v_exp_f32_e32 v108, v108
	v_exp_f32_e32 v109, v109
	v_add_f32_e32 v16, 1.0, v16
	v_add_f32_e32 v17, 1.0, v17
	v_add_f32_e32 v18, 1.0, v18
	v_add_f32_e32 v19, 1.0, v19
	v_add_f32_e32 v106, 1.0, v106
	v_add_f32_e32 v107, 1.0, v107
	v_add_f32_e32 v108, 1.0, v108
	v_add_f32_e32 v109, 1.0, v109
	v_rcp_f32_e32 v16, v16
	v_rcp_f32_e32 v17, v17
	v_rcp_f32_e32 v18, v18
	v_rcp_f32_e32 v19, v19
	v_rcp_f32_e32 v106, v106
	v_rcp_f32_e32 v107, v107
	v_rcp_f32_e32 v108, v108
	v_rcp_f32_e32 v109, v109
	v_mul_f32_e32 v16, v85, v16
	v_mul_f32_e32 v17, v85, v17
	v_mul_f32_e32 v18, v85, v18
	v_mul_f32_e32 v19, v85, v19
	v_mul_f32_e32 v106, v106, v178
	v_mul_f32_e32 v107, v107, v179
	v_mul_f32_e32 v108, v108, v180
	v_mul_f32_e32 v109, v109, v181
	v_exp_f32_e32 v16, v16
	v_exp_f32_e32 v17, v17
	v_exp_f32_e32 v18, v18
	v_exp_f32_e32 v19, v19
	s_nop 0
	v_fma_f32 v138, -v16, v16, 1.0
	v_fma_f32 v139, -v17, v17, 1.0
	v_fma_f32 v140, -v18, v18, 1.0
	v_fma_f32 v141, -v19, v19, 1.0
	v_max_f32_e32 v138, 0, v138
	v_max_f32_e32 v139, 0, v139
	v_max_f32_e32 v140, 0, v140
	v_max_f32_e32 v141, 0, v141
	v_sqrt_f32_e32 v138, v138
	v_sqrt_f32_e32 v139, v139
	v_sqrt_f32_e32 v140, v140
	v_sqrt_f32_e32 v141, v141
	s_nop 0
	v_mul_f32_e32 v106, v138, v106
	v_mul_f32_e32 v107, v139, v107
	v_mul_f32_e32 v108, v140, v108
	v_mul_f32_e32 v109, v141, v109
	v_add_f32_e32 v20, v20, v75
	v_add_f32_e32 v21, v21, v75
	v_add_f32_e32 v22, v22, v75
	v_add_f32_e32 v23, v23, v75
	v_add_f32_e32 v110, v110, v84
	v_add_f32_e32 v111, v111, v84
	v_add_f32_e32 v112, v112, v84
	v_add_f32_e32 v113, v113, v84
	v_exp_f32_e32 v20, v20
	v_exp_f32_e32 v21, v21
	v_exp_f32_e32 v22, v22
	v_exp_f32_e32 v23, v23
	v_exp_f32_e32 v110, v110
	v_exp_f32_e32 v111, v111
	v_exp_f32_e32 v112, v112
	v_exp_f32_e32 v113, v113
	v_add_f32_e32 v20, 1.0, v20
	v_add_f32_e32 v21, 1.0, v21
	v_add_f32_e32 v22, 1.0, v22
	v_add_f32_e32 v23, 1.0, v23
	v_add_f32_e32 v110, 1.0, v110
	v_add_f32_e32 v111, 1.0, v111
	v_add_f32_e32 v112, 1.0, v112
	v_add_f32_e32 v113, 1.0, v113
	v_rcp_f32_e32 v20, v20
	v_rcp_f32_e32 v21, v21
	v_rcp_f32_e32 v22, v22
	v_rcp_f32_e32 v23, v23
	v_rcp_f32_e32 v110, v110
	v_rcp_f32_e32 v111, v111
	v_rcp_f32_e32 v112, v112
; __device__ __forceinline__ float bf2f(u16 h) { return __uint_as_float(((unsigned)h) << 16); }
; __device__ __forceinline__ void lru_tile(const Params& P, int chunk, int head, int pass, char* smem_raw) {
;     ...
; #pragma unroll
;       for (int tc = 0; tc < 4; ++tc)
; #pragma unroll
;         for (int reg = 0; reg < 4; ++reg) {
;           const int tl = wid * 16 + (lane >> 4) * 4 + reg;
;           const int c = 16 * tc + (lane & 15);
;           const float r = __builtin_amdgcn_rcpf(1.f + __builtin_amdgcn_exp2f(acc[tc][reg] + ba[tc]));
;           const float ii = __builtin_amdgcn_rcpf(1.f + __builtin_amdgcn_exp2f(acc[tc + 4][reg] + bi[tc]));
;           const float la = -c8[tc] * r;
;           const float a = __builtin_amdgcn_exp2f(la);
;           const float ucv = bf2f(sm_uc[(sb * 64 + tl) * LDSS + c]);
;           const float bt = __builtin_amdgcn_sqrtf(fmaxf(1.f - a * a, 0.f)) * (ii * ucv);
;           sm_a[tl * 64 + c] = a;
;           sm_b[tl * 64 + c] = bt;
;         }
;       __syncthreads();
;       const int pos = (d == 0) ? q : 3 - q;
;       {
;         float Pp = 1.f, H = 0.f;
; #pragma unroll 4
;         for (int i = 0; i < 16; ++i) {
;           const int tl = (d == 0) ? (q * 16 + i) : (q * 16 + 15 - i);
;           const float a = sm_a[tl * 64 + ch], b = sm_b[tl * 64 + ch];
;           H = a * H + b; Pp *= a;
;         }
;         sm_ph[pos * 64 + ch] = make_float2(Pp, H);
	v_rcp_f32_e32 v113, v113
	v_mul_f32_e32 v20, v85, v20
	v_mul_f32_e32 v21, v85, v21
	v_mul_f32_e32 v22, v85, v22
	v_mul_f32_e32 v23, v85, v23
	v_mul_f32_e32 v110, v110, v182
	v_mul_f32_e32 v111, v111, v183
	v_mul_f32_e32 v112, v112, v184
	v_mul_f32_e32 v113, v113, v185
	v_exp_f32_e32 v20, v20
	v_exp_f32_e32 v21, v21
	v_exp_f32_e32 v22, v22
	v_exp_f32_e32 v23, v23
	s_nop 0
	v_fma_f32 v138, -v20, v20, 1.0
	v_fma_f32 v139, -v21, v21, 1.0
	v_fma_f32 v140, -v22, v22, 1.0
	v_fma_f32 v141, -v23, v23, 1.0
	v_max_f32_e32 v138, 0, v138
	v_max_f32_e32 v139, 0, v139
	v_max_f32_e32 v140, 0, v140
	v_max_f32_e32 v141, 0, v141
	v_sqrt_f32_e32 v138, v138
	v_sqrt_f32_e32 v139, v139
	v_sqrt_f32_e32 v140, v140
	v_sqrt_f32_e32 v141, v141
	s_nop 0
	v_mul_f32_e32 v110, v138, v110
	v_mul_f32_e32 v111, v139, v111
	v_mul_f32_e32 v112, v140, v112
	v_mul_f32_e32 v113, v141, v113
	v_add_f32_e32 v24, v24, v75
	v_add_f32_e32 v25, v25, v75
	v_add_f32_e32 v26, v26, v75
	v_add_f32_e32 v27, v27, v75
	v_add_f32_e32 v114, v114, v84
	v_add_f32_e32 v115, v115, v84
	v_add_f32_e32 v116, v116, v84
	v_add_f32_e32 v117, v117, v84
	v_exp_f32_e32 v24, v24
	v_exp_f32_e32 v25, v25
	v_exp_f32_e32 v26, v26
	v_exp_f32_e32 v27, v27
	v_exp_f32_e32 v114, v114
	v_exp_f32_e32 v115, v115
	v_exp_f32_e32 v116, v116
	v_exp_f32_e32 v117, v117
	v_add_f32_e32 v24, 1.0, v24
	v_add_f32_e32 v25, 1.0, v25
	v_add_f32_e32 v26, 1.0, v26
	v_add_f32_e32 v27, 1.0, v27
	v_add_f32_e32 v114, 1.0, v114
	v_add_f32_e32 v115, 1.0, v115
	v_add_f32_e32 v116, 1.0, v116
	v_add_f32_e32 v117, 1.0, v117
	v_rcp_f32_e32 v24, v24
	v_rcp_f32_e32 v25, v25
	v_rcp_f32_e32 v26, v26
	v_rcp_f32_e32 v27, v27
	v_rcp_f32_e32 v114, v114
	v_rcp_f32_e32 v115, v115
	v_rcp_f32_e32 v116, v116
	v_rcp_f32_e32 v117, v117
	v_mul_f32_e32 v24, v85, v24
	v_mul_f32_e32 v25, v85, v25
	v_mul_f32_e32 v26, v85, v26
	v_mul_f32_e32 v27, v85, v27
	v_mul_f32_e32 v114, v114, v186
	v_mul_f32_e32 v115, v115, v187
	v_mul_f32_e32 v116, v116, v188
	v_mul_f32_e32 v117, v117, v189
	v_exp_f32_e32 v24, v24
	v_exp_f32_e32 v25, v25
	v_exp_f32_e32 v26, v26
	v_exp_f32_e32 v27, v27
	s_nop 0
	v_fma_f32 v138, -v24, v24, 1.0
	v_fma_f32 v139, -v25, v25, 1.0
	v_fma_f32 v140, -v26, v26, 1.0
	v_fma_f32 v141, -v27, v27, 1.0
	v_max_f32_e32 v138, 0, v138
	v_max_f32_e32 v139, 0, v139
	v_max_f32_e32 v140, 0, v140
	v_max_f32_e32 v141, 0, v141
	v_sqrt_f32_e32 v138, v138
	v_sqrt_f32_e32 v139, v139
	v_sqrt_f32_e32 v140, v140
	v_sqrt_f32_e32 v141, v141
	s_nop 0
	v_mul_f32_e32 v114, v138, v114
	v_mul_f32_e32 v115, v139, v115
	v_mul_f32_e32 v116, v140, v116
	v_mul_f32_e32 v117, v141, v117
	v_add_f32_e32 v28, v28, v75
	v_add_f32_e32 v29, v29, v75
	v_add_f32_e32 v30, v30, v75
	v_add_f32_e32 v31, v31, v75
	v_add_f32_e32 v118, v118, v84
	v_add_f32_e32 v119, v119, v84
	v_add_f32_e32 v120, v120, v84
	v_add_f32_e32 v121, v121, v84
	v_exp_f32_e32 v28, v28
	v_exp_f32_e32 v29, v29
	v_exp_f32_e32 v30, v30
	v_exp_f32_e32 v31, v31
	v_exp_f32_e32 v118, v118
	v_exp_f32_e32 v119, v119
	v_exp_f32_e32 v120, v120
	v_exp_f32_e32 v121, v121
	v_add_f32_e32 v28, 1.0, v28
	v_add_f32_e32 v29, 1.0, v29
	v_add_f32_e32 v30, 1.0, v30
	v_add_f32_e32 v31, 1.0, v31
	v_add_f32_e32 v118, 1.0, v118
	v_add_f32_e32 v119, 1.0, v119
	v_add_f32_e32 v120, 1.0, v120
	v_add_f32_e32 v121, 1.0, v121
	v_rcp_f32_e32 v28, v28
	v_rcp_f32_e32 v29, v29
	v_rcp_f32_e32 v30, v30
	v_rcp_f32_e32 v31, v31
	v_rcp_f32_e32 v118, v118
	v_rcp_f32_e32 v119, v119
	v_rcp_f32_e32 v120, v120
	v_rcp_f32_e32 v121, v121
	v_mul_f32_e32 v28, v85, v28
	v_mul_f32_e32 v29, v85, v29
	v_mul_f32_e32 v30, v85, v30
	v_mul_f32_e32 v31, v85, v31
	v_mul_f32_e32 v118, v118, v190
	v_mul_f32_e32 v119, v119, v191
	v_mul_f32_e32 v120, v120, v192
	v_mul_f32_e32 v121, v121, v193
	v_exp_f32_e32 v28, v28
	v_exp_f32_e32 v29, v29
	v_exp_f32_e32 v30, v30
	v_exp_f32_e32 v31, v31
	s_nop 0
	v_fma_f32 v138, -v28, v28, 1.0
	v_fma_f32 v139, -v29, v29, 1.0
	v_fma_f32 v140, -v30, v30, 1.0
	v_fma_f32 v141, -v31, v31, 1.0
	v_max_f32_e32 v138, 0, v138
	v_max_f32_e32 v139, 0, v139
	v_max_f32_e32 v140, 0, v140
	v_max_f32_e32 v141, 0, v141
	v_sqrt_f32_e32 v138, v138
	v_sqrt_f32_e32 v139, v139
	v_sqrt_f32_e32 v140, v140
	v_sqrt_f32_e32 v141, v141
	s_nop 0
	v_mul_f32_e32 v118, v138, v118
	v_mul_f32_e32 v119, v139, v119
	v_mul_f32_e32 v120, v140, v120
	v_mul_f32_e32 v121, v141, v121
	v_mov_b32_e32 v253, v0
	v_mov_b32_e32 v254, v90
	v_fma_f32 v254, v1, v254, v91
	v_mul_f32_e32 v253, v253, v1
	v_fma_f32 v254, v2, v254, v92
	v_mul_f32_e32 v253, v253, v2
	v_fma_f32 v254, v3, v254, v93
	v_mul_f32_e32 v253, v253, v3
	v_fma_f32 v254, v4, v254, v94
	v_mul_f32_e32 v253, v253, v4
	v_fma_f32 v254, v5, v254, v95
	v_mul_f32_e32 v253, v253, v5
	v_fma_f32 v254, v6, v254, v96
	v_mul_f32_e32 v253, v253, v6
	v_fma_f32 v254, v7, v254, v97
	v_mul_f32_e32 v253, v253, v7
	v_fma_f32 v254, v8, v254, v98
	v_mul_f32_e32 v253, v253, v8
	v_fma_f32 v254, v9, v254, v99
	v_mul_f32_e32 v253, v253, v9
	v_fma_f32 v254, v10, v254, v100
	v_mul_f32_e32 v253, v253, v10
	v_fma_f32 v254, v11, v254, v101
	v_mul_f32_e32 v253, v253, v11
	v_fma_f32 v254, v12, v254, v102
	v_mul_f32_e32 v253, v253, v12
	v_fma_f32 v254, v13, v254, v103
	v_mul_f32_e32 v253, v253, v13
	v_fma_f32 v254, v14, v254, v104
	v_mul_f32_e32 v253, v253, v14
	v_fma_f32 v254, v15, v254, v105
	v_mul_f32_e32 v253, v253, v15
	v_fma_f32 v254, v16, v254, v106
	v_mul_f32_e32 v253, v253, v16
	v_fma_f32 v254, v17, v254, v107
	v_mul_f32_e32 v253, v253, v17
	v_fma_f32 v254, v18, v254, v108
	v_mul_f32_e32 v253, v253, v18
	v_fma_f32 v254, v19, v254, v109
	v_mul_f32_e32 v253, v253, v19
	v_fma_f32 v254, v20, v254, v110
	v_mul_f32_e32 v253, v253, v20
	v_fma_f32 v254, v21, v254, v111
; __device__ __forceinline__ float bf2f(u16 h) { return __uint_as_float(((unsigned)h) << 16); }
; __device__ __forceinline__ void lru_tile(const Params& P, int chunk, int head, int pass, char* smem_raw) {
;     ...
;         float Pp = 1.f, H = 0.f;
; #pragma unroll 4
;         for (int i = 0; i < 16; ++i) {
;           const int tl = (d == 0) ? (q * 16 + i) : (q * 16 + 15 - i);
;           const float a = sm_a[tl * 64 + ch], b = sm_b[tl * 64 + ch];
;           H = a * H + b; Pp *= a;
;         }
;         sm_ph[pos * 64 + ch] = make_float2(Pp, H);
;       }
;       __syncthreads();
;       const float2 p0 = sm_ph[ch], p1 = sm_ph[64 + ch], p2 = sm_ph[128 + ch], p3 = sm_ph[192 + ch];
;       if (pass == 2) {
;         float hin = cB;
;         if (pos > 0) hin = p0.x * hin + p0.y;
;         if (pos > 1) hin = p1.x * hin + p1.y;
;         if (pos > 2) hin = p2.x * hin + p2.y;
;         float h = hin;
;         float hfp[16], gp[16];
;         if (d == 1) {
; #pragma unroll
;           for (int i = 0; i < 16; ++i) {
;             const long rowp = row0 + sb * 64 + q * 16 + 15 - i;
;             hfp[i] = hfbuf[rowp * 512 + gch];
;             gp[i] = bf2f(P.zq[rowp * 1536 + 512 + gch]);
;           }
;         }
; #pragma unroll
;         for (int i = 0; i < 16; ++i) {
;           const int tl = (d == 0) ? (q * 16 + i) : (q * 16 + 15 - i);
;           const float a = sm_a[tl * 64 + ch], b = sm_b[tl * 64 + ch];
;           h = a * h + b;
;           const long row = row0 + sb * 64 + tl;
;           if (d == 0) {
;             hfw[row * 512 + gch] = h;
;           } else {
;             const float hfv = hfp[i];
;             const float g = gp[i];
;             const float tz = 0.7978845608028654f * (g + 0.044715f * g * g * g);
;             const float th = 1.f - 2.f * __builtin_amdgcn_rcpf(1.f + __expf(2.f * tz));
;             const float ge = 0.5f * g * (1.f + th);
;             P.cat[row * 1024 + gch] = f2bf((hfv + h) * ge);
;           }
;         }
;       }
;       cB = p0.x * cB + p0.y; cA *= p0.x;
;       cB = p1.x * cB + p1.y; cA *= p1.x;
;       cB = p2.x * cB + p2.y; cA *= p2.x;
;       cB = p3.x * cB + p3.y; cA *= p3.x;
;       __syncthreads();
;     }
;     if (pass == 1 && q == 0) P.summ[((long)d * 264 + chunk) * 512 + gch] = make_float2(cA, cB);
	v_mul_f32_e32 v253, v253, v21
	v_fma_f32 v254, v22, v254, v112
	v_mul_f32_e32 v253, v253, v22
	v_fma_f32 v254, v23, v254, v113
	v_mul_f32_e32 v253, v253, v23
	v_fma_f32 v254, v24, v254, v114
	v_mul_f32_e32 v253, v253, v24
	v_fma_f32 v254, v25, v254, v115
	v_mul_f32_e32 v253, v253, v25
	v_fma_f32 v254, v26, v254, v116
	v_mul_f32_e32 v253, v253, v26
	v_fma_f32 v254, v27, v254, v117
	v_mul_f32_e32 v253, v253, v27
	v_fma_f32 v254, v28, v254, v118
	v_mul_f32_e32 v253, v253, v28
	v_fma_f32 v254, v29, v254, v119
	v_mul_f32_e32 v253, v253, v29
	v_fma_f32 v254, v30, v254, v120
	v_mul_f32_e32 v253, v253, v30
	v_fma_f32 v254, v31, v254, v121
	v_mul_f32_e32 v253, v253, v31
	v_mov_b32_e32 v138, v253
	v_mov_b32_e32 v139, v253
	s_nop 1
	v_permlane16_swap_b32_e32 v138, v139
	v_mov_b32_e32 v140, v138
	v_mov_b32_e32 v141, v139
	s_nop 1
	v_permlane32_swap_b32_e32 v138, v140
	v_permlane32_swap_b32_e32 v139, v141
	v_mov_b32_e32 v198, v254
	v_mov_b32_e32 v199, v254
	s_nop 1
	v_permlane16_swap_b32_e32 v198, v199
	v_mov_b32_e32 v200, v198
	v_mov_b32_e32 v201, v199
	s_nop 1
	v_permlane32_swap_b32_e32 v198, v200
	v_permlane32_swap_b32_e32 v199, v201
	v_mov_b32_e32 v136, 0
	v_fma_f32 v150, v138, v136, v198
	v_fma_f32 v151, v139, v150, v199
	v_fma_f32 v202, v140, v151, v200
	v_fma_f32 v254, v141, v202, v201
	v_mul_f32_e32 v253, v138, v139
	v_mul_f32_e32 v253, v253, v140
	v_mul_f32_e32 v200, v253, v141
	v_mov_b32_e32 v201, v254
	s_add_u32 s0, s71, 0
	s_lshl_b32 s0, s0, 12
	s_lshl_b32 s1, s56, 3
	s_add_u32 s0, s0, s1
	s_add_u32 s4, s18, s0
	s_addc_u32 s5, s19, 0
	global_store_dwordx2 v250, v[200:201], s[4:5]
	ds_read_b128 v[76:79], v131 offset:0
	ds_read_b128 v[80:83], v133 offset:0
	ds_read_b128 v[122:125], v131 offset:512
	ds_read_b128 v[126:129], v133 offset:512
	s_waitcnt vmcnt(0)
	s_waitcnt lgkmcnt(3)
	v_mfma_f32_16x16x32_bf16 v[0:3], v[76:79], v[238:241], 0
	v_mfma_f32_16x16x32_bf16 v[90:93], v[76:79], v[246:249], 0
	ds_read_b128 v[76:79], v131 offset:1024
	s_waitcnt lgkmcnt(3)
	v_mfma_f32_16x16x32_bf16 v[0:3], v[80:83], v[242:245], v[0:3]
	v_mfma_f32_16x16x32_bf16 v[90:93], v[80:83], v[194:197], v[90:93]
	ds_read_b128 v[80:83], v133 offset:1024
	s_waitcnt lgkmcnt(3)
	v_mfma_f32_16x16x32_bf16 v[4:7], v[122:125], v[238:241], 0
	v_mfma_f32_16x16x32_bf16 v[94:97], v[122:125], v[246:249], 0
	ds_read_b128 v[122:125], v131 offset:1536
	s_waitcnt lgkmcnt(3)
	v_mfma_f32_16x16x32_bf16 v[4:7], v[126:129], v[242:245], v[4:7]
	v_mfma_f32_16x16x32_bf16 v[94:97], v[126:129], v[194:197], v[94:97]
	ds_read_b128 v[126:129], v133 offset:1536
	s_waitcnt lgkmcnt(3)
	v_mfma_f32_16x16x32_bf16 v[8:11], v[76:79], v[238:241], 0
	v_mfma_f32_16x16x32_bf16 v[98:101], v[76:79], v[246:249], 0
	ds_read_b128 v[76:79], v131 offset:2048
	s_waitcnt lgkmcnt(3)
	v_mfma_f32_16x16x32_bf16 v[8:11], v[80:83], v[242:245], v[8:11]
	v_mfma_f32_16x16x32_bf16 v[98:101], v[80:83], v[194:197], v[98:101]
	ds_read_b128 v[80:83], v133 offset:2048
	s_waitcnt lgkmcnt(3)
	v_mfma_f32_16x16x32_bf16 v[12:15], v[122:125], v[238:241], 0
	v_mfma_f32_16x16x32_bf16 v[102:105], v[122:125], v[246:249], 0
	ds_read_b128 v[122:125], v131 offset:2560
	s_waitcnt lgkmcnt(3)
	v_mfma_f32_16x16x32_bf16 v[12:15], v[126:129], v[242:245], v[12:15]
	v_mfma_f32_16x16x32_bf16 v[102:105], v[126:129], v[194:197], v[102:105]
	ds_read_b128 v[126:129], v133 offset:2560
	s_waitcnt lgkmcnt(3)
	v_mfma_f32_16x16x32_bf16 v[16:19], v[76:79], v[238:241], 0
	v_mfma_f32_16x16x32_bf16 v[106:109], v[76:79], v[246:249], 0
	ds_read_b128 v[76:79], v131 offset:3072
	s_waitcnt lgkmcnt(3)
	v_mfma_f32_16x16x32_bf16 v[16:19], v[80:83], v[242:245], v[16:19]
	v_mfma_f32_16x16x32_bf16 v[106:109], v[80:83], v[194:197], v[106:109]
	ds_read_b128 v[80:83], v133 offset:3072
	s_waitcnt lgkmcnt(3)
	v_mfma_f32_16x16x32_bf16 v[20:23], v[122:125], v[238:241], 0
	v_mfma_f32_16x16x32_bf16 v[110:113], v[122:125], v[246:249], 0
	ds_read_b128 v[122:125], v131 offset:3584
	s_waitcnt lgkmcnt(3)
	v_mfma_f32_16x16x32_bf16 v[20:23], v[126:129], v[242:245], v[20:23]
	v_mfma_f32_16x16x32_bf16 v[110:113], v[126:129], v[194:197], v[110:113]
	ds_read_b128 v[126:129], v133 offset:3584
	s_waitcnt lgkmcnt(3)
	v_mfma_f32_16x16x32_bf16 v[24:27], v[76:79], v[238:241], 0
	v_mfma_f32_16x16x32_bf16 v[114:117], v[76:79], v[246:249], 0
	s_waitcnt lgkmcnt(2)
	v_mfma_f32_16x16x32_bf16 v[24:27], v[80:83], v[242:245], v[24:27]
	v_mfma_f32_16x16x32_bf16 v[114:117], v[80:83], v[194:197], v[114:117]
	s_waitcnt lgkmcnt(1)
	v_mfma_f32_16x16x32_bf16 v[28:31], v[122:125], v[238:241], 0
	v_mfma_f32_16x16x32_bf16 v[118:121], v[122:125], v[246:249], 0
	s_waitcnt lgkmcnt(0)
; __device__ __forceinline__ float bf2f(u16 h) { return __uint_as_float(((unsigned)h) << 16); }
; __device__ __forceinline__ void lru_tile(const Params& P, int chunk, int head, int pass, char* smem_raw) {
;     ...
;       ba[tc] = P.b_a[cidx] * -1.4426950408889634f; bi[tc] = P.b_i[cidx] * -1.4426950408889634f;
;       const float nl = -P.lam[cidx];
;       const float e_ = __expf(nl);
;       const float sp = (nl > 20.f) ? nl
;                      : (e_ < 0.03f ? e_ * (1.f - e_ * (0.5f - e_ * (0.33333334f - 0.25f * e_))) : __logf(1.f + e_));
;       c8[tc] = 8.f * 1.4426950408889634f * sp;
;     ...
; #pragma unroll
;       for (int tc = 0; tc < 4; ++tc)
; #pragma unroll
;         for (int reg = 0; reg < 4; ++reg) {
;           const int tl = wid * 16 + (lane >> 4) * 4 + reg;
;           const int c = 16 * tc + (lane & 15);
;           const float r = __builtin_amdgcn_rcpf(1.f + __builtin_amdgcn_exp2f(acc[tc][reg] + ba[tc]));
;           const float ii = __builtin_amdgcn_rcpf(1.f + __builtin_amdgcn_exp2f(acc[tc + 4][reg] + bi[tc]));
;           const float la = -c8[tc] * r;
;           const float a = __builtin_amdgcn_exp2f(la);
;           const float ucv = bf2f(sm_uc[(sb * 64 + tl) * LDSS + c]);
;           const float bt = __builtin_amdgcn_sqrtf(fmaxf(1.f - a * a, 0.f)) * (ii * ucv);
	v_mfma_f32_16x16x32_bf16 v[28:31], v[126:129], v[242:245], v[28:31]
	v_mfma_f32_16x16x32_bf16 v[118:121], v[126:129], v[194:197], v[118:121]
	v_mul_f32_e32 v68, 0xbfb8aa3b, v68
	v_mul_f32_e32 v70, 0xbfb8aa3b, v70
	v_sub_f32_e32 v138, 0, v73
	v_mul_f32_e32 v139, 0x3fb8aa3b, v138
	v_exp_f32_e32 v139, v139
	s_nop 0
	v_mul_f32_e32 v140, 0xbe800000, v139
	v_add_f32_e32 v140, 0x3eaaaaab, v140
	v_fma_f32 v140, -v139, v140, 0.5
	v_fma_f32 v140, -v139, v140, 1.0
	v_mul_f32_e32 v140, v139, v140
	v_add_f32_e32 v141, 1.0, v139
	v_log_f32_e32 v141, v141
	v_mov_b32_e32 v255, 0x3cf5c28f
	v_mul_f32_e32 v141, 0x3f317218, v141
	v_cmp_gt_f32_e32 vcc, v255, v139
	s_nop 1
	v_cndmask_b32_e32 v140, v141, v140, vcc
	v_mov_b32_e32 v255, 0x41a00000
	v_cmp_lt_f32_e32 vcc, v255, v138
	s_nop 1
	v_cndmask_b32_e32 v140, v140, v138, vcc
	v_mul_f32_e32 v73, 0xc138aa3b, v140
	s_nop 7
	v_add_f32_e32 v0, v0, v68
	v_add_f32_e32 v1, v1, v68
	v_add_f32_e32 v2, v2, v68
	v_add_f32_e32 v3, v3, v68
	v_add_f32_e32 v90, v90, v70
	v_add_f32_e32 v91, v91, v70
	v_add_f32_e32 v92, v92, v70
	v_add_f32_e32 v93, v93, v70
	v_exp_f32_e32 v0, v0
	v_exp_f32_e32 v1, v1
	v_exp_f32_e32 v2, v2
	v_exp_f32_e32 v3, v3
	v_exp_f32_e32 v90, v90
	v_exp_f32_e32 v91, v91
	v_exp_f32_e32 v92, v92
	v_exp_f32_e32 v93, v93
	v_add_f32_e32 v0, 1.0, v0
	v_add_f32_e32 v1, 1.0, v1
	v_add_f32_e32 v2, 1.0, v2
	v_add_f32_e32 v3, 1.0, v3
	v_add_f32_e32 v90, 1.0, v90
	v_add_f32_e32 v91, 1.0, v91
	v_add_f32_e32 v92, 1.0, v92
	v_add_f32_e32 v93, 1.0, v93
	v_rcp_f32_e32 v0, v0
	v_rcp_f32_e32 v1, v1
	v_rcp_f32_e32 v2, v2
	v_rcp_f32_e32 v3, v3
	v_rcp_f32_e32 v90, v90
	v_rcp_f32_e32 v91, v91
	v_rcp_f32_e32 v92, v92
	v_rcp_f32_e32 v93, v93
	v_mul_f32_e32 v0, v73, v0
	v_mul_f32_e32 v1, v73, v1
	v_mul_f32_e32 v2, v73, v2
	v_mul_f32_e32 v3, v73, v3
	v_mul_f32_e32 v90, v90, v162
	v_mul_f32_e32 v91, v91, v163
	v_mul_f32_e32 v92, v92, v164
	v_mul_f32_e32 v93, v93, v165
	v_exp_f32_e32 v0, v0
	v_exp_f32_e32 v1, v1
	v_exp_f32_e32 v2, v2
	v_exp_f32_e32 v3, v3
	s_nop 0
	v_fma_f32 v138, -v0, v0, 1.0
	v_fma_f32 v139, -v1, v1, 1.0
	v_fma_f32 v140, -v2, v2, 1.0
	v_fma_f32 v141, -v3, v3, 1.0
	v_max_f32_e32 v138, 0, v138
	v_max_f32_e32 v139, 0, v139
	v_max_f32_e32 v140, 0, v140
	v_max_f32_e32 v141, 0, v141
	v_sqrt_f32_e32 v138, v138
	v_sqrt_f32_e32 v139, v139
	v_sqrt_f32_e32 v140, v140
	v_sqrt_f32_e32 v141, v141
	s_nop 0
	v_mul_f32_e32 v90, v138, v90
	v_mul_f32_e32 v91, v139, v91
	v_mul_f32_e32 v92, v140, v92
	v_mul_f32_e32 v93, v141, v93
	v_add_f32_e32 v4, v4, v68
	v_add_f32_e32 v5, v5, v68
	v_add_f32_e32 v6, v6, v68
	v_add_f32_e32 v7, v7, v68
	v_add_f32_e32 v94, v94, v70
	v_add_f32_e32 v95, v95, v70
	v_add_f32_e32 v96, v96, v70
	v_add_f32_e32 v97, v97, v70
	v_exp_f32_e32 v4, v4
	v_exp_f32_e32 v5, v5
	v_exp_f32_e32 v6, v6
	v_exp_f32_e32 v7, v7
	v_exp_f32_e32 v94, v94
	v_exp_f32_e32 v95, v95
	v_exp_f32_e32 v96, v96
	v_exp_f32_e32 v97, v97
	v_add_f32_e32 v4, 1.0, v4
	v_add_f32_e32 v5, 1.0, v5
	v_add_f32_e32 v6, 1.0, v6
	v_add_f32_e32 v7, 1.0, v7
	v_add_f32_e32 v94, 1.0, v94
	v_add_f32_e32 v95, 1.0, v95
	v_add_f32_e32 v96, 1.0, v96
	v_add_f32_e32 v97, 1.0, v97
	v_rcp_f32_e32 v4, v4
	v_rcp_f32_e32 v5, v5
	v_rcp_f32_e32 v6, v6
	v_rcp_f32_e32 v7, v7
	v_rcp_f32_e32 v94, v94
	v_rcp_f32_e32 v95, v95
	v_rcp_f32_e32 v96, v96
	v_rcp_f32_e32 v97, v97
	v_mul_f32_e32 v4, v73, v4
	v_mul_f32_e32 v5, v73, v5
	v_mul_f32_e32 v6, v73, v6
	v_mul_f32_e32 v7, v73, v7
	v_mul_f32_e32 v94, v94, v166
	v_mul_f32_e32 v95, v95, v167
	v_mul_f32_e32 v96, v96, v168
	v_mul_f32_e32 v97, v97, v169
	v_exp_f32_e32 v4, v4
	v_exp_f32_e32 v5, v5
	v_exp_f32_e32 v6, v6
	v_exp_f32_e32 v7, v7
	s_nop 0
	v_fma_f32 v138, -v4, v4, 1.0
	v_fma_f32 v139, -v5, v5, 1.0
	v_fma_f32 v140, -v6, v6, 1.0
	v_fma_f32 v141, -v7, v7, 1.0
	v_max_f32_e32 v138, 0, v138
	v_max_f32_e32 v139, 0, v139
	v_max_f32_e32 v140, 0, v140
	v_max_f32_e32 v141, 0, v141
	v_sqrt_f32_e32 v138, v138
	v_sqrt_f32_e32 v139, v139
	v_sqrt_f32_e32 v140, v140
	v_sqrt_f32_e32 v141, v141
	s_nop 0
	v_mul_f32_e32 v94, v138, v94
	v_mul_f32_e32 v95, v139, v95
	v_mul_f32_e32 v96, v140, v96
	v_mul_f32_e32 v97, v141, v97
	v_add_f32_e32 v8, v8, v68
	v_add_f32_e32 v9, v9, v68
	v_add_f32_e32 v10, v10, v68
	v_add_f32_e32 v11, v11, v68
	v_add_f32_e32 v98, v98, v70
	v_add_f32_e32 v99, v99, v70
	v_add_f32_e32 v100, v100, v70
	v_add_f32_e32 v101, v101, v70
	v_exp_f32_e32 v8, v8
	v_exp_f32_e32 v9, v9
	v_exp_f32_e32 v10, v10
	v_exp_f32_e32 v11, v11
	v_exp_f32_e32 v98, v98
	v_exp_f32_e32 v99, v99
	v_exp_f32_e32 v100, v100
	v_exp_f32_e32 v101, v101
	v_add_f32_e32 v8, 1.0, v8
	v_add_f32_e32 v9, 1.0, v9
	v_add_f32_e32 v10, 1.0, v10
	v_add_f32_e32 v11, 1.0, v11
	v_add_f32_e32 v98, 1.0, v98
	v_add_f32_e32 v99, 1.0, v99
	v_add_f32_e32 v100, 1.0, v100
	v_add_f32_e32 v101, 1.0, v101
	v_rcp_f32_e32 v8, v8
	v_rcp_f32_e32 v9, v9
	v_rcp_f32_e32 v10, v10
	v_rcp_f32_e32 v11, v11
	v_rcp_f32_e32 v98, v98
	v_rcp_f32_e32 v99, v99
	v_rcp_f32_e32 v100, v100
	v_rcp_f32_e32 v101, v101
	v_mul_f32_e32 v8, v73, v8
	v_mul_f32_e32 v9, v73, v9
	v_mul_f32_e32 v10, v73, v10
	v_mul_f32_e32 v11, v73, v11
	v_mul_f32_e32 v98, v98, v170
	v_mul_f32_e32 v99, v99, v171
	v_mul_f32_e32 v100, v100, v172
	v_mul_f32_e32 v101, v101, v173
	v_exp_f32_e32 v8, v8
	v_exp_f32_e32 v9, v9
	v_exp_f32_e32 v10, v10
	v_exp_f32_e32 v11, v11
	s_nop 0
	v_fma_f32 v138, -v8, v8, 1.0
	v_fma_f32 v139, -v9, v9, 1.0
	v_fma_f32 v140, -v10, v10, 1.0
	v_fma_f32 v141, -v11, v11, 1.0
	v_max_f32_e32 v138, 0, v138
	v_max_f32_e32 v139, 0, v139
	v_max_f32_e32 v140, 0, v140
	v_max_f32_e32 v141, 0, v141
	v_sqrt_f32_e32 v138, v138
	v_sqrt_f32_e32 v139, v139
	v_sqrt_f32_e32 v140, v140
	v_sqrt_f32_e32 v141, v141
	s_nop 0
; __device__ __forceinline__ float bf2f(u16 h) { return __uint_as_float(((unsigned)h) << 16); }
; __device__ __forceinline__ void lru_tile(const Params& P, int chunk, int head, int pass, char* smem_raw) {
;     ...
; #pragma unroll
;       for (int tc = 0; tc < 4; ++tc)
; #pragma unroll
;         for (int reg = 0; reg < 4; ++reg) {
;           const int tl = wid * 16 + (lane >> 4) * 4 + reg;
;           const int c = 16 * tc + (lane & 15);
;           const float r = __builtin_amdgcn_rcpf(1.f + __builtin_amdgcn_exp2f(acc[tc][reg] + ba[tc]));
;           const float ii = __builtin_amdgcn_rcpf(1.f + __builtin_amdgcn_exp2f(acc[tc + 4][reg] + bi[tc]));
;           const float la = -c8[tc] * r;
;           const float a = __builtin_amdgcn_exp2f(la);
;           const float ucv = bf2f(sm_uc[(sb * 64 + tl) * LDSS + c]);
;           const float bt = __builtin_amdgcn_sqrtf(fmaxf(1.f - a * a, 0.f)) * (ii * ucv);
	v_mul_f32_e32 v98, v138, v98
	v_mul_f32_e32 v99, v139, v99
	v_mul_f32_e32 v100, v140, v100
	v_mul_f32_e32 v101, v141, v101
	v_add_f32_e32 v12, v12, v68
	v_add_f32_e32 v13, v13, v68
	v_add_f32_e32 v14, v14, v68
	v_add_f32_e32 v15, v15, v68
	v_add_f32_e32 v102, v102, v70
	v_add_f32_e32 v103, v103, v70
	v_add_f32_e32 v104, v104, v70
	v_add_f32_e32 v105, v105, v70
	v_exp_f32_e32 v12, v12
	v_exp_f32_e32 v13, v13
	v_exp_f32_e32 v14, v14
	v_exp_f32_e32 v15, v15
	v_exp_f32_e32 v102, v102
	v_exp_f32_e32 v103, v103
	v_exp_f32_e32 v104, v104
	v_exp_f32_e32 v105, v105
	v_add_f32_e32 v12, 1.0, v12
	v_add_f32_e32 v13, 1.0, v13
	v_add_f32_e32 v14, 1.0, v14
	v_add_f32_e32 v15, 1.0, v15
	v_add_f32_e32 v102, 1.0, v102
	v_add_f32_e32 v103, 1.0, v103
	v_add_f32_e32 v104, 1.0, v104
	v_add_f32_e32 v105, 1.0, v105
	v_rcp_f32_e32 v12, v12
	v_rcp_f32_e32 v13, v13
	v_rcp_f32_e32 v14, v14
	v_rcp_f32_e32 v15, v15
	v_rcp_f32_e32 v102, v102
	v_rcp_f32_e32 v103, v103
	v_rcp_f32_e32 v104, v104
	v_rcp_f32_e32 v105, v105
	v_mul_f32_e32 v12, v73, v12
	v_mul_f32_e32 v13, v73, v13
	v_mul_f32_e32 v14, v73, v14
	v_mul_f32_e32 v15, v73, v15
	v_mul_f32_e32 v102, v102, v174
	v_mul_f32_e32 v103, v103, v175
	v_mul_f32_e32 v104, v104, v176
	v_mul_f32_e32 v105, v105, v177
	v_exp_f32_e32 v12, v12
	v_exp_f32_e32 v13, v13
	v_exp_f32_e32 v14, v14
	v_exp_f32_e32 v15, v15
	s_nop 0
	v_fma_f32 v138, -v12, v12, 1.0
	v_fma_f32 v139, -v13, v13, 1.0
	v_fma_f32 v140, -v14, v14, 1.0
	v_fma_f32 v141, -v15, v15, 1.0
	v_max_f32_e32 v138, 0, v138
	v_max_f32_e32 v139, 0, v139
	v_max_f32_e32 v140, 0, v140
	v_max_f32_e32 v141, 0, v141
	v_sqrt_f32_e32 v138, v138
	v_sqrt_f32_e32 v139, v139
	v_sqrt_f32_e32 v140, v140
	v_sqrt_f32_e32 v141, v141
	s_nop 0
	v_mul_f32_e32 v102, v138, v102
	v_mul_f32_e32 v103, v139, v103
	v_mul_f32_e32 v104, v140, v104
	v_mul_f32_e32 v105, v141, v105
	v_add_f32_e32 v16, v16, v68
	v_add_f32_e32 v17, v17, v68
	v_add_f32_e32 v18, v18, v68
	v_add_f32_e32 v19, v19, v68
	v_add_f32_e32 v106, v106, v70
	v_add_f32_e32 v107, v107, v70
	v_add_f32_e32 v108, v108, v70
	v_add_f32_e32 v109, v109, v70
	v_exp_f32_e32 v16, v16
	v_exp_f32_e32 v17, v17
	v_exp_f32_e32 v18, v18
	v_exp_f32_e32 v19, v19
	v_exp_f32_e32 v106, v106
	v_exp_f32_e32 v107, v107
	v_exp_f32_e32 v108, v108
	v_exp_f32_e32 v109, v109
	v_add_f32_e32 v16, 1.0, v16
	v_add_f32_e32 v17, 1.0, v17
	v_add_f32_e32 v18, 1.0, v18
	v_add_f32_e32 v19, 1.0, v19
	v_add_f32_e32 v106, 1.0, v106
	v_add_f32_e32 v107, 1.0, v107
	v_add_f32_e32 v108, 1.0, v108
	v_add_f32_e32 v109, 1.0, v109
	v_rcp_f32_e32 v16, v16
	v_rcp_f32_e32 v17, v17
	v_rcp_f32_e32 v18, v18
	v_rcp_f32_e32 v19, v19
	v_rcp_f32_e32 v106, v106
	v_rcp_f32_e32 v107, v107
	v_rcp_f32_e32 v108, v108
	v_rcp_f32_e32 v109, v109
	v_mul_f32_e32 v16, v73, v16
	v_mul_f32_e32 v17, v73, v17
	v_mul_f32_e32 v18, v73, v18
	v_mul_f32_e32 v19, v73, v19
	v_mul_f32_e32 v106, v106, v178
	v_mul_f32_e32 v107, v107, v179
	v_mul_f32_e32 v108, v108, v180
	v_mul_f32_e32 v109, v109, v181
	v_exp_f32_e32 v16, v16
	v_exp_f32_e32 v17, v17
	v_exp_f32_e32 v18, v18
	v_exp_f32_e32 v19, v19
	s_nop 0
	v_fma_f32 v138, -v16, v16, 1.0
	v_fma_f32 v139, -v17, v17, 1.0
	v_fma_f32 v140, -v18, v18, 1.0
	v_fma_f32 v141, -v19, v19, 1.0
	v_max_f32_e32 v138, 0, v138
	v_max_f32_e32 v139, 0, v139
	v_max_f32_e32 v140, 0, v140
	v_max_f32_e32 v141, 0, v141
	v_sqrt_f32_e32 v138, v138
	v_sqrt_f32_e32 v139, v139
	v_sqrt_f32_e32 v140, v140
	v_sqrt_f32_e32 v141, v141
	s_nop 0
	v_mul_f32_e32 v106, v138, v106
	v_mul_f32_e32 v107, v139, v107
	v_mul_f32_e32 v108, v140, v108
	v_mul_f32_e32 v109, v141, v109
	v_add_f32_e32 v20, v20, v68
	v_add_f32_e32 v21, v21, v68
	v_add_f32_e32 v22, v22, v68
	v_add_f32_e32 v23, v23, v68
	v_add_f32_e32 v110, v110, v70
	v_add_f32_e32 v111, v111, v70
	v_add_f32_e32 v112, v112, v70
	v_add_f32_e32 v113, v113, v70
	v_exp_f32_e32 v20, v20
	v_exp_f32_e32 v21, v21
	v_exp_f32_e32 v22, v22
	v_exp_f32_e32 v23, v23
	v_exp_f32_e32 v110, v110
	v_exp_f32_e32 v111, v111
	v_exp_f32_e32 v112, v112
	v_exp_f32_e32 v113, v113
	v_add_f32_e32 v20, 1.0, v20
	v_add_f32_e32 v21, 1.0, v21
	v_add_f32_e32 v22, 1.0, v22
	v_add_f32_e32 v23, 1.0, v23
	v_add_f32_e32 v110, 1.0, v110
	v_add_f32_e32 v111, 1.0, v111
	v_add_f32_e32 v112, 1.0, v112
	v_add_f32_e32 v113, 1.0, v113
	v_rcp_f32_e32 v20, v20
	v_rcp_f32_e32 v21, v21
	v_rcp_f32_e32 v22, v22
	v_rcp_f32_e32 v23, v23
	v_rcp_f32_e32 v110, v110
	v_rcp_f32_e32 v111, v111
	v_rcp_f32_e32 v112, v112
	v_rcp_f32_e32 v113, v113
	v_mul_f32_e32 v20, v73, v20
	v_mul_f32_e32 v21, v73, v21
	v_mul_f32_e32 v22, v73, v22
	v_mul_f32_e32 v23, v73, v23
	v_mul_f32_e32 v110, v110, v182
	v_mul_f32_e32 v111, v111, v183
	v_mul_f32_e32 v112, v112, v184
	v_mul_f32_e32 v113, v113, v185
	v_exp_f32_e32 v20, v20
	v_exp_f32_e32 v21, v21
	v_exp_f32_e32 v22, v22
	v_exp_f32_e32 v23, v23
	s_nop 0
	v_fma_f32 v138, -v20, v20, 1.0
	v_fma_f32 v139, -v21, v21, 1.0
	v_fma_f32 v140, -v22, v22, 1.0
	v_fma_f32 v141, -v23, v23, 1.0
	v_max_f32_e32 v138, 0, v138
	v_max_f32_e32 v139, 0, v139
	v_max_f32_e32 v140, 0, v140
	v_max_f32_e32 v141, 0, v141
	v_sqrt_f32_e32 v138, v138
	v_sqrt_f32_e32 v139, v139
	v_sqrt_f32_e32 v140, v140
	v_sqrt_f32_e32 v141, v141
	s_nop 0
	v_mul_f32_e32 v110, v138, v110
	v_mul_f32_e32 v111, v139, v111
	v_mul_f32_e32 v112, v140, v112
	v_mul_f32_e32 v113, v141, v113
	v_add_f32_e32 v24, v24, v68
	v_add_f32_e32 v25, v25, v68
	v_add_f32_e32 v26, v26, v68
	v_add_f32_e32 v27, v27, v68
	v_add_f32_e32 v114, v114, v70
	v_add_f32_e32 v115, v115, v70
	v_add_f32_e32 v116, v116, v70
	v_add_f32_e32 v117, v117, v70
	v_exp_f32_e32 v24, v24
	v_exp_f32_e32 v25, v25
	v_exp_f32_e32 v26, v26
	v_exp_f32_e32 v27, v27
	v_exp_f32_e32 v114, v114
; __device__ __forceinline__ float bf2f(u16 h) { return __uint_as_float(((unsigned)h) << 16); }
; __device__ __forceinline__ void lru_tile(const Params& P, int chunk, int head, int pass, char* smem_raw) {
;     ...
; #pragma unroll
;       for (int tc = 0; tc < 4; ++tc)
; #pragma unroll
;         for (int reg = 0; reg < 4; ++reg) {
;           const int tl = wid * 16 + (lane >> 4) * 4 + reg;
;           const int c = 16 * tc + (lane & 15);
;           const float r = __builtin_amdgcn_rcpf(1.f + __builtin_amdgcn_exp2f(acc[tc][reg] + ba[tc]));
;           const float ii = __builtin_amdgcn_rcpf(1.f + __builtin_amdgcn_exp2f(acc[tc + 4][reg] + bi[tc]));
;           const float la = -c8[tc] * r;
;           const float a = __builtin_amdgcn_exp2f(la);
;           const float ucv = bf2f(sm_uc[(sb * 64 + tl) * LDSS + c]);
;           const float bt = __builtin_amdgcn_sqrtf(fmaxf(1.f - a * a, 0.f)) * (ii * ucv);
;           sm_a[tl * 64 + c] = a;
;           sm_b[tl * 64 + c] = bt;
;         }
;       __syncthreads();
;       const int pos = (d == 0) ? q : 3 - q;
;       {
;         float Pp = 1.f, H = 0.f;
; #pragma unroll 4
;         for (int i = 0; i < 16; ++i) {
;           const int tl = (d == 0) ? (q * 16 + i) : (q * 16 + 15 - i);
;           const float a = sm_a[tl * 64 + ch], b = sm_b[tl * 64 + ch];
;           H = a * H + b; Pp *= a;
;         }
;         sm_ph[pos * 64 + ch] = make_float2(Pp, H);
;     ...
;       cB = p0.x * cB + p0.y; cA *= p0.x;
;       cB = p1.x * cB + p1.y; cA *= p1.x;
;       cB = p2.x * cB + p2.y; cA *= p2.x;
;       cB = p3.x * cB + p3.y; cA *= p3.x;
;       __syncthreads();
;     }
;     if (pass == 1 && q == 0) P.summ[((long)d * 264 + chunk) * 512 + gch] = make_float2(cA, cB);
	v_exp_f32_e32 v115, v115
	v_exp_f32_e32 v116, v116
	v_exp_f32_e32 v117, v117
	v_add_f32_e32 v24, 1.0, v24
	v_add_f32_e32 v25, 1.0, v25
	v_add_f32_e32 v26, 1.0, v26
	v_add_f32_e32 v27, 1.0, v27
	v_add_f32_e32 v114, 1.0, v114
	v_add_f32_e32 v115, 1.0, v115
	v_add_f32_e32 v116, 1.0, v116
	v_add_f32_e32 v117, 1.0, v117
	v_rcp_f32_e32 v24, v24
	v_rcp_f32_e32 v25, v25
	v_rcp_f32_e32 v26, v26
	v_rcp_f32_e32 v27, v27
	v_rcp_f32_e32 v114, v114
	v_rcp_f32_e32 v115, v115
	v_rcp_f32_e32 v116, v116
	v_rcp_f32_e32 v117, v117
	v_mul_f32_e32 v24, v73, v24
	v_mul_f32_e32 v25, v73, v25
	v_mul_f32_e32 v26, v73, v26
	v_mul_f32_e32 v27, v73, v27
	v_mul_f32_e32 v114, v114, v186
	v_mul_f32_e32 v115, v115, v187
	v_mul_f32_e32 v116, v116, v188
	v_mul_f32_e32 v117, v117, v189
	v_exp_f32_e32 v24, v24
	v_exp_f32_e32 v25, v25
	v_exp_f32_e32 v26, v26
	v_exp_f32_e32 v27, v27
	s_nop 0
	v_fma_f32 v138, -v24, v24, 1.0
	v_fma_f32 v139, -v25, v25, 1.0
	v_fma_f32 v140, -v26, v26, 1.0
	v_fma_f32 v141, -v27, v27, 1.0
	v_max_f32_e32 v138, 0, v138
	v_max_f32_e32 v139, 0, v139
	v_max_f32_e32 v140, 0, v140
	v_max_f32_e32 v141, 0, v141
	v_sqrt_f32_e32 v138, v138
	v_sqrt_f32_e32 v139, v139
	v_sqrt_f32_e32 v140, v140
	v_sqrt_f32_e32 v141, v141
	s_nop 0
	v_mul_f32_e32 v114, v138, v114
	v_mul_f32_e32 v115, v139, v115
	v_mul_f32_e32 v116, v140, v116
	v_mul_f32_e32 v117, v141, v117
	v_add_f32_e32 v28, v28, v68
	v_add_f32_e32 v29, v29, v68
	v_add_f32_e32 v30, v30, v68
	v_add_f32_e32 v31, v31, v68
	v_add_f32_e32 v118, v118, v70
	v_add_f32_e32 v119, v119, v70
	v_add_f32_e32 v120, v120, v70
	v_add_f32_e32 v121, v121, v70
	v_exp_f32_e32 v28, v28
	v_exp_f32_e32 v29, v29
	v_exp_f32_e32 v30, v30
	v_exp_f32_e32 v31, v31
	v_exp_f32_e32 v118, v118
	v_exp_f32_e32 v119, v119
	v_exp_f32_e32 v120, v120
	v_exp_f32_e32 v121, v121
	v_add_f32_e32 v28, 1.0, v28
	v_add_f32_e32 v29, 1.0, v29
	v_add_f32_e32 v30, 1.0, v30
	v_add_f32_e32 v31, 1.0, v31
	v_add_f32_e32 v118, 1.0, v118
	v_add_f32_e32 v119, 1.0, v119
	v_add_f32_e32 v120, 1.0, v120
	v_add_f32_e32 v121, 1.0, v121
	v_rcp_f32_e32 v28, v28
	v_rcp_f32_e32 v29, v29
	v_rcp_f32_e32 v30, v30
	v_rcp_f32_e32 v31, v31
	v_rcp_f32_e32 v118, v118
	v_rcp_f32_e32 v119, v119
	v_rcp_f32_e32 v120, v120
	v_rcp_f32_e32 v121, v121
	v_mul_f32_e32 v28, v73, v28
	v_mul_f32_e32 v29, v73, v29
	v_mul_f32_e32 v30, v73, v30
	v_mul_f32_e32 v31, v73, v31
	v_mul_f32_e32 v118, v118, v190
	v_mul_f32_e32 v119, v119, v191
	v_mul_f32_e32 v120, v120, v192
	v_mul_f32_e32 v121, v121, v193
	v_exp_f32_e32 v28, v28
	v_exp_f32_e32 v29, v29
	v_exp_f32_e32 v30, v30
	v_exp_f32_e32 v31, v31
	s_nop 0
	v_fma_f32 v138, -v28, v28, 1.0
	v_fma_f32 v139, -v29, v29, 1.0
	v_fma_f32 v140, -v30, v30, 1.0
	v_fma_f32 v141, -v31, v31, 1.0
	v_max_f32_e32 v138, 0, v138
	v_max_f32_e32 v139, 0, v139
	v_max_f32_e32 v140, 0, v140
	v_max_f32_e32 v141, 0, v141
	v_sqrt_f32_e32 v138, v138
	v_sqrt_f32_e32 v139, v139
	v_sqrt_f32_e32 v140, v140
	v_sqrt_f32_e32 v141, v141
	s_nop 0
	v_mul_f32_e32 v118, v138, v118
	v_mul_f32_e32 v119, v139, v119
	v_mul_f32_e32 v120, v140, v120
	v_mul_f32_e32 v121, v141, v121
	v_mov_b32_e32 v253, v31
	v_mov_b32_e32 v254, v121
	v_fma_f32 v254, v30, v254, v120
	v_mul_f32_e32 v253, v253, v30
	v_fma_f32 v254, v29, v254, v119
	v_mul_f32_e32 v253, v253, v29
	v_fma_f32 v254, v28, v254, v118
	v_mul_f32_e32 v253, v253, v28
	v_fma_f32 v254, v27, v254, v117
	v_mul_f32_e32 v253, v253, v27
	v_fma_f32 v254, v26, v254, v116
	v_mul_f32_e32 v253, v253, v26
	v_fma_f32 v254, v25, v254, v115
	v_mul_f32_e32 v253, v253, v25
	v_fma_f32 v254, v24, v254, v114
	v_mul_f32_e32 v253, v253, v24
	v_fma_f32 v254, v23, v254, v113
	v_mul_f32_e32 v253, v253, v23
	v_fma_f32 v254, v22, v254, v112
	v_mul_f32_e32 v253, v253, v22
	v_fma_f32 v254, v21, v254, v111
	v_mul_f32_e32 v253, v253, v21
	v_fma_f32 v254, v20, v254, v110
	v_mul_f32_e32 v253, v253, v20
	v_fma_f32 v254, v19, v254, v109
	v_mul_f32_e32 v253, v253, v19
	v_fma_f32 v254, v18, v254, v108
	v_mul_f32_e32 v253, v253, v18
	v_fma_f32 v254, v17, v254, v107
	v_mul_f32_e32 v253, v253, v17
	v_fma_f32 v254, v16, v254, v106
	v_mul_f32_e32 v253, v253, v16
	v_fma_f32 v254, v15, v254, v105
	v_mul_f32_e32 v253, v253, v15
	v_fma_f32 v254, v14, v254, v104
	v_mul_f32_e32 v253, v253, v14
	v_fma_f32 v254, v13, v254, v103
	v_mul_f32_e32 v253, v253, v13
	v_fma_f32 v254, v12, v254, v102
	v_mul_f32_e32 v253, v253, v12
	v_fma_f32 v254, v11, v254, v101
	v_mul_f32_e32 v253, v253, v11
	v_fma_f32 v254, v10, v254, v100
	v_mul_f32_e32 v253, v253, v10
	v_fma_f32 v254, v9, v254, v99
	v_mul_f32_e32 v253, v253, v9
	v_fma_f32 v254, v8, v254, v98
	v_mul_f32_e32 v253, v253, v8
	v_fma_f32 v254, v7, v254, v97
	v_mul_f32_e32 v253, v253, v7
	v_fma_f32 v254, v6, v254, v96
	v_mul_f32_e32 v253, v253, v6
	v_fma_f32 v254, v5, v254, v95
	v_mul_f32_e32 v253, v253, v5
	v_fma_f32 v254, v4, v254, v94
	v_mul_f32_e32 v253, v253, v4
	v_fma_f32 v254, v3, v254, v93
	v_mul_f32_e32 v253, v253, v3
	v_fma_f32 v254, v2, v254, v92
	v_mul_f32_e32 v253, v253, v2
	v_fma_f32 v254, v1, v254, v91
	v_mul_f32_e32 v253, v253, v1
	v_fma_f32 v254, v0, v254, v90
	v_mul_f32_e32 v253, v253, v0
	v_mov_b32_e32 v138, v253
	v_mov_b32_e32 v139, v253
	s_nop 1
	v_permlane16_swap_b32_e32 v138, v139
	v_mov_b32_e32 v140, v138
	v_mov_b32_e32 v141, v139
	s_nop 1
	v_permlane32_swap_b32_e32 v138, v140
	v_permlane32_swap_b32_e32 v139, v141
	v_mov_b32_e32 v198, v254
	v_mov_b32_e32 v199, v254
	s_nop 1
	v_permlane16_swap_b32_e32 v198, v199
	v_mov_b32_e32 v200, v198
	v_mov_b32_e32 v201, v199
	s_nop 1
	v_permlane32_swap_b32_e32 v198, v200
	v_permlane32_swap_b32_e32 v199, v201
	v_mov_b32_e32 v202, 0
	v_fma_f32 v151, v141, v202, v201
	v_fma_f32 v150, v140, v151, v200
	v_fma_f32 v136, v139, v150, v199
	v_fma_f32 v254, v138, v136, v198
	v_mul_f32_e32 v253, v138, v139
	v_mul_f32_e32 v253, v253, v140
	v_mul_f32_e32 v200, v253, v141
	v_mov_b32_e32 v201, v254
	s_add_u32 s0, s71, 264
	s_lshl_b32 s0, s0, 12
	s_lshl_b32 s1, s56, 3
	s_add_u32 s0, s0, s1
	s_add_u32 s4, s18, s0
	s_addc_u32 s5, s19, 0
	global_store_dwordx2 v250, v[200:201], s[4:5]
	s_add_u32 s69, s69, 1
	s_cmp_lt_u32 s69, s70
	s_cbranch_scc1 .Lmy_lrua_tile
	s_waitcnt lgkmcnt(0)
	s_barrier

; __device__ __forceinline__ float bf2f(u16 h) { return __uint_as_float(((unsigned)h) << 16); }
; __device__ __forceinline__ void lru_tile(const Params& P, int chunk, int head, int pass, char* smem_raw) {
;     ...
;       for (int s = 0; s < 2; ++s) {
;         const bf16x8 af = *reinterpret_cast<const bf16x8*>(&sm_uc[(sb * 64 + wid * 16 + (lane & 15)) * LDSS + s * 32 + (lane >> 4) * 8]);
; #pragma unroll
;         for (int t = 0; t < 8; ++t) {
;           const bf16x8 bfr = *reinterpret_cast<const bf16x8*>(&sm_w[(t * 16 + (lane & 15)) * LDSS + s * 32 + (lane >> 4) * 8]);
;           acc[t] = __builtin_amdgcn_mfma_f32_16x16x32_bf16(af, bfr, acc[t], 0, 0, 0);
;         }
;       }
; #pragma unroll
;       for (int tc = 0; tc < 4; ++tc)
; #pragma unroll
;         for (int reg = 0; reg < 4; ++reg) {
;           const int tl = wid * 16 + (lane >> 4) * 4 + reg;
;           const int c = 16 * tc + (lane & 15);
;           const float r = __builtin_amdgcn_rcpf(1.f + __builtin_amdgcn_exp2f(acc[tc][reg] + ba[tc]));
;           const float ii = __builtin_amdgcn_rcpf(1.f + __builtin_amdgcn_exp2f(acc[tc + 4][reg] + bi[tc]));
;           const float la = -c8[tc] * r;
;           const float a = __builtin_amdgcn_exp2f(la);
;           const float ucv = bf2f(sm_uc[(sb * 64 + tl) * LDSS + c]);
;           const float bt = __builtin_amdgcn_sqrtf(fmaxf(1.f - a * a, 0.f)) * (ii * ucv);
.Lmy_lrub_lb1_done:
	ds_read_b128 v[76:79], v131 offset:0
	ds_read_b128 v[80:83], v133 offset:0
	ds_read_b128 v[122:125], v131 offset:512
	ds_read_b128 v[126:129], v133 offset:512
	s_waitcnt lgkmcnt(3)
	v_mfma_f32_16x16x32_bf16 v[0:3], v[76:79], v[238:241], 0
	v_mfma_f32_16x16x32_bf16 v[90:93], v[76:79], v[246:249], 0
	ds_read_b128 v[76:79], v131 offset:1024
	s_waitcnt lgkmcnt(3)
	v_mfma_f32_16x16x32_bf16 v[0:3], v[80:83], v[242:245], v[0:3]
	v_mfma_f32_16x16x32_bf16 v[90:93], v[80:83], v[194:197], v[90:93]
	ds_read_b128 v[80:83], v133 offset:1024
	s_waitcnt lgkmcnt(3)
	v_mfma_f32_16x16x32_bf16 v[4:7], v[122:125], v[238:241], 0
	v_mfma_f32_16x16x32_bf16 v[94:97], v[122:125], v[246:249], 0
	ds_read_b128 v[122:125], v131 offset:1536
	s_waitcnt lgkmcnt(3)
	v_mfma_f32_16x16x32_bf16 v[4:7], v[126:129], v[242:245], v[4:7]
	v_mfma_f32_16x16x32_bf16 v[94:97], v[126:129], v[194:197], v[94:97]
	ds_read_b128 v[126:129], v133 offset:1536
	s_waitcnt lgkmcnt(3)
	v_mfma_f32_16x16x32_bf16 v[8:11], v[76:79], v[238:241], 0
	v_mfma_f32_16x16x32_bf16 v[98:101], v[76:79], v[246:249], 0
	ds_read_b128 v[76:79], v131 offset:2048
	s_waitcnt lgkmcnt(3)
	v_mfma_f32_16x16x32_bf16 v[8:11], v[80:83], v[242:245], v[8:11]
	v_mfma_f32_16x16x32_bf16 v[98:101], v[80:83], v[194:197], v[98:101]
	ds_read_b128 v[80:83], v133 offset:2048
	s_waitcnt lgkmcnt(3)
	v_mfma_f32_16x16x32_bf16 v[12:15], v[122:125], v[238:241], 0
	v_mfma_f32_16x16x32_bf16 v[102:105], v[122:125], v[246:249], 0
	ds_read_b128 v[122:125], v131 offset:2560
	s_waitcnt lgkmcnt(3)
	v_mfma_f32_16x16x32_bf16 v[12:15], v[126:129], v[242:245], v[12:15]
	v_mfma_f32_16x16x32_bf16 v[102:105], v[126:129], v[194:197], v[102:105]
	ds_read_b128 v[126:129], v133 offset:2560
	s_waitcnt lgkmcnt(3)
	v_mfma_f32_16x16x32_bf16 v[16:19], v[76:79], v[238:241], 0
	v_mfma_f32_16x16x32_bf16 v[106:109], v[76:79], v[246:249], 0
	ds_read_b128 v[76:79], v131 offset:3072
	s_waitcnt lgkmcnt(3)
	v_mfma_f32_16x16x32_bf16 v[16:19], v[80:83], v[242:245], v[16:19]
	v_mfma_f32_16x16x32_bf16 v[106:109], v[80:83], v[194:197], v[106:109]
	ds_read_b128 v[80:83], v133 offset:3072
	s_waitcnt lgkmcnt(3)
	v_mfma_f32_16x16x32_bf16 v[20:23], v[122:125], v[238:241], 0
	v_mfma_f32_16x16x32_bf16 v[110:113], v[122:125], v[246:249], 0
	ds_read_b128 v[122:125], v131 offset:3584
	s_waitcnt lgkmcnt(3)
	v_mfma_f32_16x16x32_bf16 v[20:23], v[126:129], v[242:245], v[20:23]
	v_mfma_f32_16x16x32_bf16 v[110:113], v[126:129], v[194:197], v[110:113]
	ds_read_b128 v[126:129], v133 offset:3584
	s_waitcnt lgkmcnt(3)
	v_mfma_f32_16x16x32_bf16 v[24:27], v[76:79], v[238:241], 0
	v_mfma_f32_16x16x32_bf16 v[114:117], v[76:79], v[246:249], 0
	s_waitcnt lgkmcnt(2)
	v_mfma_f32_16x16x32_bf16 v[24:27], v[80:83], v[242:245], v[24:27]
	v_mfma_f32_16x16x32_bf16 v[114:117], v[80:83], v[194:197], v[114:117]
	s_waitcnt lgkmcnt(1)
	v_mfma_f32_16x16x32_bf16 v[28:31], v[122:125], v[238:241], 0
	v_mfma_f32_16x16x32_bf16 v[118:121], v[122:125], v[246:249], 0
	s_waitcnt lgkmcnt(0)
	v_mfma_f32_16x16x32_bf16 v[28:31], v[126:129], v[242:245], v[28:31]
	v_mfma_f32_16x16x32_bf16 v[118:121], v[126:129], v[194:197], v[118:121]
	s_lshl_b32 s0, s56, 8
	s_add_u32 s0, s0, 0x20000
	s_add_u32 s4, s20, s0
	s_addc_u32 s5, s21, 0
	global_load_dwordx4 v[238:241], v251, s[4:5]
	global_load_dwordx4 v[242:245], v251, s[4:5] offset:64
	s_add_u32 s4, s4, 0x2000
	s_addc_u32 s5, s5, 0
	global_load_dwordx4 v[246:249], v251, s[4:5]
	global_load_dwordx4 v[194:197], v251, s[4:5] offset:64
	v_bfe_u32 v255, v152, 6, 2
	v_and_b32_e32 v253, 15, v152
	v_lshl_add_u32 v255, v255, 4, v253
	v_add_u32_e32 v255, s56, v255
	v_lshlrev_b32_e32 v255, 2, v255
	s_add_u32 s0, s28, 0x800
	s_addc_u32 s1, s29, 0
	global_load_dword v68, v255, s[0:1]
	s_add_u32 s0, s30, 0x800
	s_addc_u32 s1, s31, 0
	global_load_dword v70, v255, s[0:1]
	s_add_u32 s0, s36, 0x800
	s_addc_u32 s1, s37, 0
	global_load_dword v73, v255, s[0:1]
	v_mul_f32_e32 v75, 0xbfb8aa3b, v75
	v_mul_f32_e32 v84, 0xbfb8aa3b, v84
	v_sub_f32_e32 v138, 0, v85
	v_mul_f32_e32 v139, 0x3fb8aa3b, v138
	v_exp_f32_e32 v139, v139
	s_nop 0
	v_mul_f32_e32 v140, 0xbe800000, v139
	v_add_f32_e32 v140, 0x3eaaaaab, v140
	v_fma_f32 v140, -v139, v140, 0.5
	v_fma_f32 v140, -v139, v140, 1.0
	v_mul_f32_e32 v140, v139, v140
	v_add_f32_e32 v141, 1.0, v139
	v_log_f32_e32 v141, v141
	v_mov_b32_e32 v255, 0x3cf5c28f
	v_mul_f32_e32 v141, 0x3f317218, v141
	v_cmp_gt_f32_e32 vcc, v255, v139
	s_nop 1
	v_cndmask_b32_e32 v140, v141, v140, vcc
	v_mov_b32_e32 v255, 0x41a00000
	v_cmp_lt_f32_e32 vcc, v255, v138
	s_nop 1
	v_cndmask_b32_e32 v140, v140, v138, vcc
	v_mul_f32_e32 v85, 0xc138aa3b, v140
	s_nop 7
	v_add_f32_e32 v0, v0, v75
	v_add_f32_e32 v1, v1, v75
	v_add_f32_e32 v2, v2, v75
	v_add_f32_e32 v3, v3, v75
	v_add_f32_e32 v90, v90, v84
	v_add_f32_e32 v91, v91, v84
	v_add_f32_e32 v92, v92, v84
	v_add_f32_e32 v93, v93, v84
	v_exp_f32_e32 v0, v0
	v_exp_f32_e32 v1, v1
	v_exp_f32_e32 v2, v2
	v_exp_f32_e32 v3, v3
	v_exp_f32_e32 v90, v90
	v_exp_f32_e32 v91, v91
	v_exp_f32_e32 v92, v92
	v_exp_f32_e32 v93, v93
	v_add_f32_e32 v0, 1.0, v0
	v_add_f32_e32 v1, 1.0, v1
	v_add_f32_e32 v2, 1.0, v2
	v_add_f32_e32 v3, 1.0, v3
	v_add_f32_e32 v90, 1.0, v90
	v_add_f32_e32 v91, 1.0, v91
	v_add_f32_e32 v92, 1.0, v92
	v_add_f32_e32 v93, 1.0, v93
	v_rcp_f32_e32 v0, v0
	v_rcp_f32_e32 v1, v1
	v_rcp_f32_e32 v2, v2
	v_rcp_f32_e32 v3, v3
	v_rcp_f32_e32 v90, v90
	v_rcp_f32_e32 v91, v91
	v_rcp_f32_e32 v92, v92
	v_rcp_f32_e32 v93, v93
	v_mul_f32_e32 v0, v85, v0
	v_mul_f32_e32 v1, v85, v1
	v_mul_f32_e32 v2, v85, v2
	v_mul_f32_e32 v3, v85, v3
	v_mul_f32_e32 v90, v90, v162
	v_mul_f32_e32 v91, v91, v163
	v_mul_f32_e32 v92, v92, v164
	v_mul_f32_e32 v93, v93, v165
; __device__ __forceinline__ float bf2f(u16 h) { return __uint_as_float(((unsigned)h) << 16); }
; __device__ __forceinline__ void lru_tile(const Params& P, int chunk, int head, int pass, char* smem_raw) {
;     ...
; #pragma unroll
;       for (int tc = 0; tc < 4; ++tc)
; #pragma unroll
;         for (int reg = 0; reg < 4; ++reg) {
;           const int tl = wid * 16 + (lane >> 4) * 4 + reg;
;           const int c = 16 * tc + (lane & 15);
;           const float r = __builtin_amdgcn_rcpf(1.f + __builtin_amdgcn_exp2f(acc[tc][reg] + ba[tc]));
;           const float ii = __builtin_amdgcn_rcpf(1.f + __builtin_amdgcn_exp2f(acc[tc + 4][reg] + bi[tc]));
;           const float la = -c8[tc] * r;
;           const float a = __builtin_amdgcn_exp2f(la);
;           const float ucv = bf2f(sm_uc[(sb * 64 + tl) * LDSS + c]);
;           const float bt = __builtin_amdgcn_sqrtf(fmaxf(1.f - a * a, 0.f)) * (ii * ucv);
	v_exp_f32_e32 v0, v0
	v_exp_f32_e32 v1, v1
	v_exp_f32_e32 v2, v2
	v_exp_f32_e32 v3, v3
	s_nop 0
	v_fma_f32 v138, -v0, v0, 1.0
	v_fma_f32 v139, -v1, v1, 1.0
	v_fma_f32 v140, -v2, v2, 1.0
	v_fma_f32 v141, -v3, v3, 1.0
	v_max_f32_e32 v138, 0, v138
	v_max_f32_e32 v139, 0, v139
	v_max_f32_e32 v140, 0, v140
	v_max_f32_e32 v141, 0, v141
	v_sqrt_f32_e32 v138, v138
	v_sqrt_f32_e32 v139, v139
	v_sqrt_f32_e32 v140, v140
	v_sqrt_f32_e32 v141, v141
	s_nop 0
	v_mul_f32_e32 v90, v138, v90
	v_mul_f32_e32 v91, v139, v91
	v_mul_f32_e32 v92, v140, v92
	v_mul_f32_e32 v93, v141, v93
	v_add_f32_e32 v4, v4, v75
	v_add_f32_e32 v5, v5, v75
	v_add_f32_e32 v6, v6, v75
	v_add_f32_e32 v7, v7, v75
	v_add_f32_e32 v94, v94, v84
	v_add_f32_e32 v95, v95, v84
	v_add_f32_e32 v96, v96, v84
	v_add_f32_e32 v97, v97, v84
	v_exp_f32_e32 v4, v4
	v_exp_f32_e32 v5, v5
	v_exp_f32_e32 v6, v6
	v_exp_f32_e32 v7, v7
	v_exp_f32_e32 v94, v94
	v_exp_f32_e32 v95, v95
	v_exp_f32_e32 v96, v96
	v_exp_f32_e32 v97, v97
	v_add_f32_e32 v4, 1.0, v4
	v_add_f32_e32 v5, 1.0, v5
	v_add_f32_e32 v6, 1.0, v6
	v_add_f32_e32 v7, 1.0, v7
	v_add_f32_e32 v94, 1.0, v94
	v_add_f32_e32 v95, 1.0, v95
	v_add_f32_e32 v96, 1.0, v96
	v_add_f32_e32 v97, 1.0, v97
	v_rcp_f32_e32 v4, v4
	v_rcp_f32_e32 v5, v5
	v_rcp_f32_e32 v6, v6
	v_rcp_f32_e32 v7, v7
	v_rcp_f32_e32 v94, v94
	v_rcp_f32_e32 v95, v95
	v_rcp_f32_e32 v96, v96
	v_rcp_f32_e32 v97, v97
	v_mul_f32_e32 v4, v85, v4
	v_mul_f32_e32 v5, v85, v5
	v_mul_f32_e32 v6, v85, v6
	v_mul_f32_e32 v7, v85, v7
	v_mul_f32_e32 v94, v94, v166
	v_mul_f32_e32 v95, v95, v167
	v_mul_f32_e32 v96, v96, v168
	v_mul_f32_e32 v97, v97, v169
	v_exp_f32_e32 v4, v4
	v_exp_f32_e32 v5, v5
	v_exp_f32_e32 v6, v6
	v_exp_f32_e32 v7, v7
	s_nop 0
	v_fma_f32 v138, -v4, v4, 1.0
	v_fma_f32 v139, -v5, v5, 1.0
	v_fma_f32 v140, -v6, v6, 1.0
	v_fma_f32 v141, -v7, v7, 1.0
	v_max_f32_e32 v138, 0, v138
	v_max_f32_e32 v139, 0, v139
	v_max_f32_e32 v140, 0, v140
	v_max_f32_e32 v141, 0, v141
	v_sqrt_f32_e32 v138, v138
	v_sqrt_f32_e32 v139, v139
	v_sqrt_f32_e32 v140, v140
	v_sqrt_f32_e32 v141, v141
	s_nop 0
	v_mul_f32_e32 v94, v138, v94
	v_mul_f32_e32 v95, v139, v95
	v_mul_f32_e32 v96, v140, v96
	v_mul_f32_e32 v97, v141, v97
	v_add_f32_e32 v8, v8, v75
	v_add_f32_e32 v9, v9, v75
	v_add_f32_e32 v10, v10, v75
	v_add_f32_e32 v11, v11, v75
	v_add_f32_e32 v98, v98, v84
	v_add_f32_e32 v99, v99, v84
	v_add_f32_e32 v100, v100, v84
	v_add_f32_e32 v101, v101, v84
	v_exp_f32_e32 v8, v8
	v_exp_f32_e32 v9, v9
	v_exp_f32_e32 v10, v10
	v_exp_f32_e32 v11, v11
	v_exp_f32_e32 v98, v98
	v_exp_f32_e32 v99, v99
	v_exp_f32_e32 v100, v100
	v_exp_f32_e32 v101, v101
	v_add_f32_e32 v8, 1.0, v8
	v_add_f32_e32 v9, 1.0, v9
	v_add_f32_e32 v10, 1.0, v10
	v_add_f32_e32 v11, 1.0, v11
	v_add_f32_e32 v98, 1.0, v98
	v_add_f32_e32 v99, 1.0, v99
	v_add_f32_e32 v100, 1.0, v100
	v_add_f32_e32 v101, 1.0, v101
	v_rcp_f32_e32 v8, v8
	v_rcp_f32_e32 v9, v9
	v_rcp_f32_e32 v10, v10
	v_rcp_f32_e32 v11, v11
	v_rcp_f32_e32 v98, v98
	v_rcp_f32_e32 v99, v99
	v_rcp_f32_e32 v100, v100
	v_rcp_f32_e32 v101, v101
	v_mul_f32_e32 v8, v85, v8
	v_mul_f32_e32 v9, v85, v9
	v_mul_f32_e32 v10, v85, v10
	v_mul_f32_e32 v11, v85, v11
	v_mul_f32_e32 v98, v98, v170
	v_mul_f32_e32 v99, v99, v171
	v_mul_f32_e32 v100, v100, v172
	v_mul_f32_e32 v101, v101, v173
	v_exp_f32_e32 v8, v8
	v_exp_f32_e32 v9, v9
	v_exp_f32_e32 v10, v10
	v_exp_f32_e32 v11, v11
	s_nop 0
	v_fma_f32 v138, -v8, v8, 1.0
	v_fma_f32 v139, -v9, v9, 1.0
	v_fma_f32 v140, -v10, v10, 1.0
	v_fma_f32 v141, -v11, v11, 1.0
	v_max_f32_e32 v138, 0, v138
	v_max_f32_e32 v139, 0, v139
	v_max_f32_e32 v140, 0, v140
	v_max_f32_e32 v141, 0, v141
	v_sqrt_f32_e32 v138, v138
	v_sqrt_f32_e32 v139, v139
	v_sqrt_f32_e32 v140, v140
	v_sqrt_f32_e32 v141, v141
	s_nop 0
	v_mul_f32_e32 v98, v138, v98
	v_mul_f32_e32 v99, v139, v99
	v_mul_f32_e32 v100, v140, v100
	v_mul_f32_e32 v101, v141, v101
	v_add_f32_e32 v12, v12, v75
	v_add_f32_e32 v13, v13, v75
	v_add_f32_e32 v14, v14, v75
	v_add_f32_e32 v15, v15, v75
	v_add_f32_e32 v102, v102, v84
	v_add_f32_e32 v103, v103, v84
	v_add_f32_e32 v104, v104, v84
	v_add_f32_e32 v105, v105, v84
	v_exp_f32_e32 v12, v12
	v_exp_f32_e32 v13, v13
	v_exp_f32_e32 v14, v14
	v_exp_f32_e32 v15, v15
	v_exp_f32_e32 v102, v102
	v_exp_f32_e32 v103, v103
	v_exp_f32_e32 v104, v104
	v_exp_f32_e32 v105, v105
	v_add_f32_e32 v12, 1.0, v12
	v_add_f32_e32 v13, 1.0, v13
	v_add_f32_e32 v14, 1.0, v14
	v_add_f32_e32 v15, 1.0, v15
	v_add_f32_e32 v102, 1.0, v102
	v_add_f32_e32 v103, 1.0, v103
	v_add_f32_e32 v104, 1.0, v104
	v_add_f32_e32 v105, 1.0, v105
	v_rcp_f32_e32 v12, v12
	v_rcp_f32_e32 v13, v13
	v_rcp_f32_e32 v14, v14
	v_rcp_f32_e32 v15, v15
	v_rcp_f32_e32 v102, v102
	v_rcp_f32_e32 v103, v103
	v_rcp_f32_e32 v104, v104
	v_rcp_f32_e32 v105, v105
	v_mul_f32_e32 v12, v85, v12
	v_mul_f32_e32 v13, v85, v13
	v_mul_f32_e32 v14, v85, v14
	v_mul_f32_e32 v15, v85, v15
	v_mul_f32_e32 v102, v102, v174
	v_mul_f32_e32 v103, v103, v175
	v_mul_f32_e32 v104, v104, v176
	v_mul_f32_e32 v105, v105, v177
	v_exp_f32_e32 v12, v12
	v_exp_f32_e32 v13, v13
	v_exp_f32_e32 v14, v14
	v_exp_f32_e32 v15, v15
	s_nop 0
	v_fma_f32 v138, -v12, v12, 1.0
	v_fma_f32 v139, -v13, v13, 1.0
	v_fma_f32 v140, -v14, v14, 1.0
	v_fma_f32 v141, -v15, v15, 1.0
	v_max_f32_e32 v138, 0, v138
	v_max_f32_e32 v139, 0, v139
	v_max_f32_e32 v140, 0, v140
	v_max_f32_e32 v141, 0, v141
	v_sqrt_f32_e32 v138, v138
	v_sqrt_f32_e32 v139, v139
	v_sqrt_f32_e32 v140, v140
	v_sqrt_f32_e32 v141, v141
	s_nop 0
	v_mul_f32_e32 v102, v138, v102
	v_mul_f32_e32 v103, v139, v103
	v_mul_f32_e32 v104, v140, v104
	v_mul_f32_e32 v105, v141, v105
	v_add_f32_e32 v16, v16, v75
	v_add_f32_e32 v17, v17, v75
; __device__ __forceinline__ float bf2f(u16 h) { return __uint_as_float(((unsigned)h) << 16); }
; __device__ __forceinline__ void lru_tile(const Params& P, int chunk, int head, int pass, char* smem_raw) {
;     ...
; #pragma unroll
;       for (int tc = 0; tc < 4; ++tc)
; #pragma unroll
;         for (int reg = 0; reg < 4; ++reg) {
;           const int tl = wid * 16 + (lane >> 4) * 4 + reg;
;           const int c = 16 * tc + (lane & 15);
;           const float r = __builtin_amdgcn_rcpf(1.f + __builtin_amdgcn_exp2f(acc[tc][reg] + ba[tc]));
;           const float ii = __builtin_amdgcn_rcpf(1.f + __builtin_amdgcn_exp2f(acc[tc + 4][reg] + bi[tc]));
;           const float la = -c8[tc] * r;
;           const float a = __builtin_amdgcn_exp2f(la);
;           const float ucv = bf2f(sm_uc[(sb * 64 + tl) * LDSS + c]);
;           const float bt = __builtin_amdgcn_sqrtf(fmaxf(1.f - a * a, 0.f)) * (ii * ucv);
	v_add_f32_e32 v18, v18, v75
	v_add_f32_e32 v19, v19, v75
	v_add_f32_e32 v106, v106, v84
	v_add_f32_e32 v107, v107, v84
	v_add_f32_e32 v108, v108, v84
	v_add_f32_e32 v109, v109, v84
	v_exp_f32_e32 v16, v16
	v_exp_f32_e32 v17, v17
	v_exp_f32_e32 v18, v18
	v_exp_f32_e32 v19, v19
	v_exp_f32_e32 v106, v106
	v_exp_f32_e32 v107, v107
	v_exp_f32_e32 v108, v108
	v_exp_f32_e32 v109, v109
	v_add_f32_e32 v16, 1.0, v16
	v_add_f32_e32 v17, 1.0, v17
	v_add_f32_e32 v18, 1.0, v18
	v_add_f32_e32 v19, 1.0, v19
	v_add_f32_e32 v106, 1.0, v106
	v_add_f32_e32 v107, 1.0, v107
	v_add_f32_e32 v108, 1.0, v108
	v_add_f32_e32 v109, 1.0, v109
	v_rcp_f32_e32 v16, v16
	v_rcp_f32_e32 v17, v17
	v_rcp_f32_e32 v18, v18
	v_rcp_f32_e32 v19, v19
	v_rcp_f32_e32 v106, v106
	v_rcp_f32_e32 v107, v107
	v_rcp_f32_e32 v108, v108
	v_rcp_f32_e32 v109, v109
	v_mul_f32_e32 v16, v85, v16
	v_mul_f32_e32 v17, v85, v17
	v_mul_f32_e32 v18, v85, v18
	v_mul_f32_e32 v19, v85, v19
	v_mul_f32_e32 v106, v106, v178
	v_mul_f32_e32 v107, v107, v179
	v_mul_f32_e32 v108, v108, v180
	v_mul_f32_e32 v109, v109, v181
	v_exp_f32_e32 v16, v16
	v_exp_f32_e32 v17, v17
	v_exp_f32_e32 v18, v18
	v_exp_f32_e32 v19, v19
	s_nop 0
	v_fma_f32 v138, -v16, v16, 1.0
	v_fma_f32 v139, -v17, v17, 1.0
	v_fma_f32 v140, -v18, v18, 1.0
	v_fma_f32 v141, -v19, v19, 1.0
	v_max_f32_e32 v138, 0, v138
	v_max_f32_e32 v139, 0, v139
	v_max_f32_e32 v140, 0, v140
	v_max_f32_e32 v141, 0, v141
	v_sqrt_f32_e32 v138, v138
	v_sqrt_f32_e32 v139, v139
	v_sqrt_f32_e32 v140, v140
	v_sqrt_f32_e32 v141, v141
	s_nop 0
	v_mul_f32_e32 v106, v138, v106
	v_mul_f32_e32 v107, v139, v107
	v_mul_f32_e32 v108, v140, v108
	v_mul_f32_e32 v109, v141, v109
	v_add_f32_e32 v20, v20, v75
	v_add_f32_e32 v21, v21, v75
	v_add_f32_e32 v22, v22, v75
	v_add_f32_e32 v23, v23, v75
	v_add_f32_e32 v110, v110, v84
	v_add_f32_e32 v111, v111, v84
	v_add_f32_e32 v112, v112, v84
	v_add_f32_e32 v113, v113, v84
	v_exp_f32_e32 v20, v20
	v_exp_f32_e32 v21, v21
	v_exp_f32_e32 v22, v22
	v_exp_f32_e32 v23, v23
	v_exp_f32_e32 v110, v110
	v_exp_f32_e32 v111, v111
	v_exp_f32_e32 v112, v112
	v_exp_f32_e32 v113, v113
	v_add_f32_e32 v20, 1.0, v20
	v_add_f32_e32 v21, 1.0, v21
	v_add_f32_e32 v22, 1.0, v22
	v_add_f32_e32 v23, 1.0, v23
	v_add_f32_e32 v110, 1.0, v110
	v_add_f32_e32 v111, 1.0, v111
	v_add_f32_e32 v112, 1.0, v112
	v_add_f32_e32 v113, 1.0, v113
	v_rcp_f32_e32 v20, v20
	v_rcp_f32_e32 v21, v21
	v_rcp_f32_e32 v22, v22
	v_rcp_f32_e32 v23, v23
	v_rcp_f32_e32 v110, v110
	v_rcp_f32_e32 v111, v111
	v_rcp_f32_e32 v112, v112
	v_rcp_f32_e32 v113, v113
	v_mul_f32_e32 v20, v85, v20
	v_mul_f32_e32 v21, v85, v21
	v_mul_f32_e32 v22, v85, v22
	v_mul_f32_e32 v23, v85, v23
	v_mul_f32_e32 v110, v110, v182
	v_mul_f32_e32 v111, v111, v183
	v_mul_f32_e32 v112, v112, v184
	v_mul_f32_e32 v113, v113, v185
	v_exp_f32_e32 v20, v20
	v_exp_f32_e32 v21, v21
	v_exp_f32_e32 v22, v22
	v_exp_f32_e32 v23, v23
	s_nop 0
	v_fma_f32 v138, -v20, v20, 1.0
	v_fma_f32 v139, -v21, v21, 1.0
	v_fma_f32 v140, -v22, v22, 1.0
	v_fma_f32 v141, -v23, v23, 1.0
	v_max_f32_e32 v138, 0, v138
	v_max_f32_e32 v139, 0, v139
	v_max_f32_e32 v140, 0, v140
	v_max_f32_e32 v141, 0, v141
	v_sqrt_f32_e32 v138, v138
	v_sqrt_f32_e32 v139, v139
	v_sqrt_f32_e32 v140, v140
	v_sqrt_f32_e32 v141, v141
	s_nop 0
	v_mul_f32_e32 v110, v138, v110
	v_mul_f32_e32 v111, v139, v111
	v_mul_f32_e32 v112, v140, v112
	v_mul_f32_e32 v113, v141, v113
	v_add_f32_e32 v24, v24, v75
	v_add_f32_e32 v25, v25, v75
	v_add_f32_e32 v26, v26, v75
	v_add_f32_e32 v27, v27, v75
	v_add_f32_e32 v114, v114, v84
	v_add_f32_e32 v115, v115, v84
	v_add_f32_e32 v116, v116, v84
	v_add_f32_e32 v117, v117, v84
	v_exp_f32_e32 v24, v24
	v_exp_f32_e32 v25, v25
	v_exp_f32_e32 v26, v26
	v_exp_f32_e32 v27, v27
	v_exp_f32_e32 v114, v114
	v_exp_f32_e32 v115, v115
	v_exp_f32_e32 v116, v116
	v_exp_f32_e32 v117, v117
	v_add_f32_e32 v24, 1.0, v24
	v_add_f32_e32 v25, 1.0, v25
	v_add_f32_e32 v26, 1.0, v26
	v_add_f32_e32 v27, 1.0, v27
	v_add_f32_e32 v114, 1.0, v114
	v_add_f32_e32 v115, 1.0, v115
	v_add_f32_e32 v116, 1.0, v116
	v_add_f32_e32 v117, 1.0, v117
	v_rcp_f32_e32 v24, v24
	v_rcp_f32_e32 v25, v25
	v_rcp_f32_e32 v26, v26
	v_rcp_f32_e32 v27, v27
	v_rcp_f32_e32 v114, v114
	v_rcp_f32_e32 v115, v115
	v_rcp_f32_e32 v116, v116
	v_rcp_f32_e32 v117, v117
	v_mul_f32_e32 v24, v85, v24
	v_mul_f32_e32 v25, v85, v25
	v_mul_f32_e32 v26, v85, v26
	v_mul_f32_e32 v27, v85, v27
	v_mul_f32_e32 v114, v114, v186
	v_mul_f32_e32 v115, v115, v187
	v_mul_f32_e32 v116, v116, v188
	v_mul_f32_e32 v117, v117, v189
	v_exp_f32_e32 v24, v24
	v_exp_f32_e32 v25, v25
	v_exp_f32_e32 v26, v26
	v_exp_f32_e32 v27, v27
	s_nop 0
	v_fma_f32 v138, -v24, v24, 1.0
	v_fma_f32 v139, -v25, v25, 1.0
	v_fma_f32 v140, -v26, v26, 1.0
	v_fma_f32 v141, -v27, v27, 1.0
	v_max_f32_e32 v138, 0, v138
	v_max_f32_e32 v139, 0, v139
	v_max_f32_e32 v140, 0, v140
	v_max_f32_e32 v141, 0, v141
	v_sqrt_f32_e32 v138, v138
	v_sqrt_f32_e32 v139, v139
	v_sqrt_f32_e32 v140, v140
	v_sqrt_f32_e32 v141, v141
	s_nop 0
	v_mul_f32_e32 v114, v138, v114
	v_mul_f32_e32 v115, v139, v115
	v_mul_f32_e32 v116, v140, v116
	v_mul_f32_e32 v117, v141, v117
	v_add_f32_e32 v28, v28, v75
	v_add_f32_e32 v29, v29, v75
	v_add_f32_e32 v30, v30, v75
	v_add_f32_e32 v31, v31, v75
	v_add_f32_e32 v118, v118, v84
	v_add_f32_e32 v119, v119, v84
	v_add_f32_e32 v120, v120, v84
	v_add_f32_e32 v121, v121, v84
	v_exp_f32_e32 v28, v28
	v_exp_f32_e32 v29, v29
	v_exp_f32_e32 v30, v30
	v_exp_f32_e32 v31, v31
	v_exp_f32_e32 v118, v118
	v_exp_f32_e32 v119, v119
	v_exp_f32_e32 v120, v120
	v_exp_f32_e32 v121, v121
	v_add_f32_e32 v28, 1.0, v28
	v_add_f32_e32 v29, 1.0, v29
	v_add_f32_e32 v30, 1.0, v30
	v_add_f32_e32 v31, 1.0, v31
; __device__ __forceinline__ float bf2f(u16 h) { return __uint_as_float(((unsigned)h) << 16); }
; __device__ __forceinline__ void lru_tile(const Params& P, int chunk, int head, int pass, char* smem_raw) {
;     ...
;         float Pp = 1.f, H = 0.f;
; #pragma unroll 4
;         for (int i = 0; i < 16; ++i) {
;           const int tl = (d == 0) ? (q * 16 + i) : (q * 16 + 15 - i);
;           const float a = sm_a[tl * 64 + ch], b = sm_b[tl * 64 + ch];
;           H = a * H + b; Pp *= a;
;         }
;         sm_ph[pos * 64 + ch] = make_float2(Pp, H);
;       }
;       __syncthreads();
;       const float2 p0 = sm_ph[ch], p1 = sm_ph[64 + ch], p2 = sm_ph[128 + ch], p3 = sm_ph[192 + ch];
;       if (pass == 2) {
;         float hin = cB;
;         if (pos > 0) hin = p0.x * hin + p0.y;
;         if (pos > 1) hin = p1.x * hin + p1.y;
;         if (pos > 2) hin = p2.x * hin + p2.y;
;         float h = hin;
;         float hfp[16], gp[16];
;         if (d == 1) {
; #pragma unroll
;           for (int i = 0; i < 16; ++i) {
;             const long rowp = row0 + sb * 64 + q * 16 + 15 - i;
;             hfp[i] = hfbuf[rowp * 512 + gch];
;             gp[i] = bf2f(P.zq[rowp * 1536 + 512 + gch]);
;           }
;         }
; #pragma unroll
;         for (int i = 0; i < 16; ++i) {
;           const int tl = (d == 0) ? (q * 16 + i) : (q * 16 + 15 - i);
;           const float a = sm_a[tl * 64 + ch], b = sm_b[tl * 64 + ch];
;           h = a * h + b;
;           const long row = row0 + sb * 64 + tl;
;           if (d == 0) {
;             hfw[row * 512 + gch] = h;
	v_add_f32_e32 v118, 1.0, v118
	v_add_f32_e32 v119, 1.0, v119
	v_add_f32_e32 v120, 1.0, v120
	v_add_f32_e32 v121, 1.0, v121
	v_rcp_f32_e32 v28, v28
	v_rcp_f32_e32 v29, v29
	v_rcp_f32_e32 v30, v30
	v_rcp_f32_e32 v31, v31
	v_rcp_f32_e32 v118, v118
	v_rcp_f32_e32 v119, v119
	v_rcp_f32_e32 v120, v120
	v_rcp_f32_e32 v121, v121
	v_mul_f32_e32 v28, v85, v28
	v_mul_f32_e32 v29, v85, v29
	v_mul_f32_e32 v30, v85, v30
	v_mul_f32_e32 v31, v85, v31
	v_mul_f32_e32 v118, v118, v190
	v_mul_f32_e32 v119, v119, v191
	v_mul_f32_e32 v120, v120, v192
	v_mul_f32_e32 v121, v121, v193
	v_exp_f32_e32 v28, v28
	v_exp_f32_e32 v29, v29
	v_exp_f32_e32 v30, v30
	v_exp_f32_e32 v31, v31
	s_nop 0
	v_fma_f32 v138, -v28, v28, 1.0
	v_fma_f32 v139, -v29, v29, 1.0
	v_fma_f32 v140, -v30, v30, 1.0
	v_fma_f32 v141, -v31, v31, 1.0
	v_max_f32_e32 v138, 0, v138
	v_max_f32_e32 v139, 0, v139
	v_max_f32_e32 v140, 0, v140
	v_max_f32_e32 v141, 0, v141
	v_sqrt_f32_e32 v138, v138
	v_sqrt_f32_e32 v139, v139
	v_sqrt_f32_e32 v140, v140
	v_sqrt_f32_e32 v141, v141
	s_nop 0
	v_mul_f32_e32 v118, v138, v118
	v_mul_f32_e32 v119, v139, v119
	v_mul_f32_e32 v120, v140, v120
	v_mul_f32_e32 v121, v141, v121
	v_mov_b32_e32 v253, v0
	v_mov_b32_e32 v254, v90
	v_fma_f32 v254, v1, v254, v91
	v_mul_f32_e32 v253, v253, v1
	v_fma_f32 v254, v2, v254, v92
	v_mul_f32_e32 v253, v253, v2
	v_fma_f32 v254, v3, v254, v93
	v_mul_f32_e32 v253, v253, v3
	v_fma_f32 v254, v4, v254, v94
	v_mul_f32_e32 v253, v253, v4
	v_fma_f32 v254, v5, v254, v95
	v_mul_f32_e32 v253, v253, v5
	v_fma_f32 v254, v6, v254, v96
	v_mul_f32_e32 v253, v253, v6
	v_fma_f32 v254, v7, v254, v97
	v_mul_f32_e32 v253, v253, v7
	v_fma_f32 v254, v8, v254, v98
	v_mul_f32_e32 v253, v253, v8
	v_fma_f32 v254, v9, v254, v99
	v_mul_f32_e32 v253, v253, v9
	v_fma_f32 v254, v10, v254, v100
	v_mul_f32_e32 v253, v253, v10
	v_fma_f32 v254, v11, v254, v101
	v_mul_f32_e32 v253, v253, v11
	v_fma_f32 v254, v12, v254, v102
	v_mul_f32_e32 v253, v253, v12
	v_fma_f32 v254, v13, v254, v103
	v_mul_f32_e32 v253, v253, v13
	v_fma_f32 v254, v14, v254, v104
	v_mul_f32_e32 v253, v253, v14
	v_fma_f32 v254, v15, v254, v105
	v_mul_f32_e32 v253, v253, v15
	v_fma_f32 v254, v16, v254, v106
	v_mul_f32_e32 v253, v253, v16
	v_fma_f32 v254, v17, v254, v107
	v_mul_f32_e32 v253, v253, v17
	v_fma_f32 v254, v18, v254, v108
	v_mul_f32_e32 v253, v253, v18
	v_fma_f32 v254, v19, v254, v109
	v_mul_f32_e32 v253, v253, v19
	v_fma_f32 v254, v20, v254, v110
	v_mul_f32_e32 v253, v253, v20
	v_fma_f32 v254, v21, v254, v111
	v_mul_f32_e32 v253, v253, v21
	v_fma_f32 v254, v22, v254, v112
	v_mul_f32_e32 v253, v253, v22
	v_fma_f32 v254, v23, v254, v113
	v_mul_f32_e32 v253, v253, v23
	v_fma_f32 v254, v24, v254, v114
	v_mul_f32_e32 v253, v253, v24
	v_fma_f32 v254, v25, v254, v115
	v_mul_f32_e32 v253, v253, v25
	v_fma_f32 v254, v26, v254, v116
	v_mul_f32_e32 v253, v253, v26
	v_fma_f32 v254, v27, v254, v117
	v_mul_f32_e32 v253, v253, v27
	v_fma_f32 v254, v28, v254, v118
	v_mul_f32_e32 v253, v253, v28
	v_fma_f32 v254, v29, v254, v119
	v_mul_f32_e32 v253, v253, v29
	v_fma_f32 v254, v30, v254, v120
	v_mul_f32_e32 v253, v253, v30
	v_fma_f32 v254, v31, v254, v121
	v_mul_f32_e32 v253, v253, v31
	v_mov_b32_e32 v138, v253
	v_mov_b32_e32 v139, v253
	s_nop 1
	v_permlane16_swap_b32_e32 v138, v139
	v_mov_b32_e32 v140, v138
	v_mov_b32_e32 v141, v139
	s_nop 1
	v_permlane32_swap_b32_e32 v138, v140
	v_permlane32_swap_b32_e32 v139, v141
	v_mov_b32_e32 v198, v254
	v_mov_b32_e32 v199, v254
	s_nop 1
	v_permlane16_swap_b32_e32 v198, v199
	v_mov_b32_e32 v200, v198
	v_mov_b32_e32 v201, v199
	s_nop 1
	v_permlane32_swap_b32_e32 v198, v200
	v_permlane32_swap_b32_e32 v199, v201
	v_mov_b32_e32 v136, v65
	v_fma_f32 v150, v138, v136, v198
	v_fma_f32 v151, v139, v150, v199
	v_fma_f32 v202, v140, v151, v200
	v_mov_b32_e32 v254, v136
	v_cndmask_b32_e64 v254, v254, v150, s[72:73]
	v_cndmask_b32_e64 v254, v254, v151, s[74:75]
	v_cndmask_b32_e64 v254, v254, v202, s[76:77]
	v_fma_f32 v205, v0, v254, v90
	v_fma_f32 v206, v1, v205, v91
	v_fma_f32 v207, v2, v206, v92
	v_fma_f32 v208, v3, v207, v93
	v_fma_f32 v209, v4, v208, v94
	v_fma_f32 v210, v5, v209, v95
	v_fma_f32 v211, v6, v210, v96
	v_fma_f32 v212, v7, v211, v97
	v_fma_f32 v213, v8, v212, v98
	v_fma_f32 v214, v9, v213, v99
	v_fma_f32 v215, v10, v214, v100
	v_fma_f32 v216, v11, v215, v101
	v_fma_f32 v217, v12, v216, v102
	v_fma_f32 v218, v13, v217, v103
	v_fma_f32 v219, v14, v218, v104
	v_fma_f32 v220, v15, v219, v105
	v_fma_f32 v221, v16, v220, v106
	v_fma_f32 v222, v17, v221, v107
	v_fma_f32 v223, v18, v222, v108
	v_fma_f32 v224, v19, v223, v109
	v_fma_f32 v225, v20, v224, v110
	v_fma_f32 v226, v21, v225, v111
	v_fma_f32 v227, v22, v226, v112
	v_fma_f32 v228, v23, v227, v113
	v_fma_f32 v229, v24, v228, v114
	v_fma_f32 v230, v25, v229, v115
	v_fma_f32 v231, v26, v230, v116
	v_fma_f32 v232, v27, v231, v117
	v_fma_f32 v233, v28, v232, v118
	v_fma_f32 v234, v29, v233, v119
	v_fma_f32 v235, v30, v234, v120
	v_fma_f32 v236, v31, v235, v121
	ds_read_b128 v[76:79], v131 offset:0
	ds_read_b128 v[80:83], v133 offset:0
	ds_read_b128 v[122:125], v131 offset:512
	ds_read_b128 v[126:129], v133 offset:512
	s_waitcnt vmcnt(0)
	s_waitcnt lgkmcnt(3)
	v_mfma_f32_16x16x32_bf16 v[0:3], v[76:79], v[238:241], 0
	v_mfma_f32_16x16x32_bf16 v[90:93], v[76:79], v[246:249], 0
	ds_read_b128 v[76:79], v131 offset:1024
	s_waitcnt lgkmcnt(3)
	v_mfma_f32_16x16x32_bf16 v[0:3], v[80:83], v[242:245], v[0:3]
	v_mfma_f32_16x16x32_bf16 v[90:93], v[80:83], v[194:197], v[90:93]
	ds_read_b128 v[80:83], v133 offset:1024
	s_waitcnt lgkmcnt(3)
	v_mfma_f32_16x16x32_bf16 v[4:7], v[122:125], v[238:241], 0
	v_mfma_f32_16x16x32_bf16 v[94:97], v[122:125], v[246:249], 0
	ds_read_b128 v[122:125], v131 offset:1536
	s_waitcnt lgkmcnt(3)
; __device__ __forceinline__ float bf2f(u16 h) { return __uint_as_float(((unsigned)h) << 16); }
; __device__ __forceinline__ void lru_tile(const Params& P, int chunk, int head, int pass, char* smem_raw) {
;     ...
;       ba[tc] = P.b_a[cidx] * -1.4426950408889634f; bi[tc] = P.b_i[cidx] * -1.4426950408889634f;
;       const float nl = -P.lam[cidx];
;       const float e_ = __expf(nl);
;       const float sp = (nl > 20.f) ? nl
;                      : (e_ < 0.03f ? e_ * (1.f - e_ * (0.5f - e_ * (0.33333334f - 0.25f * e_))) : __logf(1.f + e_));
;       c8[tc] = 8.f * 1.4426950408889634f * sp;
;     }
;     __syncthreads();
;     float cA = 1.f, cB = (pass == 2) ? sm_init[d * 64 + ch] : 0.f;
;     for (int sbi = 0; sbi < 2; ++sbi) {
;       const int sb = (d == 0) ? sbi : 1 - sbi;
;       f32x4 acc[8];
; #pragma unroll
;       for (int t = 0; t < 8; ++t) acc[t] = f32x4{0.f, 0.f, 0.f, 0.f};
; #pragma unroll
;       for (int s = 0; s < 2; ++s) {
;         const bf16x8 af = *reinterpret_cast<const bf16x8*>(&sm_uc[(sb * 64 + wid * 16 + (lane & 15)) * LDSS + s * 32 + (lane >> 4) * 8]);
; #pragma unroll
;         for (int t = 0; t < 8; ++t) {
;           const bf16x8 bfr = *reinterpret_cast<const bf16x8*>(&sm_w[(t * 16 + (lane & 15)) * LDSS + s * 32 + (lane >> 4) * 8]);
;           acc[t] = __builtin_amdgcn_mfma_f32_16x16x32_bf16(af, bfr, acc[t], 0, 0, 0);
;         }
;       }
; #pragma unroll
;       for (int tc = 0; tc < 4; ++tc)
; #pragma unroll
;         for (int reg = 0; reg < 4; ++reg) {
;           const int tl = wid * 16 + (lane >> 4) * 4 + reg;
;           const int c = 16 * tc + (lane & 15);
;           const float r = __builtin_amdgcn_rcpf(1.f + __builtin_amdgcn_exp2f(acc[tc][reg] + ba[tc]));
;           const float ii = __builtin_amdgcn_rcpf(1.f + __builtin_amdgcn_exp2f(acc[tc + 4][reg] + bi[tc]));
;           const float la = -c8[tc] * r;
;           const float a = __builtin_amdgcn_exp2f(la);
;           const float ucv = bf2f(sm_uc[(sb * 64 + tl) * LDSS + c]);
;           const float bt = __builtin_amdgcn_sqrtf(fmaxf(1.f - a * a, 0.f)) * (ii * ucv);
	v_mfma_f32_16x16x32_bf16 v[4:7], v[126:129], v[242:245], v[4:7]
	v_mfma_f32_16x16x32_bf16 v[94:97], v[126:129], v[194:197], v[94:97]
	ds_read_b128 v[126:129], v133 offset:1536
	s_waitcnt lgkmcnt(3)
	v_mfma_f32_16x16x32_bf16 v[8:11], v[76:79], v[238:241], 0
	v_mfma_f32_16x16x32_bf16 v[98:101], v[76:79], v[246:249], 0
	ds_read_b128 v[76:79], v131 offset:2048
	s_waitcnt lgkmcnt(3)
	v_mfma_f32_16x16x32_bf16 v[8:11], v[80:83], v[242:245], v[8:11]
	v_mfma_f32_16x16x32_bf16 v[98:101], v[80:83], v[194:197], v[98:101]
	ds_read_b128 v[80:83], v133 offset:2048
	s_waitcnt lgkmcnt(3)
	v_mfma_f32_16x16x32_bf16 v[12:15], v[122:125], v[238:241], 0
	v_mfma_f32_16x16x32_bf16 v[102:105], v[122:125], v[246:249], 0
	ds_read_b128 v[122:125], v131 offset:2560
	s_waitcnt lgkmcnt(3)
	v_mfma_f32_16x16x32_bf16 v[12:15], v[126:129], v[242:245], v[12:15]
	v_mfma_f32_16x16x32_bf16 v[102:105], v[126:129], v[194:197], v[102:105]
	ds_read_b128 v[126:129], v133 offset:2560
	s_waitcnt lgkmcnt(3)
	v_mfma_f32_16x16x32_bf16 v[16:19], v[76:79], v[238:241], 0
	v_mfma_f32_16x16x32_bf16 v[106:109], v[76:79], v[246:249], 0
	ds_read_b128 v[76:79], v131 offset:3072
	s_waitcnt lgkmcnt(3)
	v_mfma_f32_16x16x32_bf16 v[16:19], v[80:83], v[242:245], v[16:19]
	v_mfma_f32_16x16x32_bf16 v[106:109], v[80:83], v[194:197], v[106:109]
	ds_read_b128 v[80:83], v133 offset:3072
	s_waitcnt lgkmcnt(3)
	v_mfma_f32_16x16x32_bf16 v[20:23], v[122:125], v[238:241], 0
	v_mfma_f32_16x16x32_bf16 v[110:113], v[122:125], v[246:249], 0
	ds_read_b128 v[122:125], v131 offset:3584
	s_waitcnt lgkmcnt(3)
	v_mfma_f32_16x16x32_bf16 v[20:23], v[126:129], v[242:245], v[20:23]
	v_mfma_f32_16x16x32_bf16 v[110:113], v[126:129], v[194:197], v[110:113]
	ds_read_b128 v[126:129], v133 offset:3584
	s_waitcnt lgkmcnt(3)
	v_mfma_f32_16x16x32_bf16 v[24:27], v[76:79], v[238:241], 0
	v_mfma_f32_16x16x32_bf16 v[114:117], v[76:79], v[246:249], 0
	s_waitcnt lgkmcnt(2)
	v_mfma_f32_16x16x32_bf16 v[24:27], v[80:83], v[242:245], v[24:27]
	v_mfma_f32_16x16x32_bf16 v[114:117], v[80:83], v[194:197], v[114:117]
	s_waitcnt lgkmcnt(1)
	v_mfma_f32_16x16x32_bf16 v[28:31], v[122:125], v[238:241], 0
	v_mfma_f32_16x16x32_bf16 v[118:121], v[122:125], v[246:249], 0
	s_waitcnt lgkmcnt(0)
	v_mfma_f32_16x16x32_bf16 v[28:31], v[126:129], v[242:245], v[28:31]
	v_mfma_f32_16x16x32_bf16 v[118:121], v[126:129], v[194:197], v[118:121]
	v_mul_f32_e32 v68, 0xbfb8aa3b, v68
	v_mul_f32_e32 v70, 0xbfb8aa3b, v70
	v_sub_f32_e32 v138, 0, v73
	v_mul_f32_e32 v139, 0x3fb8aa3b, v138
	v_exp_f32_e32 v139, v139
	s_nop 0
	v_mul_f32_e32 v140, 0xbe800000, v139
	v_add_f32_e32 v140, 0x3eaaaaab, v140
	v_fma_f32 v140, -v139, v140, 0.5
	v_fma_f32 v140, -v139, v140, 1.0
	v_mul_f32_e32 v140, v139, v140
	v_add_f32_e32 v141, 1.0, v139
	v_log_f32_e32 v141, v141
	v_mov_b32_e32 v255, 0x3cf5c28f
	v_mul_f32_e32 v141, 0x3f317218, v141
	v_cmp_gt_f32_e32 vcc, v255, v139
	s_nop 1
	v_cndmask_b32_e32 v140, v141, v140, vcc
	v_mov_b32_e32 v255, 0x41a00000
	v_cmp_lt_f32_e32 vcc, v255, v138
	s_nop 1
	v_cndmask_b32_e32 v140, v140, v138, vcc
	v_mul_f32_e32 v73, 0xc138aa3b, v140
	s_nop 7
	v_add_f32_e32 v0, v0, v68
	v_add_f32_e32 v1, v1, v68
	v_add_f32_e32 v2, v2, v68
	v_add_f32_e32 v3, v3, v68
	v_add_f32_e32 v90, v90, v70
	v_add_f32_e32 v91, v91, v70
	v_add_f32_e32 v92, v92, v70
	v_add_f32_e32 v93, v93, v70
	v_exp_f32_e32 v0, v0
	v_exp_f32_e32 v1, v1
	v_exp_f32_e32 v2, v2
	v_exp_f32_e32 v3, v3
	v_exp_f32_e32 v90, v90
	v_exp_f32_e32 v91, v91
	v_exp_f32_e32 v92, v92
	v_exp_f32_e32 v93, v93
	v_add_f32_e32 v0, 1.0, v0
	v_add_f32_e32 v1, 1.0, v1
	v_add_f32_e32 v2, 1.0, v2
	v_add_f32_e32 v3, 1.0, v3
	v_add_f32_e32 v90, 1.0, v90
	v_add_f32_e32 v91, 1.0, v91
	v_add_f32_e32 v92, 1.0, v92
	v_add_f32_e32 v93, 1.0, v93
	v_rcp_f32_e32 v0, v0
	v_rcp_f32_e32 v1, v1
	v_rcp_f32_e32 v2, v2
	v_rcp_f32_e32 v3, v3
	v_rcp_f32_e32 v90, v90
	v_rcp_f32_e32 v91, v91
	v_rcp_f32_e32 v92, v92
	v_rcp_f32_e32 v93, v93
	v_mul_f32_e32 v0, v73, v0
	v_mul_f32_e32 v1, v73, v1
	v_mul_f32_e32 v2, v73, v2
	v_mul_f32_e32 v3, v73, v3
	v_mul_f32_e32 v90, v90, v162
	v_mul_f32_e32 v91, v91, v163
	v_mul_f32_e32 v92, v92, v164
	v_mul_f32_e32 v93, v93, v165
	v_exp_f32_e32 v0, v0
	v_exp_f32_e32 v1, v1
	v_exp_f32_e32 v2, v2
	v_exp_f32_e32 v3, v3
	s_nop 0
	v_fma_f32 v138, -v0, v0, 1.0
	v_fma_f32 v139, -v1, v1, 1.0
	v_fma_f32 v140, -v2, v2, 1.0
	v_fma_f32 v141, -v3, v3, 1.0
	v_max_f32_e32 v138, 0, v138
	v_max_f32_e32 v139, 0, v139
	v_max_f32_e32 v140, 0, v140
	v_max_f32_e32 v141, 0, v141
	v_sqrt_f32_e32 v138, v138
	v_sqrt_f32_e32 v139, v139
	v_sqrt_f32_e32 v140, v140
	v_sqrt_f32_e32 v141, v141
	s_nop 0
	v_mul_f32_e32 v90, v138, v90
	v_mul_f32_e32 v91, v139, v91
	v_mul_f32_e32 v92, v140, v92
	v_mul_f32_e32 v93, v141, v93
	v_add_f32_e32 v4, v4, v68
	v_add_f32_e32 v5, v5, v68
	v_add_f32_e32 v6, v6, v68
	v_add_f32_e32 v7, v7, v68
	v_add_f32_e32 v94, v94, v70
	v_add_f32_e32 v95, v95, v70
	v_add_f32_e32 v96, v96, v70
	v_add_f32_e32 v97, v97, v70
	v_exp_f32_e32 v4, v4
	v_exp_f32_e32 v5, v5
	v_exp_f32_e32 v6, v6
	v_exp_f32_e32 v7, v7
	v_exp_f32_e32 v94, v94
	v_exp_f32_e32 v95, v95
	v_exp_f32_e32 v96, v96
	v_exp_f32_e32 v97, v97
	v_add_f32_e32 v4, 1.0, v4
	v_add_f32_e32 v5, 1.0, v5
	v_add_f32_e32 v6, 1.0, v6
	v_add_f32_e32 v7, 1.0, v7
	v_add_f32_e32 v94, 1.0, v94
	v_add_f32_e32 v95, 1.0, v95
	v_add_f32_e32 v96, 1.0, v96
	v_add_f32_e32 v97, 1.0, v97
	v_rcp_f32_e32 v4, v4
	v_rcp_f32_e32 v5, v5
	v_rcp_f32_e32 v6, v6
	v_rcp_f32_e32 v7, v7
	v_rcp_f32_e32 v94, v94
	v_rcp_f32_e32 v95, v95
	v_rcp_f32_e32 v96, v96
	v_rcp_f32_e32 v97, v97
	v_mul_f32_e32 v4, v73, v4
	v_mul_f32_e32 v5, v73, v5
	v_mul_f32_e32 v6, v73, v6
	v_mul_f32_e32 v7, v73, v7
	v_mul_f32_e32 v94, v94, v166
; __device__ __forceinline__ float bf2f(u16 h) { return __uint_as_float(((unsigned)h) << 16); }
; __device__ __forceinline__ void lru_tile(const Params& P, int chunk, int head, int pass, char* smem_raw) {
;     ...
; #pragma unroll
;       for (int tc = 0; tc < 4; ++tc)
; #pragma unroll
;         for (int reg = 0; reg < 4; ++reg) {
;           const int tl = wid * 16 + (lane >> 4) * 4 + reg;
;           const int c = 16 * tc + (lane & 15);
;           const float r = __builtin_amdgcn_rcpf(1.f + __builtin_amdgcn_exp2f(acc[tc][reg] + ba[tc]));
;           const float ii = __builtin_amdgcn_rcpf(1.f + __builtin_amdgcn_exp2f(acc[tc + 4][reg] + bi[tc]));
;           const float la = -c8[tc] * r;
;           const float a = __builtin_amdgcn_exp2f(la);
;           const float ucv = bf2f(sm_uc[(sb * 64 + tl) * LDSS + c]);
;           const float bt = __builtin_amdgcn_sqrtf(fmaxf(1.f - a * a, 0.f)) * (ii * ucv);
	v_mul_f32_e32 v95, v95, v167
	v_mul_f32_e32 v96, v96, v168
	v_mul_f32_e32 v97, v97, v169
	v_exp_f32_e32 v4, v4
	v_exp_f32_e32 v5, v5
	v_exp_f32_e32 v6, v6
	v_exp_f32_e32 v7, v7
	s_nop 0
	v_fma_f32 v138, -v4, v4, 1.0
	v_fma_f32 v139, -v5, v5, 1.0
	v_fma_f32 v140, -v6, v6, 1.0
	v_fma_f32 v141, -v7, v7, 1.0
	v_max_f32_e32 v138, 0, v138
	v_max_f32_e32 v139, 0, v139
	v_max_f32_e32 v140, 0, v140
	v_max_f32_e32 v141, 0, v141
	v_sqrt_f32_e32 v138, v138
	v_sqrt_f32_e32 v139, v139
	v_sqrt_f32_e32 v140, v140
	v_sqrt_f32_e32 v141, v141
	s_nop 0
	v_mul_f32_e32 v94, v138, v94
	v_mul_f32_e32 v95, v139, v95
	v_mul_f32_e32 v96, v140, v96
	v_mul_f32_e32 v97, v141, v97
	v_add_f32_e32 v8, v8, v68
	v_add_f32_e32 v9, v9, v68
	v_add_f32_e32 v10, v10, v68
	v_add_f32_e32 v11, v11, v68
	v_add_f32_e32 v98, v98, v70
	v_add_f32_e32 v99, v99, v70
	v_add_f32_e32 v100, v100, v70
	v_add_f32_e32 v101, v101, v70
	v_exp_f32_e32 v8, v8
	v_exp_f32_e32 v9, v9
	v_exp_f32_e32 v10, v10
	v_exp_f32_e32 v11, v11
	v_exp_f32_e32 v98, v98
	v_exp_f32_e32 v99, v99
	v_exp_f32_e32 v100, v100
	v_exp_f32_e32 v101, v101
	v_add_f32_e32 v8, 1.0, v8
	v_add_f32_e32 v9, 1.0, v9
	v_add_f32_e32 v10, 1.0, v10
	v_add_f32_e32 v11, 1.0, v11
	v_add_f32_e32 v98, 1.0, v98
	v_add_f32_e32 v99, 1.0, v99
	v_add_f32_e32 v100, 1.0, v100
	v_add_f32_e32 v101, 1.0, v101
	v_rcp_f32_e32 v8, v8
	v_rcp_f32_e32 v9, v9
	v_rcp_f32_e32 v10, v10
	v_rcp_f32_e32 v11, v11
	v_rcp_f32_e32 v98, v98
	v_rcp_f32_e32 v99, v99
	v_rcp_f32_e32 v100, v100
	v_rcp_f32_e32 v101, v101
	v_mul_f32_e32 v8, v73, v8
	v_mul_f32_e32 v9, v73, v9
	v_mul_f32_e32 v10, v73, v10
	v_mul_f32_e32 v11, v73, v11
	v_mul_f32_e32 v98, v98, v170
	v_mul_f32_e32 v99, v99, v171
	v_mul_f32_e32 v100, v100, v172
	v_mul_f32_e32 v101, v101, v173
	v_exp_f32_e32 v8, v8
	v_exp_f32_e32 v9, v9
	v_exp_f32_e32 v10, v10
	v_exp_f32_e32 v11, v11
	s_nop 0
	v_fma_f32 v138, -v8, v8, 1.0
	v_fma_f32 v139, -v9, v9, 1.0
	v_fma_f32 v140, -v10, v10, 1.0
	v_fma_f32 v141, -v11, v11, 1.0
	v_max_f32_e32 v138, 0, v138
	v_max_f32_e32 v139, 0, v139
	v_max_f32_e32 v140, 0, v140
	v_max_f32_e32 v141, 0, v141
	v_sqrt_f32_e32 v138, v138
	v_sqrt_f32_e32 v139, v139
	v_sqrt_f32_e32 v140, v140
	v_sqrt_f32_e32 v141, v141
	s_nop 0
	v_mul_f32_e32 v98, v138, v98
	v_mul_f32_e32 v99, v139, v99
	v_mul_f32_e32 v100, v140, v100
	v_mul_f32_e32 v101, v141, v101
	v_add_f32_e32 v12, v12, v68
	v_add_f32_e32 v13, v13, v68
	v_add_f32_e32 v14, v14, v68
	v_add_f32_e32 v15, v15, v68
	v_add_f32_e32 v102, v102, v70
	v_add_f32_e32 v103, v103, v70
	v_add_f32_e32 v104, v104, v70
	v_add_f32_e32 v105, v105, v70
	v_exp_f32_e32 v12, v12
	v_exp_f32_e32 v13, v13
	v_exp_f32_e32 v14, v14
	v_exp_f32_e32 v15, v15
	v_exp_f32_e32 v102, v102
	v_exp_f32_e32 v103, v103
	v_exp_f32_e32 v104, v104
	v_exp_f32_e32 v105, v105
	v_add_f32_e32 v12, 1.0, v12
	v_add_f32_e32 v13, 1.0, v13
	v_add_f32_e32 v14, 1.0, v14
	v_add_f32_e32 v15, 1.0, v15
	v_add_f32_e32 v102, 1.0, v102
	v_add_f32_e32 v103, 1.0, v103
	v_add_f32_e32 v104, 1.0, v104
	v_add_f32_e32 v105, 1.0, v105
	v_rcp_f32_e32 v12, v12
	v_rcp_f32_e32 v13, v13
	v_rcp_f32_e32 v14, v14
	v_rcp_f32_e32 v15, v15
	v_rcp_f32_e32 v102, v102
	v_rcp_f32_e32 v103, v103
	v_rcp_f32_e32 v104, v104
	v_rcp_f32_e32 v105, v105
	v_mul_f32_e32 v12, v73, v12
	v_mul_f32_e32 v13, v73, v13
	v_mul_f32_e32 v14, v73, v14
	v_mul_f32_e32 v15, v73, v15
	v_mul_f32_e32 v102, v102, v174
	v_mul_f32_e32 v103, v103, v175
	v_mul_f32_e32 v104, v104, v176
	v_mul_f32_e32 v105, v105, v177
	v_exp_f32_e32 v12, v12
	v_exp_f32_e32 v13, v13
	v_exp_f32_e32 v14, v14
	v_exp_f32_e32 v15, v15
	s_nop 0
	v_fma_f32 v138, -v12, v12, 1.0
	v_fma_f32 v139, -v13, v13, 1.0
	v_fma_f32 v140, -v14, v14, 1.0
	v_fma_f32 v141, -v15, v15, 1.0
	v_max_f32_e32 v138, 0, v138
	v_max_f32_e32 v139, 0, v139
	v_max_f32_e32 v140, 0, v140
	v_max_f32_e32 v141, 0, v141
	v_sqrt_f32_e32 v138, v138
	v_sqrt_f32_e32 v139, v139
	v_sqrt_f32_e32 v140, v140
	v_sqrt_f32_e32 v141, v141
	s_nop 0
	v_mul_f32_e32 v102, v138, v102
	v_mul_f32_e32 v103, v139, v103
	v_mul_f32_e32 v104, v140, v104
	v_mul_f32_e32 v105, v141, v105
	v_add_f32_e32 v16, v16, v68
	v_add_f32_e32 v17, v17, v68
	v_add_f32_e32 v18, v18, v68
	v_add_f32_e32 v19, v19, v68
	v_add_f32_e32 v106, v106, v70
	v_add_f32_e32 v107, v107, v70
	v_add_f32_e32 v108, v108, v70
	v_add_f32_e32 v109, v109, v70
	v_exp_f32_e32 v16, v16
	v_exp_f32_e32 v17, v17
	v_exp_f32_e32 v18, v18
	v_exp_f32_e32 v19, v19
	v_exp_f32_e32 v106, v106
	v_exp_f32_e32 v107, v107
	v_exp_f32_e32 v108, v108
	v_exp_f32_e32 v109, v109
	v_add_f32_e32 v16, 1.0, v16
	v_add_f32_e32 v17, 1.0, v17
	v_add_f32_e32 v18, 1.0, v18
	v_add_f32_e32 v19, 1.0, v19
	v_add_f32_e32 v106, 1.0, v106
	v_add_f32_e32 v107, 1.0, v107
	v_add_f32_e32 v108, 1.0, v108
	v_add_f32_e32 v109, 1.0, v109
	v_rcp_f32_e32 v16, v16
	v_rcp_f32_e32 v17, v17
	v_rcp_f32_e32 v18, v18
	v_rcp_f32_e32 v19, v19
	v_rcp_f32_e32 v106, v106
	v_rcp_f32_e32 v107, v107
	v_rcp_f32_e32 v108, v108
	v_rcp_f32_e32 v109, v109
	v_mul_f32_e32 v16, v73, v16
	v_mul_f32_e32 v17, v73, v17
	v_mul_f32_e32 v18, v73, v18
	v_mul_f32_e32 v19, v73, v19
	v_mul_f32_e32 v106, v106, v178
	v_mul_f32_e32 v107, v107, v179
	v_mul_f32_e32 v108, v108, v180
	v_mul_f32_e32 v109, v109, v181
	v_exp_f32_e32 v16, v16
	v_exp_f32_e32 v17, v17
	v_exp_f32_e32 v18, v18
	v_exp_f32_e32 v19, v19
	s_nop 0
	v_fma_f32 v138, -v16, v16, 1.0
	v_fma_f32 v139, -v17, v17, 1.0
	v_fma_f32 v140, -v18, v18, 1.0
	v_fma_f32 v141, -v19, v19, 1.0
	v_max_f32_e32 v138, 0, v138
	v_max_f32_e32 v139, 0, v139
	v_max_f32_e32 v140, 0, v140
	v_max_f32_e32 v141, 0, v141
	v_sqrt_f32_e32 v138, v138
	v_sqrt_f32_e32 v139, v139
	v_sqrt_f32_e32 v140, v140
	v_sqrt_f32_e32 v141, v141
	s_nop 0
; __device__ __forceinline__ float bf2f(u16 h) { return __uint_as_float(((unsigned)h) << 16); }
; __device__ __forceinline__ void lru_tile(const Params& P, int chunk, int head, int pass, char* smem_raw) {
;     ...
; #pragma unroll
;       for (int tc = 0; tc < 4; ++tc)
; #pragma unroll
;         for (int reg = 0; reg < 4; ++reg) {
;           const int tl = wid * 16 + (lane >> 4) * 4 + reg;
;           const int c = 16 * tc + (lane & 15);
;           const float r = __builtin_amdgcn_rcpf(1.f + __builtin_amdgcn_exp2f(acc[tc][reg] + ba[tc]));
;           const float ii = __builtin_amdgcn_rcpf(1.f + __builtin_amdgcn_exp2f(acc[tc + 4][reg] + bi[tc]));
;           const float la = -c8[tc] * r;
;           const float a = __builtin_amdgcn_exp2f(la);
;           const float ucv = bf2f(sm_uc[(sb * 64 + tl) * LDSS + c]);
;           const float bt = __builtin_amdgcn_sqrtf(fmaxf(1.f - a * a, 0.f)) * (ii * ucv);
;     ...
;         float hfp[16], gp[16];
;         if (d == 1) {
; #pragma unroll
;           for (int i = 0; i < 16; ++i) {
;             const long rowp = row0 + sb * 64 + q * 16 + 15 - i;
;             hfp[i] = hfbuf[rowp * 512 + gch];
;             gp[i] = bf2f(P.zq[rowp * 1536 + 512 + gch]);
;           }
	v_mul_f32_e32 v106, v138, v106
	v_mul_f32_e32 v107, v139, v107
	v_mul_f32_e32 v108, v140, v108
	v_mul_f32_e32 v109, v141, v109
	v_add_f32_e32 v20, v20, v68
	v_add_f32_e32 v21, v21, v68
	v_add_f32_e32 v22, v22, v68
	v_add_f32_e32 v23, v23, v68
	v_add_f32_e32 v110, v110, v70
	v_add_f32_e32 v111, v111, v70
	v_add_f32_e32 v112, v112, v70
	v_add_f32_e32 v113, v113, v70
	v_exp_f32_e32 v20, v20
	v_exp_f32_e32 v21, v21
	v_exp_f32_e32 v22, v22
	v_exp_f32_e32 v23, v23
	v_exp_f32_e32 v110, v110
	v_exp_f32_e32 v111, v111
	v_exp_f32_e32 v112, v112
	v_exp_f32_e32 v113, v113
	v_add_f32_e32 v20, 1.0, v20
	v_add_f32_e32 v21, 1.0, v21
	v_add_f32_e32 v22, 1.0, v22
	v_add_f32_e32 v23, 1.0, v23
	v_add_f32_e32 v110, 1.0, v110
	v_add_f32_e32 v111, 1.0, v111
	v_add_f32_e32 v112, 1.0, v112
	v_add_f32_e32 v113, 1.0, v113
	v_rcp_f32_e32 v20, v20
	v_rcp_f32_e32 v21, v21
	v_rcp_f32_e32 v22, v22
	v_rcp_f32_e32 v23, v23
	v_rcp_f32_e32 v110, v110
	v_rcp_f32_e32 v111, v111
	v_rcp_f32_e32 v112, v112
	v_rcp_f32_e32 v113, v113
	v_mul_f32_e32 v20, v73, v20
	v_mul_f32_e32 v21, v73, v21
	v_mul_f32_e32 v22, v73, v22
	v_mul_f32_e32 v23, v73, v23
	v_mul_f32_e32 v110, v110, v182
	v_mul_f32_e32 v111, v111, v183
	v_mul_f32_e32 v112, v112, v184
	v_mul_f32_e32 v113, v113, v185
	v_exp_f32_e32 v20, v20
	v_exp_f32_e32 v21, v21
	v_exp_f32_e32 v22, v22
	v_exp_f32_e32 v23, v23
	s_nop 0
	v_fma_f32 v138, -v20, v20, 1.0
	v_fma_f32 v139, -v21, v21, 1.0
	v_fma_f32 v140, -v22, v22, 1.0
	v_fma_f32 v141, -v23, v23, 1.0
	v_max_f32_e32 v138, 0, v138
	v_max_f32_e32 v139, 0, v139
	v_max_f32_e32 v140, 0, v140
	v_max_f32_e32 v141, 0, v141
	v_sqrt_f32_e32 v138, v138
	v_sqrt_f32_e32 v139, v139
	v_sqrt_f32_e32 v140, v140
	v_sqrt_f32_e32 v141, v141
	s_nop 0
	v_mul_f32_e32 v110, v138, v110
	v_mul_f32_e32 v111, v139, v111
	v_mul_f32_e32 v112, v140, v112
	v_mul_f32_e32 v113, v141, v113
	v_add_f32_e32 v24, v24, v68
	v_add_f32_e32 v25, v25, v68
	v_add_f32_e32 v26, v26, v68
	v_add_f32_e32 v27, v27, v68
	v_add_f32_e32 v114, v114, v70
	v_add_f32_e32 v115, v115, v70
	v_add_f32_e32 v116, v116, v70
	v_add_f32_e32 v117, v117, v70
	v_exp_f32_e32 v24, v24
	v_exp_f32_e32 v25, v25
	v_exp_f32_e32 v26, v26
	v_exp_f32_e32 v27, v27
	v_exp_f32_e32 v114, v114
	v_exp_f32_e32 v115, v115
	v_exp_f32_e32 v116, v116
	v_exp_f32_e32 v117, v117
	v_add_f32_e32 v24, 1.0, v24
	v_add_f32_e32 v25, 1.0, v25
	v_add_f32_e32 v26, 1.0, v26
	v_add_f32_e32 v27, 1.0, v27
	v_add_f32_e32 v114, 1.0, v114
	v_add_f32_e32 v115, 1.0, v115
	v_add_f32_e32 v116, 1.0, v116
	v_add_f32_e32 v117, 1.0, v117
	v_rcp_f32_e32 v24, v24
	v_rcp_f32_e32 v25, v25
	v_rcp_f32_e32 v26, v26
	v_rcp_f32_e32 v27, v27
	v_rcp_f32_e32 v114, v114
	v_rcp_f32_e32 v115, v115
	v_rcp_f32_e32 v116, v116
	v_rcp_f32_e32 v117, v117
	v_mul_f32_e32 v24, v73, v24
	v_mul_f32_e32 v25, v73, v25
	v_mul_f32_e32 v26, v73, v26
	v_mul_f32_e32 v27, v73, v27
	v_mul_f32_e32 v114, v114, v186
	v_mul_f32_e32 v115, v115, v187
	v_mul_f32_e32 v116, v116, v188
	v_mul_f32_e32 v117, v117, v189
	v_exp_f32_e32 v24, v24
	v_exp_f32_e32 v25, v25
	v_exp_f32_e32 v26, v26
	v_exp_f32_e32 v27, v27
	s_nop 0
	v_fma_f32 v138, -v24, v24, 1.0
	v_fma_f32 v139, -v25, v25, 1.0
	v_fma_f32 v140, -v26, v26, 1.0
	v_fma_f32 v141, -v27, v27, 1.0
	v_max_f32_e32 v138, 0, v138
	v_max_f32_e32 v139, 0, v139
	v_max_f32_e32 v140, 0, v140
	v_max_f32_e32 v141, 0, v141
	v_sqrt_f32_e32 v138, v138
	v_sqrt_f32_e32 v139, v139
	v_sqrt_f32_e32 v140, v140
	v_sqrt_f32_e32 v141, v141
	s_nop 0
	v_mul_f32_e32 v114, v138, v114
	v_mul_f32_e32 v115, v139, v115
	v_mul_f32_e32 v116, v140, v116
	v_mul_f32_e32 v117, v141, v117
	v_add_f32_e32 v28, v28, v68
	v_add_f32_e32 v29, v29, v68
	v_add_f32_e32 v30, v30, v68
	v_add_f32_e32 v31, v31, v68
	v_add_f32_e32 v118, v118, v70
	v_add_f32_e32 v119, v119, v70
	v_add_f32_e32 v120, v120, v70
	v_add_f32_e32 v121, v121, v70
	v_exp_f32_e32 v28, v28
	v_exp_f32_e32 v29, v29
	v_exp_f32_e32 v30, v30
	v_exp_f32_e32 v31, v31
	v_exp_f32_e32 v118, v118
	v_exp_f32_e32 v119, v119
	v_exp_f32_e32 v120, v120
	v_exp_f32_e32 v121, v121
	v_add_f32_e32 v28, 1.0, v28
	v_add_f32_e32 v29, 1.0, v29
	v_add_f32_e32 v30, 1.0, v30
	v_add_f32_e32 v31, 1.0, v31
	v_add_f32_e32 v118, 1.0, v118
	v_add_f32_e32 v119, 1.0, v119
	v_add_f32_e32 v120, 1.0, v120
	v_add_f32_e32 v121, 1.0, v121
	v_rcp_f32_e32 v28, v28
	v_rcp_f32_e32 v29, v29
	v_rcp_f32_e32 v30, v30
	v_rcp_f32_e32 v31, v31
	v_rcp_f32_e32 v118, v118
	v_rcp_f32_e32 v119, v119
	v_rcp_f32_e32 v120, v120
	v_rcp_f32_e32 v121, v121
	v_mul_f32_e32 v28, v73, v28
	v_mul_f32_e32 v29, v73, v29
	v_mul_f32_e32 v30, v73, v30
	v_mul_f32_e32 v31, v73, v31
	v_mul_f32_e32 v118, v118, v190
	v_mul_f32_e32 v119, v119, v191
	v_mul_f32_e32 v120, v120, v192
	v_mul_f32_e32 v121, v121, v193
	v_exp_f32_e32 v28, v28
	v_exp_f32_e32 v29, v29
	v_exp_f32_e32 v30, v30
	v_exp_f32_e32 v31, v31
	s_nop 0
	v_fma_f32 v138, -v28, v28, 1.0
	v_fma_f32 v139, -v29, v29, 1.0
	v_fma_f32 v140, -v30, v30, 1.0
	v_fma_f32 v141, -v31, v31, 1.0
	v_max_f32_e32 v138, 0, v138
	v_max_f32_e32 v139, 0, v139
	v_max_f32_e32 v140, 0, v140
	v_max_f32_e32 v141, 0, v141
	v_sqrt_f32_e32 v138, v138
	v_sqrt_f32_e32 v139, v139
	v_sqrt_f32_e32 v140, v140
	v_sqrt_f32_e32 v141, v141
	s_nop 0
	v_mul_f32_e32 v118, v138, v118
	v_mul_f32_e32 v119, v139, v119
	v_mul_f32_e32 v120, v140, v120
	v_mul_f32_e32 v121, v141, v121
	s_mul_i32 s0, s71, 0x60000
	s_lshl_b32 s1, s56, 1
	s_add_u32 s0, s0, s1
	s_add_u32 s0, s0, 0x400
	s_add_u32 s4, s10, s0
	s_addc_u32 s5, s11, 0
	global_load_ushort v162, v134, s[4:5]
	s_add_u32 s4, s4, 0xc00
	s_addc_u32 s5, s5, 0
	global_load_ushort v163, v134, s[4:5]
	s_add_u32 s4, s4, 0xc00
	s_addc_u32 s5, s5, 0
	global_load_ushort v164, v134, s[4:5]
; __device__ __forceinline__ float bf2f(u16 h) { return __uint_as_float(((unsigned)h) << 16); }
; __device__ __forceinline__ void lru_tile(const Params& P, int chunk, int head, int pass, char* smem_raw) {
;     ...
;         float Pp = 1.f, H = 0.f;
; #pragma unroll 4
;         for (int i = 0; i < 16; ++i) {
;           const int tl = (d == 0) ? (q * 16 + i) : (q * 16 + 15 - i);
;           const float a = sm_a[tl * 64 + ch], b = sm_b[tl * 64 + ch];
;           H = a * H + b; Pp *= a;
;         }
;         sm_ph[pos * 64 + ch] = make_float2(Pp, H);
;       }
;       __syncthreads();
;       const float2 p0 = sm_ph[ch], p1 = sm_ph[64 + ch], p2 = sm_ph[128 + ch], p3 = sm_ph[192 + ch];
;       if (pass == 2) {
;         float hin = cB;
;         if (pos > 0) hin = p0.x * hin + p0.y;
;         if (pos > 1) hin = p1.x * hin + p1.y;
;         if (pos > 2) hin = p2.x * hin + p2.y;
;         float h = hin;
;         float hfp[16], gp[16];
;         if (d == 1) {
; #pragma unroll
;           for (int i = 0; i < 16; ++i) {
;             const long rowp = row0 + sb * 64 + q * 16 + 15 - i;
;             hfp[i] = hfbuf[rowp * 512 + gch];
;             gp[i] = bf2f(P.zq[rowp * 1536 + 512 + gch]);
;           }
;         }
; #pragma unroll
;         for (int i = 0; i < 16; ++i) {
;           const int tl = (d == 0) ? (q * 16 + i) : (q * 16 + 15 - i);
;           const float a = sm_a[tl * 64 + ch], b = sm_b[tl * 64 + ch];
;           h = a * h + b;
;           const long row = row0 + sb * 64 + tl;
;           if (d == 0) {
;             hfw[row * 512 + gch] = h;
;           } else {
;             const float hfv = hfp[i];
;             const float g = gp[i];
;             const float tz = 0.7978845608028654f * (g + 0.044715f * g * g * g);
;             const float th = 1.f - 2.f * __builtin_amdgcn_rcpf(1.f + __expf(2.f * tz));
;             const float ge = 0.5f * g * (1.f + th);
;             P.cat[row * 1024 + gch] = f2bf((hfv + h) * ge);
;           }
;         }
	s_add_u32 s4, s4, 0xc00
	s_addc_u32 s5, s5, 0
	global_load_ushort v165, v134, s[4:5]
	s_add_u32 s4, s4, 0xc00
	s_addc_u32 s5, s5, 0
	global_load_ushort v166, v134, s[4:5]
	s_add_u32 s4, s4, 0xc00
	s_addc_u32 s5, s5, 0
	global_load_ushort v167, v134, s[4:5]
	s_add_u32 s4, s4, 0xc00
	s_addc_u32 s5, s5, 0
	global_load_ushort v168, v134, s[4:5]
	s_add_u32 s4, s4, 0xc00
	s_addc_u32 s5, s5, 0
	global_load_ushort v169, v134, s[4:5]
	s_add_u32 s4, s4, 0xc00
	s_addc_u32 s5, s5, 0
	global_load_ushort v170, v134, s[4:5]
	s_add_u32 s4, s4, 0xc00
	s_addc_u32 s5, s5, 0
	global_load_ushort v171, v134, s[4:5]
	s_add_u32 s4, s4, 0xc00
	s_addc_u32 s5, s5, 0
	global_load_ushort v172, v134, s[4:5]
	s_add_u32 s4, s4, 0xc00
	s_addc_u32 s5, s5, 0
	global_load_ushort v173, v134, s[4:5]
	s_add_u32 s4, s4, 0xc00
	s_addc_u32 s5, s5, 0
	global_load_ushort v174, v134, s[4:5]
	s_add_u32 s4, s4, 0xc00
	s_addc_u32 s5, s5, 0
	global_load_ushort v175, v134, s[4:5]
	s_add_u32 s4, s4, 0xc00
	s_addc_u32 s5, s5, 0
	global_load_ushort v176, v134, s[4:5]
	s_add_u32 s4, s4, 0xc00
	s_addc_u32 s5, s5, 0
	global_load_ushort v177, v134, s[4:5]
	s_add_u32 s4, s4, 0xc00
	s_addc_u32 s5, s5, 0
	global_load_ushort v178, v134, s[4:5]
	s_add_u32 s4, s4, 0xc00
	s_addc_u32 s5, s5, 0
	global_load_ushort v179, v134, s[4:5]
	s_add_u32 s4, s4, 0xc00
	s_addc_u32 s5, s5, 0
	global_load_ushort v180, v134, s[4:5]
	s_add_u32 s4, s4, 0xc00
	s_addc_u32 s5, s5, 0
	global_load_ushort v181, v134, s[4:5]
	s_add_u32 s4, s4, 0xc00
	s_addc_u32 s5, s5, 0
	global_load_ushort v182, v134, s[4:5]
	s_add_u32 s4, s4, 0xc00
	s_addc_u32 s5, s5, 0
	global_load_ushort v183, v134, s[4:5]
	s_add_u32 s4, s4, 0xc00
	s_addc_u32 s5, s5, 0
	global_load_ushort v184, v134, s[4:5]
	s_add_u32 s4, s4, 0xc00
	s_addc_u32 s5, s5, 0
	global_load_ushort v185, v134, s[4:5]
	s_add_u32 s4, s4, 0xc00
	s_addc_u32 s5, s5, 0
	global_load_ushort v186, v134, s[4:5]
	s_add_u32 s4, s4, 0xc00
	s_addc_u32 s5, s5, 0
	global_load_ushort v187, v134, s[4:5]
	s_add_u32 s4, s4, 0xc00
	s_addc_u32 s5, s5, 0
	global_load_ushort v188, v134, s[4:5]
	s_add_u32 s4, s4, 0xc00
	s_addc_u32 s5, s5, 0
	global_load_ushort v189, v134, s[4:5]
	s_add_u32 s4, s4, 0xc00
	s_addc_u32 s5, s5, 0
	global_load_ushort v190, v134, s[4:5]
	s_add_u32 s4, s4, 0xc00
	s_addc_u32 s5, s5, 0
	global_load_ushort v191, v134, s[4:5]
	s_add_u32 s4, s4, 0xc00
	s_addc_u32 s5, s5, 0
	global_load_ushort v192, v134, s[4:5]
	s_add_u32 s4, s4, 0xc00
	s_addc_u32 s5, s5, 0
	global_load_ushort v193, v134, s[4:5]
	v_mov_b32_e32 v253, v31
	v_mov_b32_e32 v254, v121
	v_fma_f32 v254, v30, v254, v120
	v_mul_f32_e32 v253, v253, v30
	v_fma_f32 v254, v29, v254, v119
	v_mul_f32_e32 v253, v253, v29
	v_fma_f32 v254, v28, v254, v118
	v_mul_f32_e32 v253, v253, v28
	v_fma_f32 v254, v27, v254, v117
	v_mul_f32_e32 v253, v253, v27
	v_fma_f32 v254, v26, v254, v116
	v_mul_f32_e32 v253, v253, v26
	v_fma_f32 v254, v25, v254, v115
	v_mul_f32_e32 v253, v253, v25
	v_fma_f32 v254, v24, v254, v114
	v_mul_f32_e32 v253, v253, v24
	v_fma_f32 v254, v23, v254, v113
	v_mul_f32_e32 v253, v253, v23
	v_fma_f32 v254, v22, v254, v112
	v_mul_f32_e32 v253, v253, v22
	v_fma_f32 v254, v21, v254, v111
	v_mul_f32_e32 v253, v253, v21
	v_fma_f32 v254, v20, v254, v110
	v_mul_f32_e32 v253, v253, v20
	v_fma_f32 v254, v19, v254, v109
	v_mul_f32_e32 v253, v253, v19
	v_fma_f32 v254, v18, v254, v108
	v_mul_f32_e32 v253, v253, v18
	v_fma_f32 v254, v17, v254, v107
	v_mul_f32_e32 v253, v253, v17
	v_fma_f32 v254, v16, v254, v106
	v_mul_f32_e32 v253, v253, v16
	v_fma_f32 v254, v15, v254, v105
	v_mul_f32_e32 v253, v253, v15
	v_fma_f32 v254, v14, v254, v104
	v_mul_f32_e32 v253, v253, v14
	v_fma_f32 v254, v13, v254, v103
	v_mul_f32_e32 v253, v253, v13
	v_fma_f32 v254, v12, v254, v102
	v_mul_f32_e32 v253, v253, v12
	v_fma_f32 v254, v11, v254, v101
	v_mul_f32_e32 v253, v253, v11
	v_fma_f32 v254, v10, v254, v100
	v_mul_f32_e32 v253, v253, v10
	v_fma_f32 v254, v9, v254, v99
	v_mul_f32_e32 v253, v253, v9
	v_fma_f32 v254, v8, v254, v98
	v_mul_f32_e32 v253, v253, v8
	v_fma_f32 v254, v7, v254, v97
	v_mul_f32_e32 v253, v253, v7
	v_fma_f32 v254, v6, v254, v96
	v_mul_f32_e32 v253, v253, v6
	v_fma_f32 v254, v5, v254, v95
	v_mul_f32_e32 v253, v253, v5
	v_fma_f32 v254, v4, v254, v94
	v_mul_f32_e32 v253, v253, v4
	v_fma_f32 v254, v3, v254, v93
	v_mul_f32_e32 v253, v253, v3
	v_fma_f32 v254, v2, v254, v92
	v_mul_f32_e32 v253, v253, v2
	v_fma_f32 v254, v1, v254, v91
	v_mul_f32_e32 v253, v253, v1
	v_fma_f32 v254, v0, v254, v90
	v_mul_f32_e32 v253, v253, v0
	v_mov_b32_e32 v138, v253
	v_mov_b32_e32 v139, v253
	s_nop 1
	v_permlane16_swap_b32_e32 v138, v139
	v_mov_b32_e32 v140, v138
	v_mov_b32_e32 v141, v139
	s_nop 1
	v_permlane32_swap_b32_e32 v138, v140
	v_permlane32_swap_b32_e32 v139, v141
	v_mov_b32_e32 v198, v254
	v_mov_b32_e32 v199, v254
	s_nop 1
	v_permlane16_swap_b32_e32 v198, v199
	v_mov_b32_e32 v200, v198
	v_mov_b32_e32 v201, v199
	s_nop 1
	v_permlane32_swap_b32_e32 v198, v200
	v_permlane32_swap_b32_e32 v199, v201
	v_mov_b32_e32 v202, v67
	v_fma_f32 v151, v141, v202, v201
	v_fma_f32 v150, v140, v151, v200
	v_fma_f32 v136, v139, v150, v199
	v_mov_b32_e32 v254, v202
	v_cndmask_b32_e64 v254, v254, v151, s[78:79]
	v_cndmask_b32_e64 v254, v254, v150, s[80:81]
	v_cndmask_b32_e64 v254, v254, v136, s[82:83]
	v_fma_f32 v121, v31, v254, v121
	v_fma_f32 v120, v30, v121, v120
	v_fma_f32 v119, v29, v120, v119
	v_fma_f32 v118, v28, v119, v118
	v_fma_f32 v117, v27, v118, v117
	v_fma_f32 v116, v26, v117, v116
	v_fma_f32 v115, v25, v116, v115
	v_fma_f32 v114, v24, v115, v114
	v_fma_f32 v113, v23, v114, v113
	v_fma_f32 v112, v22, v113, v112
	v_fma_f32 v111, v21, v112, v111
	v_fma_f32 v110, v20, v111, v110
	v_fma_f32 v109, v19, v110, v109
	v_fma_f32 v108, v18, v109, v108
	v_fma_f32 v107, v17, v108, v107
	v_fma_f32 v106, v16, v107, v106
	v_fma_f32 v105, v15, v106, v105
	v_fma_f32 v104, v14, v105, v104
	v_fma_f32 v103, v13, v104, v103
	v_fma_f32 v102, v12, v103, v102
	v_fma_f32 v101, v11, v102, v101
	v_fma_f32 v100, v10, v101, v100
	v_fma_f32 v99, v9, v100, v99
	v_fma_f32 v98, v8, v99, v98
	v_fma_f32 v97, v7, v98, v97
	v_fma_f32 v96, v6, v97, v96
	v_fma_f32 v95, v5, v96, v95
	v_fma_f32 v94, v4, v95, v94
	v_fma_f32 v93, v3, v94, v93
	v_fma_f32 v92, v2, v93, v92
	v_fma_f32 v91, v1, v92, v91
	v_fma_f32 v90, v0, v91, v90
	s_waitcnt vmcnt(0)
; __device__ __forceinline__ void lru_tile(const Params& P, int chunk, int head, int pass, char* smem_raw) {
;     ...
;           } else {
;             const float hfv = hfp[i];
;             const float g = gp[i];
;             const float tz = 0.7978845608028654f * (g + 0.044715f * g * g * g);
;             const float th = 1.f - 2.f * __builtin_amdgcn_rcpf(1.f + __expf(2.f * tz));
;             const float ge = 0.5f * g * (1.f + th);
;             P.cat[row * 1024 + gch] = f2bf((hfv + h) * ge);
;           }
;         }
	v_lshlrev_b32_e32 v162, 16, v162
	v_lshlrev_b32_e32 v163, 16, v163
	v_lshlrev_b32_e32 v164, 16, v164
	v_lshlrev_b32_e32 v165, 16, v165
	v_lshlrev_b32_e32 v166, 16, v166
	v_lshlrev_b32_e32 v167, 16, v167
	v_lshlrev_b32_e32 v168, 16, v168
	v_lshlrev_b32_e32 v169, 16, v169
	v_lshlrev_b32_e32 v170, 16, v170
	v_lshlrev_b32_e32 v171, 16, v171
	v_lshlrev_b32_e32 v172, 16, v172
	v_lshlrev_b32_e32 v173, 16, v173
	v_lshlrev_b32_e32 v174, 16, v174
	v_lshlrev_b32_e32 v175, 16, v175
	v_lshlrev_b32_e32 v176, 16, v176
	v_lshlrev_b32_e32 v177, 16, v177
	v_lshlrev_b32_e32 v178, 16, v178
	v_lshlrev_b32_e32 v179, 16, v179
	v_lshlrev_b32_e32 v180, 16, v180
	v_lshlrev_b32_e32 v181, 16, v181
	v_lshlrev_b32_e32 v182, 16, v182
	v_lshlrev_b32_e32 v183, 16, v183
	v_lshlrev_b32_e32 v184, 16, v184
	v_lshlrev_b32_e32 v185, 16, v185
	v_lshlrev_b32_e32 v186, 16, v186
	v_lshlrev_b32_e32 v187, 16, v187
	v_lshlrev_b32_e32 v188, 16, v188
	v_lshlrev_b32_e32 v189, 16, v189
	v_lshlrev_b32_e32 v190, 16, v190
	v_lshlrev_b32_e32 v191, 16, v191
	v_lshlrev_b32_e32 v192, 16, v192
	v_lshlrev_b32_e32 v193, 16, v193
	v_mov_b32_e32 v202, 0x3d372713
	v_mul_f32_e32 v138, v162, v162
	v_mul_f32_e32 v139, v163, v163
	v_mul_f32_e32 v140, v164, v164
	v_mul_f32_e32 v141, v165, v165
	v_mul_f32_e32 v138, v138, v162
	v_mul_f32_e32 v139, v139, v163
	v_mul_f32_e32 v140, v140, v164
	v_mul_f32_e32 v141, v141, v165
	v_fma_f32 v138, v202, v138, v162
	v_fma_f32 v139, v202, v139, v163
	v_fma_f32 v140, v202, v140, v164
	v_fma_f32 v141, v202, v141, v165
	v_mul_f32_e32 v138, 0x40135761, v138
	v_mul_f32_e32 v139, 0x40135761, v139
	v_mul_f32_e32 v140, 0x40135761, v140
	v_mul_f32_e32 v141, 0x40135761, v141
	v_exp_f32_e32 v138, v138
	v_exp_f32_e32 v139, v139
	v_exp_f32_e32 v140, v140
	v_exp_f32_e32 v141, v141
	s_nop 0
	v_add_f32_e32 v138, 1.0, v138
	v_add_f32_e32 v139, 1.0, v139
	v_add_f32_e32 v140, 1.0, v140
	v_add_f32_e32 v141, 1.0, v141
	v_rcp_f32_e32 v138, v138
	v_rcp_f32_e32 v139, v139
	v_rcp_f32_e32 v140, v140
	v_rcp_f32_e32 v141, v141
	s_nop 0
	v_fma_f32 v138, -2.0, v138, 1.0
	v_fma_f32 v139, -2.0, v139, 1.0
	v_fma_f32 v140, -2.0, v140, 1.0
	v_fma_f32 v141, -2.0, v141, 1.0
	v_add_f32_e32 v138, 1.0, v138
	v_add_f32_e32 v139, 1.0, v139
	v_add_f32_e32 v140, 1.0, v140
	v_add_f32_e32 v141, 1.0, v141
	v_mul_f32_e32 v162, 0.5, v162
	v_mul_f32_e32 v163, 0.5, v163
	v_mul_f32_e32 v164, 0.5, v164
	v_mul_f32_e32 v165, 0.5, v165
	v_mul_f32_e32 v162, v162, v138
	v_mul_f32_e32 v163, v163, v139
	v_mul_f32_e32 v164, v164, v140
	v_mul_f32_e32 v165, v165, v141
	v_add_f32_e32 v90, v205, v90
	v_add_f32_e32 v91, v206, v91
	v_add_f32_e32 v92, v207, v92
	v_add_f32_e32 v93, v208, v93
	v_mul_f32_e32 v90, v90, v162
	v_mul_f32_e32 v91, v91, v163
	v_mul_f32_e32 v92, v92, v164
	v_mul_f32_e32 v93, v93, v165
	v_cvt_pk_bf16_f32 v90, v90, v90
	v_cvt_pk_bf16_f32 v91, v91, v91
	v_cvt_pk_bf16_f32 v92, v92, v92
	v_cvt_pk_bf16_f32 v93, v93, v93
	v_mul_f32_e32 v138, v166, v166
	v_mul_f32_e32 v139, v167, v167
	v_mul_f32_e32 v140, v168, v168
	v_mul_f32_e32 v141, v169, v169
	v_mul_f32_e32 v138, v138, v166
	v_mul_f32_e32 v139, v139, v167
	v_mul_f32_e32 v140, v140, v168
	v_mul_f32_e32 v141, v141, v169
	v_fma_f32 v138, v202, v138, v166
	v_fma_f32 v139, v202, v139, v167
	v_fma_f32 v140, v202, v140, v168
	v_fma_f32 v141, v202, v141, v169
	v_mul_f32_e32 v138, 0x40135761, v138
	v_mul_f32_e32 v139, 0x40135761, v139
	v_mul_f32_e32 v140, 0x40135761, v140
	v_mul_f32_e32 v141, 0x40135761, v141
	v_exp_f32_e32 v138, v138
	v_exp_f32_e32 v139, v139
	v_exp_f32_e32 v140, v140
	v_exp_f32_e32 v141, v141
	s_nop 0
	v_add_f32_e32 v138, 1.0, v138
	v_add_f32_e32 v139, 1.0, v139
	v_add_f32_e32 v140, 1.0, v140
	v_add_f32_e32 v141, 1.0, v141
	v_rcp_f32_e32 v138, v138
	v_rcp_f32_e32 v139, v139
	v_rcp_f32_e32 v140, v140
	v_rcp_f32_e32 v141, v141
	s_nop 0
	v_fma_f32 v138, -2.0, v138, 1.0
	v_fma_f32 v139, -2.0, v139, 1.0
	v_fma_f32 v140, -2.0, v140, 1.0
	v_fma_f32 v141, -2.0, v141, 1.0
	v_add_f32_e32 v138, 1.0, v138
	v_add_f32_e32 v139, 1.0, v139
	v_add_f32_e32 v140, 1.0, v140
	v_add_f32_e32 v141, 1.0, v141
	v_mul_f32_e32 v166, 0.5, v166
	v_mul_f32_e32 v167, 0.5, v167
	v_mul_f32_e32 v168, 0.5, v168
	v_mul_f32_e32 v169, 0.5, v169
	v_mul_f32_e32 v166, v166, v138
	v_mul_f32_e32 v167, v167, v139
	v_mul_f32_e32 v168, v168, v140
	v_mul_f32_e32 v169, v169, v141
	v_add_f32_e32 v94, v209, v94
	v_add_f32_e32 v95, v210, v95
	v_add_f32_e32 v96, v211, v96
	v_add_f32_e32 v97, v212, v97
	v_mul_f32_e32 v94, v94, v166
	v_mul_f32_e32 v95, v95, v167
	v_mul_f32_e32 v96, v96, v168
	v_mul_f32_e32 v97, v97, v169
	v_cvt_pk_bf16_f32 v94, v94, v94
	v_cvt_pk_bf16_f32 v95, v95, v95
	v_cvt_pk_bf16_f32 v96, v96, v96
	v_cvt_pk_bf16_f32 v97, v97, v97
	v_mul_f32_e32 v138, v170, v170
	v_mul_f32_e32 v139, v171, v171
	v_mul_f32_e32 v140, v172, v172
	v_mul_f32_e32 v141, v173, v173
	v_mul_f32_e32 v138, v138, v170
	v_mul_f32_e32 v139, v139, v171
	v_mul_f32_e32 v140, v140, v172
	v_mul_f32_e32 v141, v141, v173
	v_fma_f32 v138, v202, v138, v170
	v_fma_f32 v139, v202, v139, v171
	v_fma_f32 v140, v202, v140, v172
	v_fma_f32 v141, v202, v141, v173
	v_mul_f32_e32 v138, 0x40135761, v138
	v_mul_f32_e32 v139, 0x40135761, v139
	v_mul_f32_e32 v140, 0x40135761, v140
	v_mul_f32_e32 v141, 0x40135761, v141
	v_exp_f32_e32 v138, v138
	v_exp_f32_e32 v139, v139
	v_exp_f32_e32 v140, v140
	v_exp_f32_e32 v141, v141
	s_nop 0
	v_add_f32_e32 v138, 1.0, v138
	v_add_f32_e32 v139, 1.0, v139
	v_add_f32_e32 v140, 1.0, v140
	v_add_f32_e32 v141, 1.0, v141
	v_rcp_f32_e32 v138, v138
	v_rcp_f32_e32 v139, v139
	v_rcp_f32_e32 v140, v140
	v_rcp_f32_e32 v141, v141
	s_nop 0
	v_fma_f32 v138, -2.0, v138, 1.0
	v_fma_f32 v139, -2.0, v139, 1.0
; __device__ __forceinline__ void lru_tile(const Params& P, int chunk, int head, int pass, char* smem_raw) {
;     ...
;           } else {
;             const float hfv = hfp[i];
;             const float g = gp[i];
;             const float tz = 0.7978845608028654f * (g + 0.044715f * g * g * g);
;             const float th = 1.f - 2.f * __builtin_amdgcn_rcpf(1.f + __expf(2.f * tz));
;             const float ge = 0.5f * g * (1.f + th);
;             P.cat[row * 1024 + gch] = f2bf((hfv + h) * ge);
;           }
;         }
	v_fma_f32 v140, -2.0, v140, 1.0
	v_fma_f32 v141, -2.0, v141, 1.0
	v_add_f32_e32 v138, 1.0, v138
	v_add_f32_e32 v139, 1.0, v139
	v_add_f32_e32 v140, 1.0, v140
	v_add_f32_e32 v141, 1.0, v141
	v_mul_f32_e32 v170, 0.5, v170
	v_mul_f32_e32 v171, 0.5, v171
	v_mul_f32_e32 v172, 0.5, v172
	v_mul_f32_e32 v173, 0.5, v173
	v_mul_f32_e32 v170, v170, v138
	v_mul_f32_e32 v171, v171, v139
	v_mul_f32_e32 v172, v172, v140
	v_mul_f32_e32 v173, v173, v141
	v_add_f32_e32 v98, v213, v98
	v_add_f32_e32 v99, v214, v99
	v_add_f32_e32 v100, v215, v100
	v_add_f32_e32 v101, v216, v101
	v_mul_f32_e32 v98, v98, v170
	v_mul_f32_e32 v99, v99, v171
	v_mul_f32_e32 v100, v100, v172
	v_mul_f32_e32 v101, v101, v173
	v_cvt_pk_bf16_f32 v98, v98, v98
	v_cvt_pk_bf16_f32 v99, v99, v99
	v_cvt_pk_bf16_f32 v100, v100, v100
	v_cvt_pk_bf16_f32 v101, v101, v101
	v_mul_f32_e32 v138, v174, v174
	v_mul_f32_e32 v139, v175, v175
	v_mul_f32_e32 v140, v176, v176
	v_mul_f32_e32 v141, v177, v177
	v_mul_f32_e32 v138, v138, v174
	v_mul_f32_e32 v139, v139, v175
	v_mul_f32_e32 v140, v140, v176
	v_mul_f32_e32 v141, v141, v177
	v_fma_f32 v138, v202, v138, v174
	v_fma_f32 v139, v202, v139, v175
	v_fma_f32 v140, v202, v140, v176
	v_fma_f32 v141, v202, v141, v177
	v_mul_f32_e32 v138, 0x40135761, v138
	v_mul_f32_e32 v139, 0x40135761, v139
	v_mul_f32_e32 v140, 0x40135761, v140
	v_mul_f32_e32 v141, 0x40135761, v141
	v_exp_f32_e32 v138, v138
	v_exp_f32_e32 v139, v139
	v_exp_f32_e32 v140, v140
	v_exp_f32_e32 v141, v141
	s_nop 0
	v_add_f32_e32 v138, 1.0, v138
	v_add_f32_e32 v139, 1.0, v139
	v_add_f32_e32 v140, 1.0, v140
	v_add_f32_e32 v141, 1.0, v141
	v_rcp_f32_e32 v138, v138
	v_rcp_f32_e32 v139, v139
	v_rcp_f32_e32 v140, v140
	v_rcp_f32_e32 v141, v141
	s_nop 0
	v_fma_f32 v138, -2.0, v138, 1.0
	v_fma_f32 v139, -2.0, v139, 1.0
	v_fma_f32 v140, -2.0, v140, 1.0
	v_fma_f32 v141, -2.0, v141, 1.0
	v_add_f32_e32 v138, 1.0, v138
	v_add_f32_e32 v139, 1.0, v139
	v_add_f32_e32 v140, 1.0, v140
	v_add_f32_e32 v141, 1.0, v141
	v_mul_f32_e32 v174, 0.5, v174
	v_mul_f32_e32 v175, 0.5, v175
	v_mul_f32_e32 v176, 0.5, v176
	v_mul_f32_e32 v177, 0.5, v177
	v_mul_f32_e32 v174, v174, v138
	v_mul_f32_e32 v175, v175, v139
	v_mul_f32_e32 v176, v176, v140
	v_mul_f32_e32 v177, v177, v141
	v_add_f32_e32 v102, v217, v102
	v_add_f32_e32 v103, v218, v103
	v_add_f32_e32 v104, v219, v104
	v_add_f32_e32 v105, v220, v105
	v_mul_f32_e32 v102, v102, v174
	v_mul_f32_e32 v103, v103, v175
	v_mul_f32_e32 v104, v104, v176
	v_mul_f32_e32 v105, v105, v177
	v_cvt_pk_bf16_f32 v102, v102, v102
	v_cvt_pk_bf16_f32 v103, v103, v103
	v_cvt_pk_bf16_f32 v104, v104, v104
	v_cvt_pk_bf16_f32 v105, v105, v105
	v_mul_f32_e32 v138, v178, v178
	v_mul_f32_e32 v139, v179, v179
	v_mul_f32_e32 v140, v180, v180
	v_mul_f32_e32 v141, v181, v181
	v_mul_f32_e32 v138, v138, v178
	v_mul_f32_e32 v139, v139, v179
	v_mul_f32_e32 v140, v140, v180
	v_mul_f32_e32 v141, v141, v181
	v_fma_f32 v138, v202, v138, v178
	v_fma_f32 v139, v202, v139, v179
	v_fma_f32 v140, v202, v140, v180
	v_fma_f32 v141, v202, v141, v181
	v_mul_f32_e32 v138, 0x40135761, v138
	v_mul_f32_e32 v139, 0x40135761, v139
	v_mul_f32_e32 v140, 0x40135761, v140
	v_mul_f32_e32 v141, 0x40135761, v141
	v_exp_f32_e32 v138, v138
	v_exp_f32_e32 v139, v139
	v_exp_f32_e32 v140, v140
	v_exp_f32_e32 v141, v141
	s_nop 0
	v_add_f32_e32 v138, 1.0, v138
	v_add_f32_e32 v139, 1.0, v139
	v_add_f32_e32 v140, 1.0, v140
	v_add_f32_e32 v141, 1.0, v141
	v_rcp_f32_e32 v138, v138
	v_rcp_f32_e32 v139, v139
	v_rcp_f32_e32 v140, v140
	v_rcp_f32_e32 v141, v141
	s_nop 0
	v_fma_f32 v138, -2.0, v138, 1.0
	v_fma_f32 v139, -2.0, v139, 1.0
	v_fma_f32 v140, -2.0, v140, 1.0
	v_fma_f32 v141, -2.0, v141, 1.0
	v_add_f32_e32 v138, 1.0, v138
	v_add_f32_e32 v139, 1.0, v139
	v_add_f32_e32 v140, 1.0, v140
	v_add_f32_e32 v141, 1.0, v141
	v_mul_f32_e32 v178, 0.5, v178
	v_mul_f32_e32 v179, 0.5, v179
	v_mul_f32_e32 v180, 0.5, v180
	v_mul_f32_e32 v181, 0.5, v181
	v_mul_f32_e32 v178, v178, v138
	v_mul_f32_e32 v179, v179, v139
	v_mul_f32_e32 v180, v180, v140
	v_mul_f32_e32 v181, v181, v141
	v_add_f32_e32 v106, v221, v106
	v_add_f32_e32 v107, v222, v107
	v_add_f32_e32 v108, v223, v108
	v_add_f32_e32 v109, v224, v109
	v_mul_f32_e32 v106, v106, v178
	v_mul_f32_e32 v107, v107, v179
	v_mul_f32_e32 v108, v108, v180
	v_mul_f32_e32 v109, v109, v181
	v_cvt_pk_bf16_f32 v106, v106, v106
	v_cvt_pk_bf16_f32 v107, v107, v107
	v_cvt_pk_bf16_f32 v108, v108, v108
	v_cvt_pk_bf16_f32 v109, v109, v109
	v_mul_f32_e32 v138, v182, v182
	v_mul_f32_e32 v139, v183, v183
	v_mul_f32_e32 v140, v184, v184
	v_mul_f32_e32 v141, v185, v185
	v_mul_f32_e32 v138, v138, v182
	v_mul_f32_e32 v139, v139, v183
	v_mul_f32_e32 v140, v140, v184
	v_mul_f32_e32 v141, v141, v185
	v_fma_f32 v138, v202, v138, v182
	v_fma_f32 v139, v202, v139, v183
	v_fma_f32 v140, v202, v140, v184
	v_fma_f32 v141, v202, v141, v185
	v_mul_f32_e32 v138, 0x40135761, v138
	v_mul_f32_e32 v139, 0x40135761, v139
	v_mul_f32_e32 v140, 0x40135761, v140
	v_mul_f32_e32 v141, 0x40135761, v141
	v_exp_f32_e32 v138, v138
	v_exp_f32_e32 v139, v139
	v_exp_f32_e32 v140, v140
	v_exp_f32_e32 v141, v141
	s_nop 0
	v_add_f32_e32 v138, 1.0, v138
	v_add_f32_e32 v139, 1.0, v139
	v_add_f32_e32 v140, 1.0, v140
	v_add_f32_e32 v141, 1.0, v141
	v_rcp_f32_e32 v138, v138
	v_rcp_f32_e32 v139, v139
	v_rcp_f32_e32 v140, v140
	v_rcp_f32_e32 v141, v141
	s_nop 0
	v_fma_f32 v138, -2.0, v138, 1.0
	v_fma_f32 v139, -2.0, v139, 1.0
	v_fma_f32 v140, -2.0, v140, 1.0
	v_fma_f32 v141, -2.0, v141, 1.0
	v_add_f32_e32 v138, 1.0, v138
	v_add_f32_e32 v139, 1.0, v139
	v_add_f32_e32 v140, 1.0, v140
	v_add_f32_e32 v141, 1.0, v141
	v_mul_f32_e32 v182, 0.5, v182
	v_mul_f32_e32 v183, 0.5, v183
; __device__ __forceinline__ void lru_tile(const Params& P, int chunk, int head, int pass, char* smem_raw) {
;     ...
;           } else {
;             const float hfv = hfp[i];
;             const float g = gp[i];
;             const float tz = 0.7978845608028654f * (g + 0.044715f * g * g * g);
;             const float th = 1.f - 2.f * __builtin_amdgcn_rcpf(1.f + __expf(2.f * tz));
;             const float ge = 0.5f * g * (1.f + th);
;             P.cat[row * 1024 + gch] = f2bf((hfv + h) * ge);
;           }
;         }
	v_mul_f32_e32 v184, 0.5, v184
	v_mul_f32_e32 v185, 0.5, v185
	v_mul_f32_e32 v182, v182, v138
	v_mul_f32_e32 v183, v183, v139
	v_mul_f32_e32 v184, v184, v140
	v_mul_f32_e32 v185, v185, v141
	v_add_f32_e32 v110, v225, v110
	v_add_f32_e32 v111, v226, v111
	v_add_f32_e32 v112, v227, v112
	v_add_f32_e32 v113, v228, v113
	v_mul_f32_e32 v110, v110, v182
	v_mul_f32_e32 v111, v111, v183
	v_mul_f32_e32 v112, v112, v184
	v_mul_f32_e32 v113, v113, v185
	v_cvt_pk_bf16_f32 v110, v110, v110
	v_cvt_pk_bf16_f32 v111, v111, v111
	v_cvt_pk_bf16_f32 v112, v112, v112
	v_cvt_pk_bf16_f32 v113, v113, v113
	v_mul_f32_e32 v138, v186, v186
	v_mul_f32_e32 v139, v187, v187
	v_mul_f32_e32 v140, v188, v188
	v_mul_f32_e32 v141, v189, v189
	v_mul_f32_e32 v138, v138, v186
	v_mul_f32_e32 v139, v139, v187
	v_mul_f32_e32 v140, v140, v188
	v_mul_f32_e32 v141, v141, v189
	v_fma_f32 v138, v202, v138, v186
	v_fma_f32 v139, v202, v139, v187
	v_fma_f32 v140, v202, v140, v188
	v_fma_f32 v141, v202, v141, v189
	v_mul_f32_e32 v138, 0x40135761, v138
	v_mul_f32_e32 v139, 0x40135761, v139
	v_mul_f32_e32 v140, 0x40135761, v140
	v_mul_f32_e32 v141, 0x40135761, v141
	v_exp_f32_e32 v138, v138
	v_exp_f32_e32 v139, v139
	v_exp_f32_e32 v140, v140
	v_exp_f32_e32 v141, v141
	s_nop 0
	v_add_f32_e32 v138, 1.0, v138
	v_add_f32_e32 v139, 1.0, v139
	v_add_f32_e32 v140, 1.0, v140
	v_add_f32_e32 v141, 1.0, v141
	v_rcp_f32_e32 v138, v138
	v_rcp_f32_e32 v139, v139
	v_rcp_f32_e32 v140, v140
	v_rcp_f32_e32 v141, v141
	s_nop 0
	v_fma_f32 v138, -2.0, v138, 1.0
	v_fma_f32 v139, -2.0, v139, 1.0
	v_fma_f32 v140, -2.0, v140, 1.0
	v_fma_f32 v141, -2.0, v141, 1.0
	v_add_f32_e32 v138, 1.0, v138
	v_add_f32_e32 v139, 1.0, v139
	v_add_f32_e32 v140, 1.0, v140
	v_add_f32_e32 v141, 1.0, v141
	v_mul_f32_e32 v186, 0.5, v186
	v_mul_f32_e32 v187, 0.5, v187
	v_mul_f32_e32 v188, 0.5, v188
	v_mul_f32_e32 v189, 0.5, v189
	v_mul_f32_e32 v186, v186, v138
	v_mul_f32_e32 v187, v187, v139
	v_mul_f32_e32 v188, v188, v140
	v_mul_f32_e32 v189, v189, v141
	v_add_f32_e32 v114, v229, v114
	v_add_f32_e32 v115, v230, v115
	v_add_f32_e32 v116, v231, v116
	v_add_f32_e32 v117, v232, v117
	v_mul_f32_e32 v114, v114, v186
	v_mul_f32_e32 v115, v115, v187
	v_mul_f32_e32 v116, v116, v188
	v_mul_f32_e32 v117, v117, v189
	v_cvt_pk_bf16_f32 v114, v114, v114
	v_cvt_pk_bf16_f32 v115, v115, v115
	v_cvt_pk_bf16_f32 v116, v116, v116
	v_cvt_pk_bf16_f32 v117, v117, v117
	v_mul_f32_e32 v138, v190, v190
	v_mul_f32_e32 v139, v191, v191
	v_mul_f32_e32 v140, v192, v192
	v_mul_f32_e32 v141, v193, v193
	v_mul_f32_e32 v138, v138, v190
	v_mul_f32_e32 v139, v139, v191
	v_mul_f32_e32 v140, v140, v192
	v_mul_f32_e32 v141, v141, v193
	v_fma_f32 v138, v202, v138, v190
	v_fma_f32 v139, v202, v139, v191
	v_fma_f32 v140, v202, v140, v192
	v_fma_f32 v141, v202, v141, v193
	v_mul_f32_e32 v138, 0x40135761, v138
	v_mul_f32_e32 v139, 0x40135761, v139
	v_mul_f32_e32 v140, 0x40135761, v140
	v_mul_f32_e32 v141, 0x40135761, v141
	v_exp_f32_e32 v138, v138
	v_exp_f32_e32 v139, v139
	v_exp_f32_e32 v140, v140
	v_exp_f32_e32 v141, v141
	s_nop 0
	v_add_f32_e32 v138, 1.0, v138
	v_add_f32_e32 v139, 1.0, v139
	v_add_f32_e32 v140, 1.0, v140
	v_add_f32_e32 v141, 1.0, v141
	v_rcp_f32_e32 v138, v138
	v_rcp_f32_e32 v139, v139
	v_rcp_f32_e32 v140, v140
	v_rcp_f32_e32 v141, v141
	s_nop 0
	v_fma_f32 v138, -2.0, v138, 1.0
	v_fma_f32 v139, -2.0, v139, 1.0
	v_fma_f32 v140, -2.0, v140, 1.0
	v_fma_f32 v141, -2.0, v141, 1.0
	v_add_f32_e32 v138, 1.0, v138
	v_add_f32_e32 v139, 1.0, v139
	v_add_f32_e32 v140, 1.0, v140
	v_add_f32_e32 v141, 1.0, v141
	v_mul_f32_e32 v190, 0.5, v190
; __device__ __forceinline__ void lru_tile(const Params& P, int chunk, int head, int pass, char* smem_raw) {
;     ...
;             const float tz = 0.7978845608028654f * (g + 0.044715f * g * g * g);
;             const float th = 1.f - 2.f * __builtin_amdgcn_rcpf(1.f + __expf(2.f * tz));
;             const float ge = 0.5f * g * (1.f + th);
;             P.cat[row * 1024 + gch] = f2bf((hfv + h) * ge);
;           }
;         }
; __device__ __forceinline__ void run_phase(const Params& P, const int ph, char* smem_raw) {
;     ...
;       for (int t = VBID; t < 2112; t += VGRID) lru_tile(P, t >> 3, t & 7, 2, smv_raw);
	v_mul_f32_e32 v191, 0.5, v191
	v_mul_f32_e32 v192, 0.5, v192
	v_mul_f32_e32 v193, 0.5, v193
	v_mul_f32_e32 v190, v190, v138
	v_mul_f32_e32 v191, v191, v139
	v_mul_f32_e32 v192, v192, v140
	v_mul_f32_e32 v193, v193, v141
	v_add_f32_e32 v118, v233, v118
	v_add_f32_e32 v119, v234, v119
	v_add_f32_e32 v120, v235, v120
	v_add_f32_e32 v121, v236, v121
	v_mul_f32_e32 v118, v118, v190
	v_mul_f32_e32 v119, v119, v191
	v_mul_f32_e32 v120, v120, v192
	v_mul_f32_e32 v121, v121, v193
	v_cvt_pk_bf16_f32 v118, v118, v118
	v_cvt_pk_bf16_f32 v119, v119, v119
	v_cvt_pk_bf16_f32 v120, v120, v120
	v_cvt_pk_bf16_f32 v121, v121, v121
	s_lshl_b32 s0, s71, 18
	s_lshl_b32 s1, s56, 1
	s_add_u32 s0, s0, s1
	s_add_u32 s4, s12, s0
	s_addc_u32 s5, s13, 0
	global_store_short v237, v90, s[4:5]
	s_add_u32 s4, s4, 0x800
	s_addc_u32 s5, s5, 0
	global_store_short v237, v91, s[4:5]
	s_add_u32 s4, s4, 0x800
	s_addc_u32 s5, s5, 0
	global_store_short v237, v92, s[4:5]
	s_add_u32 s4, s4, 0x800
	s_addc_u32 s5, s5, 0
	global_store_short v237, v93, s[4:5]
	s_add_u32 s4, s4, 0x800
	s_addc_u32 s5, s5, 0
	global_store_short v237, v94, s[4:5]
	s_add_u32 s4, s4, 0x800
	s_addc_u32 s5, s5, 0
	global_store_short v237, v95, s[4:5]
	s_add_u32 s4, s4, 0x800
	s_addc_u32 s5, s5, 0
	global_store_short v237, v96, s[4:5]
	s_add_u32 s4, s4, 0x800
	s_addc_u32 s5, s5, 0
	global_store_short v237, v97, s[4:5]
	s_add_u32 s4, s4, 0x800
	s_addc_u32 s5, s5, 0
	global_store_short v237, v98, s[4:5]
	s_add_u32 s4, s4, 0x800
	s_addc_u32 s5, s5, 0
	global_store_short v237, v99, s[4:5]
	s_add_u32 s4, s4, 0x800
	s_addc_u32 s5, s5, 0
	global_store_short v237, v100, s[4:5]
	s_add_u32 s4, s4, 0x800
	s_addc_u32 s5, s5, 0
	global_store_short v237, v101, s[4:5]
	s_add_u32 s4, s4, 0x800
	s_addc_u32 s5, s5, 0
	global_store_short v237, v102, s[4:5]
	s_add_u32 s4, s4, 0x800
	s_addc_u32 s5, s5, 0
	global_store_short v237, v103, s[4:5]
	s_add_u32 s4, s4, 0x800
	s_addc_u32 s5, s5, 0
	global_store_short v237, v104, s[4:5]
	s_add_u32 s4, s4, 0x800
	s_addc_u32 s5, s5, 0
	global_store_short v237, v105, s[4:5]
	s_add_u32 s4, s4, 0x800
	s_addc_u32 s5, s5, 0
	global_store_short v237, v106, s[4:5]
	s_add_u32 s4, s4, 0x800
	s_addc_u32 s5, s5, 0
	global_store_short v237, v107, s[4:5]
	s_add_u32 s4, s4, 0x800
	s_addc_u32 s5, s5, 0
	global_store_short v237, v108, s[4:5]
	s_add_u32 s4, s4, 0x800
	s_addc_u32 s5, s5, 0
	global_store_short v237, v109, s[4:5]
	s_add_u32 s4, s4, 0x800
	s_addc_u32 s5, s5, 0
	global_store_short v237, v110, s[4:5]
	s_add_u32 s4, s4, 0x800
	s_addc_u32 s5, s5, 0
	global_store_short v237, v111, s[4:5]
	s_add_u32 s4, s4, 0x800
	s_addc_u32 s5, s5, 0
	global_store_short v237, v112, s[4:5]
	s_add_u32 s4, s4, 0x800
	s_addc_u32 s5, s5, 0
	global_store_short v237, v113, s[4:5]
	s_add_u32 s4, s4, 0x800
	s_addc_u32 s5, s5, 0
	global_store_short v237, v114, s[4:5]
	s_add_u32 s4, s4, 0x800
	s_addc_u32 s5, s5, 0
	global_store_short v237, v115, s[4:5]
	s_add_u32 s4, s4, 0x800
	s_addc_u32 s5, s5, 0
	global_store_short v237, v116, s[4:5]
	s_add_u32 s4, s4, 0x800
	s_addc_u32 s5, s5, 0
	global_store_short v237, v117, s[4:5]
	s_add_u32 s4, s4, 0x800
	s_addc_u32 s5, s5, 0
	global_store_short v237, v118, s[4:5]
	s_add_u32 s4, s4, 0x800
	s_addc_u32 s5, s5, 0
	global_store_short v237, v119, s[4:5]
	s_add_u32 s4, s4, 0x800
	s_addc_u32 s5, s5, 0
	global_store_short v237, v120, s[4:5]
	s_add_u32 s4, s4, 0x800
	s_addc_u32 s5, s5, 0
	global_store_short v237, v121, s[4:5]
	s_add_u32 s69, s69, 1
	s_cmp_lt_u32 s69, s70
	s_cbranch_scc1 .Lmy_lrub_tile
	s_waitcnt lgkmcnt(0)
	s_barrier
	s_branch .LBB0_680
